# scan S1+S2 rewritten batched over 8 tokens; up-projection rotary epilogue: 16 table loads and permutes per block issued together
# speedup vs baseline: 1.0624x; 1.0075x over previous
; DI int TIDX() { int t = threadIdx.x; asm volatile("" : "+v"(t)); return t; }
; template <class BR>
; DI void gemm_tile_w(const h16* __restrict__ A, int lda, const h16* __restrict__ B, int ldb, BR brow, int K, f32x16 (&acc)[4][2], h16* sm) {
;   const int tid = TIDX(), lane = tid & 63, w = tid >> 6, wm = w >> 1, wn = w & 1, r = lane & 31, hh = lane >> 5;
;   const unsigned ao = (unsigned)(tid >> 2) * (unsigned)lda + (unsigned)(tid & 3) * 8u;
;   const unsigned bo0 = (unsigned)brow(tid >> 2) * (unsigned)ldb + (unsigned)(tid & 3) * 8u;
;   const unsigned bo1 = (unsigned)brow((tid >> 2) + 64) * (unsigned)ldb + (unsigned)(tid & 3) * 8u;
;   const h16* ag = A;
;   const h16* bg = B;
;   u32x4 ra0[4], rb0[2], ra1[4], rb1[2];
; #pragma unroll
;   for (int i = 0; i < 4; ++i) ra0[i] = *(const u32x4*)(ag + (ao + (unsigned)i * 64u * (unsigned)lda));
;   rb0[0] = *(const u32x4*)(bg + bo0);
;   rb0[1] = *(const u32x4*)(bg + bo1);
;   ag += 32; bg += 32;
; #pragma unroll
;   for (int i = 0; i < 4; ++i) ra1[i] = *(const u32x4*)(ag + (ao + (unsigned)i * 64u * (unsigned)lda));
;   rb1[0] = *(const u32x4*)(bg + bo0);
;   rb1[1] = *(const u32x4*)(bg + bo1);
;   const int nk = K >> 5;
;   const int wofs = (tid >> 2) * LS2 + (tid & 3) * 8;
; DI void phase_uproj(const P& p, int l, char* smem, int boff, int geff) {
;     ...
;       gemm_tile_w(cqkv + (size_t)m0 * 640, 640, W + WO_UQ, 384, [&](int rr) { return n0 + rr; }, 384, acc, (h16*)smem);
.LBB0_2182:
	s_and_b64 vcc, exec, s[0:1]
	s_cbranch_vccz .LBB0_2114
	v_mov_b32_e32 v30, v203
	s_add_u32 s0, s69, s23
	v_ashrrev_i32_e32 v31, 2, v30
	v_lshlrev_b32_e32 v2, 3, v30
	v_mul_lo_u32 v0, v31, s67
	v_and_b32_e32 v32, 24, v2
	s_addc_u32 s1, s83, s22
	v_or_b32_e32 v0, v0, v32
	v_add_u32_e32 v2, s20, v31
	s_movk_i32 s2, 0x180
	v_mul_lo_u32 v18, v2, s2
	v_lshl_add_u64 v[132:133], v[0:1], 1, s[0:1]
	v_add_u32_e32 v6, 0xa000, v0
	v_mov_b32_e32 v7, v1
	v_add_u32_e32 v10, 0x14000, v0
	v_add_u32_e32 v0, 0x1e000, v0
	global_load_dwordx4 v[2:5], v[132:133], off
	v_lshl_add_u64 v[134:135], v[6:7], 1, s[0:1]
	v_mov_b32_e32 v11, v1
	v_lshl_add_u64 v[138:139], v[0:1], 1, s[0:1]
	v_or_b32_e32 v0, v18, v32
	global_load_dwordx4 v[6:9], v[134:135], off
	v_lshl_add_u64 v[136:137], v[10:11], 1, s[0:1]
	v_add_u32_e32 v18, 0x6000, v0
	v_mov_b32_e32 v19, v1
	global_load_dwordx4 v[10:13], v[136:137], off
	global_load_dwordx4 v[14:17], v[138:139], off
	v_lshlrev_b64 v[140:141], 1, v[0:1]
	s_waitcnt vmcnt(8)
	v_lshlrev_b64 v[142:143], 1, v[18:19]
	v_lshl_add_u64 v[20:21], s[60:61], 0, v[140:141]
	v_lshl_add_u64 v[22:23], s[60:61], 0, v[142:143]
	global_load_dwordx4 v[18:21], v[20:21], off
	s_nop 0
	global_load_dwordx4 v[22:25], v[22:23], off
	s_nop 0
	global_load_dwordx4 v[146:149], v[132:133], off offset:64
	global_load_dwordx4 v[150:153], v[134:135], off offset:64
	global_load_dwordx4 v[154:157], v[136:137], off offset:64
	global_load_dwordx4 v[158:161], v[138:139], off offset:64
	v_lshl_add_u64 v[26:27], s[62:63], 0, v[140:141]
	v_lshl_add_u64 v[28:29], s[62:63], 0, v[142:143]
	global_load_dwordx4 v[162:165], v[26:27], off
	global_load_dwordx4 v[166:169], v[28:29], off
	v_lshrrev_b32_e32 v0, 1, v30
	v_and_b32_e32 v26, 0xfffff9f, v30
	v_and_b32_e32 v27, 0x5f, v30
	v_mul_lo_u32 v28, v31, 40
	v_and_b32_e32 v0, 16, v0
	v_mul_u32_u24_e32 v27, 40, v27
	v_add_lshl_u32 v144, v28, v32, 1
	v_mad_u64_u32 v[130:131], s[0:1], v26, s76, v[0:1]
	v_lshl_add_u32 v0, v27, 1, v0
	s_waitcnt vmcnt(11)
	ds_write_b128 v144, v[2:5]
	s_waitcnt vmcnt(10)
	ds_write_b128 v144, v[6:9] offset:5120
	s_waitcnt vmcnt(9)
	ds_write_b128 v144, v[10:13] offset:10240
	s_waitcnt vmcnt(8)
	ds_write_b128 v144, v[14:17] offset:15360
	s_waitcnt vmcnt(7)
	ds_write_b128 v144, v[18:21] offset:20480
	s_waitcnt vmcnt(6)
	ds_write_b128 v144, v[22:25] offset:25600
	s_waitcnt lgkmcnt(0)
	s_barrier
	ds_read_b128 v[2:5], v130
	ds_read_b128 v[6:9], v130 offset:2560
	ds_read_b128 v[10:13], v130 offset:5120
	ds_read_b128 v[14:17], v130 offset:7680
	ds_read_b128 v[18:21], v0 offset:20480
	ds_read_b128 v[170:173], v0 offset:23040
	global_load_dwordx4 v[174:177], v[132:133], off offset:128
	global_load_dwordx4 v[178:181], v[134:135], off offset:128
	global_load_dwordx4 v[182:185], v[136:137], off offset:128
	global_load_dwordx4 v[186:189], v[138:139], off offset:128
	v_lshl_add_u64 v[22:23], s[18:19], 0, v[140:141]
	v_lshl_add_u64 v[24:25], s[18:19], 0, v[142:143]
	global_load_dwordx4 v[190:193], v[22:23], off
	global_load_dwordx4 v[194:197], v[24:25], off
	ds_read_b128 v[198:201], v130 offset:32
	ds_read_b128 v[204:207], v130 offset:2592
	ds_read_b128 v[208:211], v130 offset:5152
	ds_read_b128 v[212:215], v130 offset:7712
	ds_read_b128 v[238:241], v0 offset:20512
	ds_read_b128 v[242:245], v0 offset:23072
	s_waitcnt lgkmcnt(7)
	v_mfma_f32_32x32x16_f16 v[114:129], v[2:5], v[18:21], 0
	s_waitcnt lgkmcnt(6)
	v_mfma_f32_32x32x16_f16 v[98:113], v[2:5], v[170:173], 0
	v_mfma_f32_32x32x16_f16 v[82:97], v[6:9], v[18:21], 0
	v_mfma_f32_32x32x16_f16 v[66:81], v[6:9], v[170:173], 0
	v_mfma_f32_32x32x16_f16 v[50:65], v[10:13], v[18:21], 0
	v_mfma_f32_32x32x16_f16 v[34:49], v[10:13], v[170:173], 0
	v_mfma_f32_32x32x16_f16 v[18:33], v[14:17], v[18:21], 0
	v_mfma_f32_32x32x16_f16 v[2:17], v[14:17], v[170:173], 0
	s_waitcnt lgkmcnt(1)
	v_mfma_f32_32x32x16_f16 v[114:129], v[198:201], v[238:241], v[114:129]
	s_waitcnt lgkmcnt(0)
	v_mfma_f32_32x32x16_f16 v[98:113], v[198:201], v[242:245], v[98:113]
	v_mfma_f32_32x32x16_f16 v[82:97], v[204:207], v[238:241], v[82:97]
	v_mfma_f32_32x32x16_f16 v[66:81], v[204:207], v[242:245], v[66:81]
	v_mfma_f32_32x32x16_f16 v[50:65], v[208:211], v[238:241], v[50:65]
	v_mfma_f32_32x32x16_f16 v[34:49], v[208:211], v[242:245], v[34:49]
	v_mfma_f32_32x32x16_f16 v[18:33], v[212:215], v[238:241], v[18:33]
	v_mfma_f32_32x32x16_f16 v[2:17], v[212:215], v[242:245], v[2:17]
	s_waitcnt vmcnt(11)
	ds_write_b128 v144, v[146:149] offset:30720
	s_waitcnt vmcnt(10)
	ds_write_b128 v144, v[150:153] offset:35840
	s_waitcnt vmcnt(9)
	ds_write_b128 v144, v[154:157] offset:40960
	s_waitcnt vmcnt(8)
	ds_write_b128 v144, v[158:161] offset:46080
	s_waitcnt vmcnt(7)
	ds_write_b128 v144, v[162:165] offset:51200
	s_waitcnt vmcnt(6)
	ds_write_b128 v144, v[166:169] offset:56320
	s_waitcnt lgkmcnt(0)
	s_barrier
	ds_read_b128 v[146:149], v130 offset:33280
	ds_read_b128 v[150:153], v130 offset:35840
	ds_read_b128 v[154:157], v130 offset:30720
	ds_read_b128 v[158:161], v130 offset:38400
	ds_read_b128 v[162:165], v0 offset:51200
	ds_read_b128 v[166:169], v0 offset:53760
	global_load_dwordx4 v[170:173], v[132:133], off offset:192
	global_load_dwordx4 v[198:201], v[134:135], off offset:192
	global_load_dwordx4 v[204:207], v[136:137], off offset:192
	global_load_dwordx4 v[208:211], v[138:139], off offset:192
	v_lshl_add_u64 v[212:213], s[50:51], 0, v[140:141]
	v_lshl_add_u64 v[216:217], s[50:51], 0, v[142:143]
	global_load_dwordx4 v[212:215], v[212:213], off
	s_nop 0
	global_load_dwordx4 v[238:241], v[216:217], off
	s_waitcnt lgkmcnt(1)
	v_mfma_f32_32x32x16_f16 v[114:129], v[154:157], v[162:165], v[114:129]
	s_waitcnt lgkmcnt(0)
	v_mfma_f32_32x32x16_f16 v[98:113], v[154:157], v[166:169], v[98:113]
	v_mfma_f32_32x32x16_f16 v[82:97], v[146:149], v[162:165], v[82:97]
	v_mfma_f32_32x32x16_f16 v[66:81], v[146:149], v[166:169], v[66:81]
	v_mfma_f32_32x32x16_f16 v[50:65], v[150:153], v[162:165], v[50:65]
	v_mfma_f32_32x32x16_f16 v[34:49], v[150:153], v[166:169], v[34:49]
	v_mfma_f32_32x32x16_f16 v[18:33], v[158:161], v[162:165], v[18:33]
	ds_read_b128 v[146:149], v130 offset:33312
	ds_read_b128 v[150:153], v130 offset:35872
	ds_read_b128 v[154:157], v130 offset:30752
	ds_read_b128 v[162:165], v130 offset:38432
	ds_read_b128 v[242:245], v0 offset:51232
	ds_read_b128 v[246:249], v0 offset:53792
	v_mfma_f32_32x32x16_f16 v[2:17], v[158:161], v[166:169], v[2:17]
	s_waitcnt lgkmcnt(1)
	v_mfma_f32_32x32x16_f16 v[114:129], v[154:157], v[242:245], v[114:129]
	s_waitcnt lgkmcnt(0)
	v_mfma_f32_32x32x16_f16 v[98:113], v[154:157], v[246:249], v[98:113]
	v_mfma_f32_32x32x16_f16 v[82:97], v[146:149], v[242:245], v[82:97]
	v_mfma_f32_32x32x16_f16 v[66:81], v[146:149], v[246:249], v[66:81]
	v_mfma_f32_32x32x16_f16 v[50:65], v[150:153], v[242:245], v[50:65]
	v_mfma_f32_32x32x16_f16 v[34:49], v[150:153], v[246:249], v[34:49]
	v_mfma_f32_32x32x16_f16 v[18:33], v[162:165], v[242:245], v[18:33]
	v_mfma_f32_32x32x16_f16 v[2:17], v[162:165], v[246:249], v[2:17]
	s_waitcnt vmcnt(11)
	ds_write_b128 v144, v[174:177]
	s_waitcnt vmcnt(10)
	ds_write_b128 v144, v[178:181] offset:5120
	s_waitcnt vmcnt(9)
	ds_write_b128 v144, v[182:185] offset:10240
	s_waitcnt vmcnt(8)
	ds_write_b128 v144, v[186:189] offset:15360
	s_waitcnt vmcnt(7)
	ds_write_b128 v144, v[190:193] offset:20480
	s_waitcnt vmcnt(6)
	ds_write_b128 v144, v[194:197] offset:25600
	s_waitcnt lgkmcnt(0)
	s_barrier
	ds_read_b128 v[146:149], v130
	ds_read_b128 v[150:153], v130 offset:2560
	ds_read_b128 v[154:157], v130 offset:5120
	ds_read_b128 v[158:161], v130 offset:7680
	ds_read_b128 v[162:165], v0 offset:20480
	ds_read_b128 v[166:169], v0 offset:23040
	global_load_dwordx4 v[174:177], v[132:133], off offset:256
	global_load_dwordx4 v[178:181], v[134:135], off offset:256
	global_load_dwordx4 v[182:185], v[136:137], off offset:256
	global_load_dwordx4 v[186:189], v[138:139], off offset:256
	v_lshl_add_u64 v[190:191], s[52:53], 0, v[140:141]
	v_lshl_add_u64 v[194:195], s[52:53], 0, v[142:143]
	global_load_dwordx4 v[190:193], v[190:191], off
	s_nop 0
	global_load_dwordx4 v[194:197], v[194:195], off
	s_waitcnt lgkmcnt(1)
	v_mfma_f32_32x32x16_f16 v[114:129], v[146:149], v[162:165], v[114:129]
	s_waitcnt lgkmcnt(0)
	v_mfma_f32_32x32x16_f16 v[98:113], v[146:149], v[166:169], v[98:113]
	v_mfma_f32_32x32x16_f16 v[82:97], v[150:153], v[162:165], v[82:97]
	v_mfma_f32_32x32x16_f16 v[66:81], v[150:153], v[166:169], v[66:81]
	v_mfma_f32_32x32x16_f16 v[50:65], v[154:157], v[162:165], v[50:65]
	v_mfma_f32_32x32x16_f16 v[34:49], v[154:157], v[166:169], v[34:49]
	v_mfma_f32_32x32x16_f16 v[18:33], v[158:161], v[162:165], v[18:33]
	ds_read_b128 v[146:149], v130 offset:32
	ds_read_b128 v[150:153], v130 offset:2592
	ds_read_b128 v[154:157], v130 offset:5152
	ds_read_b128 v[162:165], v130 offset:7712
	ds_read_b128 v[242:245], v0 offset:20512
	ds_read_b128 v[246:249], v0 offset:23072
	v_mfma_f32_32x32x16_f16 v[2:17], v[158:161], v[166:169], v[2:17]
	s_waitcnt lgkmcnt(1)
	v_mfma_f32_32x32x16_f16 v[114:129], v[146:149], v[242:245], v[114:129]
	s_waitcnt lgkmcnt(0)
	v_mfma_f32_32x32x16_f16 v[98:113], v[146:149], v[246:249], v[98:113]
	v_mfma_f32_32x32x16_f16 v[82:97], v[150:153], v[242:245], v[82:97]
	v_mfma_f32_32x32x16_f16 v[66:81], v[150:153], v[246:249], v[66:81]
	v_mfma_f32_32x32x16_f16 v[50:65], v[154:157], v[242:245], v[50:65]
	v_mfma_f32_32x32x16_f16 v[34:49], v[154:157], v[246:249], v[34:49]
	v_mfma_f32_32x32x16_f16 v[18:33], v[162:165], v[242:245], v[18:33]
	v_mfma_f32_32x32x16_f16 v[2:17], v[162:165], v[246:249], v[2:17]
	s_waitcnt vmcnt(11)
	ds_write_b128 v144, v[170:173] offset:30720
	s_waitcnt vmcnt(10)
	ds_write_b128 v144, v[198:201] offset:35840
	s_waitcnt vmcnt(9)
	ds_write_b128 v144, v[204:207] offset:40960
	s_waitcnt vmcnt(8)
	ds_write_b128 v144, v[208:211] offset:46080
	s_waitcnt vmcnt(7)
	ds_write_b128 v144, v[212:215] offset:51200
	s_waitcnt vmcnt(6)
	ds_write_b128 v144, v[238:241] offset:56320
	s_waitcnt lgkmcnt(0)
	s_barrier
	ds_read_b128 v[146:149], v130 offset:33280
	ds_read_b128 v[150:153], v130 offset:35840
	ds_read_b128 v[154:157], v130 offset:30720
	ds_read_b128 v[158:161], v130 offset:38400
	ds_read_b128 v[162:165], v0 offset:51200
	ds_read_b128 v[166:169], v0 offset:53760
	global_load_dwordx4 v[170:173], v[132:133], off offset:320
	global_load_dwordx4 v[198:201], v[134:135], off offset:320
	global_load_dwordx4 v[204:207], v[136:137], off offset:320
	global_load_dwordx4 v[208:211], v[138:139], off offset:320
	v_lshl_add_u64 v[212:213], s[72:73], 0, v[140:141]
	v_lshl_add_u64 v[216:217], s[72:73], 0, v[142:143]
	global_load_dwordx4 v[212:215], v[212:213], off
	s_nop 0
	global_load_dwordx4 v[238:241], v[216:217], off
	s_waitcnt lgkmcnt(1)
	v_mfma_f32_32x32x16_f16 v[114:129], v[154:157], v[162:165], v[114:129]
	s_waitcnt lgkmcnt(0)
	v_mfma_f32_32x32x16_f16 v[98:113], v[154:157], v[166:169], v[98:113]
	v_mfma_f32_32x32x16_f16 v[82:97], v[146:149], v[162:165], v[82:97]
	v_mfma_f32_32x32x16_f16 v[66:81], v[146:149], v[166:169], v[66:81]
	v_mfma_f32_32x32x16_f16 v[50:65], v[150:153], v[162:165], v[50:65]
	v_mfma_f32_32x32x16_f16 v[34:49], v[150:153], v[166:169], v[34:49]
	v_mfma_f32_32x32x16_f16 v[18:33], v[158:161], v[162:165], v[18:33]
	ds_read_b128 v[146:149], v130 offset:33312
	ds_read_b128 v[150:153], v130 offset:35872
	ds_read_b128 v[154:157], v130 offset:30752
	ds_read_b128 v[162:165], v130 offset:38432
	ds_read_b128 v[242:245], v0 offset:51232
	ds_read_b128 v[246:249], v0 offset:53792
	v_mfma_f32_32x32x16_f16 v[2:17], v[158:161], v[166:169], v[2:17]
	s_waitcnt lgkmcnt(1)
	v_mfma_f32_32x32x16_f16 v[114:129], v[154:157], v[242:245], v[114:129]
	s_waitcnt lgkmcnt(0)
	v_mfma_f32_32x32x16_f16 v[98:113], v[154:157], v[246:249], v[98:113]
	v_mfma_f32_32x32x16_f16 v[82:97], v[146:149], v[242:245], v[82:97]
	v_mfma_f32_32x32x16_f16 v[66:81], v[146:149], v[246:249], v[66:81]
	v_mfma_f32_32x32x16_f16 v[50:65], v[150:153], v[242:245], v[50:65]
	v_mfma_f32_32x32x16_f16 v[34:49], v[150:153], v[246:249], v[34:49]
	v_mfma_f32_32x32x16_f16 v[18:33], v[162:165], v[242:245], v[18:33]
	v_mfma_f32_32x32x16_f16 v[2:17], v[162:165], v[246:249], v[2:17]
	s_waitcnt vmcnt(11)
	ds_write_b128 v144, v[174:177]
	s_waitcnt vmcnt(10)
	ds_write_b128 v144, v[178:181] offset:5120
	s_waitcnt vmcnt(9)
	ds_write_b128 v144, v[182:185] offset:10240
	s_waitcnt vmcnt(8)
	ds_write_b128 v144, v[186:189] offset:15360
	s_waitcnt vmcnt(7)
	ds_write_b128 v144, v[190:193] offset:20480
	s_waitcnt vmcnt(6)
	ds_write_b128 v144, v[194:197] offset:25600
	s_waitcnt lgkmcnt(0)
	s_barrier
	ds_read_b128 v[146:149], v130
	ds_read_b128 v[150:153], v130 offset:2560
	ds_read_b128 v[154:157], v130 offset:5120
	ds_read_b128 v[158:161], v130 offset:7680
	ds_read_b128 v[162:165], v0 offset:20480
	ds_read_b128 v[166:169], v0 offset:23040
	global_load_dwordx4 v[174:177], v[132:133], off offset:384
	global_load_dwordx4 v[178:181], v[134:135], off offset:384
	global_load_dwordx4 v[182:185], v[136:137], off offset:384
	global_load_dwordx4 v[186:189], v[138:139], off offset:384
	v_lshl_add_u64 v[190:191], s[4:5], 0, v[140:141]
	v_lshl_add_u64 v[194:195], s[4:5], 0, v[142:143]
	global_load_dwordx4 v[190:193], v[190:191], off
	s_nop 0
	global_load_dwordx4 v[194:197], v[194:195], off
	s_waitcnt lgkmcnt(1)
	v_mfma_f32_32x32x16_f16 v[114:129], v[146:149], v[162:165], v[114:129]
	s_waitcnt lgkmcnt(0)
	v_mfma_f32_32x32x16_f16 v[98:113], v[146:149], v[166:169], v[98:113]
	v_mfma_f32_32x32x16_f16 v[82:97], v[150:153], v[162:165], v[82:97]
	v_mfma_f32_32x32x16_f16 v[66:81], v[150:153], v[166:169], v[66:81]
	v_mfma_f32_32x32x16_f16 v[50:65], v[154:157], v[162:165], v[50:65]
	v_mfma_f32_32x32x16_f16 v[34:49], v[154:157], v[166:169], v[34:49]
	v_mfma_f32_32x32x16_f16 v[18:33], v[158:161], v[162:165], v[18:33]
	ds_read_b128 v[146:149], v130 offset:32
	ds_read_b128 v[150:153], v130 offset:2592
	ds_read_b128 v[154:157], v130 offset:5152
	ds_read_b128 v[162:165], v130 offset:7712
	ds_read_b128 v[242:245], v0 offset:20512
	ds_read_b128 v[246:249], v0 offset:23072
	v_mfma_f32_32x32x16_f16 v[2:17], v[158:161], v[166:169], v[2:17]
	s_waitcnt lgkmcnt(1)
	v_mfma_f32_32x32x16_f16 v[114:129], v[146:149], v[242:245], v[114:129]
	s_waitcnt lgkmcnt(0)
	v_mfma_f32_32x32x16_f16 v[98:113], v[146:149], v[246:249], v[98:113]
	v_mfma_f32_32x32x16_f16 v[82:97], v[150:153], v[242:245], v[82:97]
	v_mfma_f32_32x32x16_f16 v[66:81], v[150:153], v[246:249], v[66:81]
	v_mfma_f32_32x32x16_f16 v[50:65], v[154:157], v[242:245], v[50:65]
	v_mfma_f32_32x32x16_f16 v[34:49], v[154:157], v[246:249], v[34:49]
	v_mfma_f32_32x32x16_f16 v[18:33], v[162:165], v[242:245], v[18:33]
	v_mfma_f32_32x32x16_f16 v[2:17], v[162:165], v[246:249], v[2:17]
	s_waitcnt vmcnt(11)
	ds_write_b128 v144, v[170:173] offset:30720
	s_waitcnt vmcnt(10)
	ds_write_b128 v144, v[198:201] offset:35840
	s_waitcnt vmcnt(9)
	ds_write_b128 v144, v[204:207] offset:40960
	s_waitcnt vmcnt(8)
	ds_write_b128 v144, v[208:211] offset:46080
	s_waitcnt vmcnt(7)
	ds_write_b128 v144, v[212:215] offset:51200
	s_waitcnt vmcnt(6)
	ds_write_b128 v144, v[238:241] offset:56320
	s_waitcnt lgkmcnt(0)
	s_barrier
	ds_read_b128 v[146:149], v130 offset:33280
	ds_read_b128 v[150:153], v130 offset:35840
	ds_read_b128 v[154:157], v130 offset:30720
	ds_read_b128 v[158:161], v130 offset:38400
	ds_read_b128 v[162:165], v0 offset:51200
	ds_read_b128 v[166:169], v0 offset:53760
	global_load_dwordx4 v[170:173], v[132:133], off offset:448
	global_load_dwordx4 v[198:201], v[134:135], off offset:448
	global_load_dwordx4 v[204:207], v[136:137], off offset:448
	global_load_dwordx4 v[208:211], v[138:139], off offset:448
	v_lshl_add_u64 v[212:213], s[6:7], 0, v[140:141]
	v_lshl_add_u64 v[216:217], s[6:7], 0, v[142:143]
	global_load_dwordx4 v[212:215], v[212:213], off
	s_nop 0
	global_load_dwordx4 v[238:241], v[216:217], off
	s_waitcnt lgkmcnt(1)
	v_mfma_f32_32x32x16_f16 v[114:129], v[154:157], v[162:165], v[114:129]
	s_waitcnt lgkmcnt(0)
	v_mfma_f32_32x32x16_f16 v[98:113], v[154:157], v[166:169], v[98:113]
	v_mfma_f32_32x32x16_f16 v[82:97], v[146:149], v[162:165], v[82:97]
	v_mfma_f32_32x32x16_f16 v[66:81], v[146:149], v[166:169], v[66:81]
	v_mfma_f32_32x32x16_f16 v[50:65], v[150:153], v[162:165], v[50:65]
	v_mfma_f32_32x32x16_f16 v[34:49], v[150:153], v[166:169], v[34:49]
	v_mfma_f32_32x32x16_f16 v[18:33], v[158:161], v[162:165], v[18:33]
	ds_read_b128 v[146:149], v130 offset:33312
	ds_read_b128 v[150:153], v130 offset:35872
	ds_read_b128 v[154:157], v130 offset:30752
	ds_read_b128 v[162:165], v130 offset:38432
	ds_read_b128 v[242:245], v0 offset:51232
	ds_read_b128 v[246:249], v0 offset:53792
	v_mfma_f32_32x32x16_f16 v[2:17], v[158:161], v[166:169], v[2:17]
	s_waitcnt lgkmcnt(1)
	v_mfma_f32_32x32x16_f16 v[114:129], v[154:157], v[242:245], v[114:129]
	s_waitcnt lgkmcnt(0)
	v_mfma_f32_32x32x16_f16 v[98:113], v[154:157], v[246:249], v[98:113]
	v_mfma_f32_32x32x16_f16 v[82:97], v[146:149], v[242:245], v[82:97]
	v_mfma_f32_32x32x16_f16 v[66:81], v[146:149], v[246:249], v[66:81]
	v_mfma_f32_32x32x16_f16 v[50:65], v[150:153], v[242:245], v[50:65]
	v_mfma_f32_32x32x16_f16 v[34:49], v[150:153], v[246:249], v[34:49]
	v_mfma_f32_32x32x16_f16 v[18:33], v[162:165], v[242:245], v[18:33]
	v_mfma_f32_32x32x16_f16 v[2:17], v[162:165], v[246:249], v[2:17]
	s_waitcnt vmcnt(11)
	ds_write_b128 v144, v[174:177]
	s_waitcnt vmcnt(10)
	ds_write_b128 v144, v[178:181] offset:5120
	s_waitcnt vmcnt(9)
	ds_write_b128 v144, v[182:185] offset:10240
	s_waitcnt vmcnt(8)
	ds_write_b128 v144, v[186:189] offset:15360
	s_waitcnt vmcnt(7)
	ds_write_b128 v144, v[190:193] offset:20480
	s_waitcnt vmcnt(6)
	ds_write_b128 v144, v[194:197] offset:25600
	s_waitcnt lgkmcnt(0)
	s_barrier
	ds_read_b128 v[146:149], v130
	ds_read_b128 v[150:153], v130 offset:2560
	ds_read_b128 v[154:157], v130 offset:5120
	ds_read_b128 v[158:161], v130 offset:7680
	ds_read_b128 v[162:165], v0 offset:20480
	ds_read_b128 v[166:169], v0 offset:23040
	global_load_dwordx4 v[174:177], v[132:133], off offset:512
	global_load_dwordx4 v[178:181], v[134:135], off offset:512
	global_load_dwordx4 v[182:185], v[136:137], off offset:512
	global_load_dwordx4 v[186:189], v[138:139], off offset:512
	v_lshl_add_u64 v[190:191], s[8:9], 0, v[140:141]
	v_lshl_add_u64 v[194:195], s[8:9], 0, v[142:143]
	global_load_dwordx4 v[190:193], v[190:191], off
	s_nop 0
	global_load_dwordx4 v[194:197], v[194:195], off
	s_waitcnt lgkmcnt(1)
	v_mfma_f32_32x32x16_f16 v[114:129], v[146:149], v[162:165], v[114:129]
	s_waitcnt lgkmcnt(0)
	v_mfma_f32_32x32x16_f16 v[98:113], v[146:149], v[166:169], v[98:113]
	v_mfma_f32_32x32x16_f16 v[82:97], v[150:153], v[162:165], v[82:97]
	v_mfma_f32_32x32x16_f16 v[66:81], v[150:153], v[166:169], v[66:81]
	v_mfma_f32_32x32x16_f16 v[50:65], v[154:157], v[162:165], v[50:65]
	v_mfma_f32_32x32x16_f16 v[34:49], v[154:157], v[166:169], v[34:49]
	v_mfma_f32_32x32x16_f16 v[18:33], v[158:161], v[162:165], v[18:33]
	ds_read_b128 v[146:149], v130 offset:32
	ds_read_b128 v[150:153], v130 offset:2592
	ds_read_b128 v[154:157], v130 offset:5152
	ds_read_b128 v[162:165], v130 offset:7712
	ds_read_b128 v[242:245], v0 offset:20512
	ds_read_b128 v[246:249], v0 offset:23072
	v_mfma_f32_32x32x16_f16 v[2:17], v[158:161], v[166:169], v[2:17]
	s_waitcnt lgkmcnt(1)
	v_mfma_f32_32x32x16_f16 v[114:129], v[146:149], v[242:245], v[114:129]
	s_waitcnt lgkmcnt(0)
	v_mfma_f32_32x32x16_f16 v[98:113], v[146:149], v[246:249], v[98:113]
	v_mfma_f32_32x32x16_f16 v[82:97], v[150:153], v[242:245], v[82:97]
	v_mfma_f32_32x32x16_f16 v[66:81], v[150:153], v[246:249], v[66:81]
	v_mfma_f32_32x32x16_f16 v[50:65], v[154:157], v[242:245], v[50:65]
	v_mfma_f32_32x32x16_f16 v[34:49], v[154:157], v[246:249], v[34:49]
	v_mfma_f32_32x32x16_f16 v[18:33], v[162:165], v[242:245], v[18:33]
	v_mfma_f32_32x32x16_f16 v[2:17], v[162:165], v[246:249], v[2:17]
	s_waitcnt vmcnt(11)
	ds_write_b128 v144, v[170:173] offset:30720
	s_waitcnt vmcnt(10)
	ds_write_b128 v144, v[198:201] offset:35840
	s_waitcnt vmcnt(9)
	ds_write_b128 v144, v[204:207] offset:40960
	s_waitcnt vmcnt(8)
	ds_write_b128 v144, v[208:211] offset:46080
	s_waitcnt vmcnt(7)
	ds_write_b128 v144, v[212:215] offset:51200
	s_waitcnt vmcnt(6)
	ds_write_b128 v144, v[238:241] offset:56320
	s_waitcnt lgkmcnt(0)
	s_barrier
	ds_read_b128 v[146:149], v130 offset:33280
	ds_read_b128 v[150:153], v130 offset:35840
	ds_read_b128 v[154:157], v130 offset:30720
	ds_read_b128 v[158:161], v130 offset:38400
	ds_read_b128 v[162:165], v0 offset:51200
	ds_read_b128 v[166:169], v0 offset:53760
	global_load_dwordx4 v[170:173], v[132:133], off offset:576
	global_load_dwordx4 v[198:201], v[134:135], off offset:576
	global_load_dwordx4 v[204:207], v[136:137], off offset:576
	global_load_dwordx4 v[208:211], v[138:139], off offset:576
	v_lshl_add_u64 v[212:213], s[10:11], 0, v[140:141]
	v_lshl_add_u64 v[216:217], s[10:11], 0, v[142:143]
	global_load_dwordx4 v[212:215], v[212:213], off
	s_nop 0
	global_load_dwordx4 v[238:241], v[216:217], off
	s_waitcnt lgkmcnt(1)
	v_mfma_f32_32x32x16_f16 v[114:129], v[154:157], v[162:165], v[114:129]
	s_waitcnt lgkmcnt(0)
	v_mfma_f32_32x32x16_f16 v[98:113], v[154:157], v[166:169], v[98:113]
	v_mfma_f32_32x32x16_f16 v[82:97], v[146:149], v[162:165], v[82:97]
	v_mfma_f32_32x32x16_f16 v[66:81], v[146:149], v[166:169], v[66:81]
	v_mfma_f32_32x32x16_f16 v[50:65], v[150:153], v[162:165], v[50:65]
	v_mfma_f32_32x32x16_f16 v[34:49], v[150:153], v[166:169], v[34:49]
	v_mfma_f32_32x32x16_f16 v[18:33], v[158:161], v[162:165], v[18:33]
	ds_read_b128 v[146:149], v130 offset:33312
	ds_read_b128 v[150:153], v130 offset:35872
	ds_read_b128 v[154:157], v130 offset:30752
	ds_read_b128 v[162:165], v130 offset:38432
	ds_read_b128 v[242:245], v0 offset:51232
	ds_read_b128 v[246:249], v0 offset:53792
	v_mfma_f32_32x32x16_f16 v[2:17], v[158:161], v[166:169], v[2:17]
	s_waitcnt lgkmcnt(1)
	v_mfma_f32_32x32x16_f16 v[114:129], v[154:157], v[242:245], v[114:129]
	s_waitcnt lgkmcnt(0)
	v_mfma_f32_32x32x16_f16 v[98:113], v[154:157], v[246:249], v[98:113]
	v_mfma_f32_32x32x16_f16 v[82:97], v[146:149], v[242:245], v[82:97]
	v_mfma_f32_32x32x16_f16 v[66:81], v[146:149], v[246:249], v[66:81]
	v_mfma_f32_32x32x16_f16 v[50:65], v[150:153], v[242:245], v[50:65]
	v_mfma_f32_32x32x16_f16 v[34:49], v[150:153], v[246:249], v[34:49]
	v_mfma_f32_32x32x16_f16 v[18:33], v[162:165], v[242:245], v[18:33]
	v_mfma_f32_32x32x16_f16 v[2:17], v[162:165], v[246:249], v[2:17]
	s_waitcnt vmcnt(11)
	ds_write_b128 v144, v[174:177]
	s_waitcnt vmcnt(10)
	ds_write_b128 v144, v[178:181] offset:5120
	s_waitcnt vmcnt(9)
	ds_write_b128 v144, v[182:185] offset:10240
	s_waitcnt vmcnt(8)
	ds_write_b128 v144, v[186:189] offset:15360
	s_waitcnt vmcnt(7)
	ds_write_b128 v144, v[190:193] offset:20480
	s_waitcnt vmcnt(6)
	ds_write_b128 v144, v[194:197] offset:25600
	s_waitcnt lgkmcnt(0)
	s_barrier
	ds_read_b128 v[146:149], v130
	ds_read_b128 v[150:153], v130 offset:2560
	ds_read_b128 v[154:157], v130 offset:5120
	ds_read_b128 v[158:161], v130 offset:7680
	ds_read_b128 v[162:165], v0 offset:20480
	ds_read_b128 v[166:169], v0 offset:23040
	global_load_dwordx4 v[174:177], v[132:133], off offset:640
	global_load_dwordx4 v[178:181], v[134:135], off offset:640
	global_load_dwordx4 v[182:185], v[136:137], off offset:640
	global_load_dwordx4 v[186:189], v[138:139], off offset:640
	v_lshl_add_u64 v[190:191], s[12:13], 0, v[140:141]
	v_lshl_add_u64 v[194:195], s[12:13], 0, v[142:143]
	global_load_dwordx4 v[190:193], v[190:191], off
	s_nop 0
	global_load_dwordx4 v[194:197], v[194:195], off
	s_waitcnt lgkmcnt(1)
	v_mfma_f32_32x32x16_f16 v[114:129], v[146:149], v[162:165], v[114:129]
	s_waitcnt lgkmcnt(0)
	v_mfma_f32_32x32x16_f16 v[98:113], v[146:149], v[166:169], v[98:113]
	v_mfma_f32_32x32x16_f16 v[82:97], v[150:153], v[162:165], v[82:97]
	v_mfma_f32_32x32x16_f16 v[66:81], v[150:153], v[166:169], v[66:81]
	v_mfma_f32_32x32x16_f16 v[50:65], v[154:157], v[162:165], v[50:65]
	v_mfma_f32_32x32x16_f16 v[34:49], v[154:157], v[166:169], v[34:49]
	v_mfma_f32_32x32x16_f16 v[18:33], v[158:161], v[162:165], v[18:33]
	ds_read_b128 v[146:149], v130 offset:32
	ds_read_b128 v[150:153], v130 offset:2592
	ds_read_b128 v[154:157], v130 offset:5152
	ds_read_b128 v[162:165], v130 offset:7712
	ds_read_b128 v[242:245], v0 offset:20512
	ds_read_b128 v[246:249], v0 offset:23072
	v_mfma_f32_32x32x16_f16 v[2:17], v[158:161], v[166:169], v[2:17]
	s_waitcnt lgkmcnt(1)
	v_mfma_f32_32x32x16_f16 v[114:129], v[146:149], v[242:245], v[114:129]
	s_waitcnt lgkmcnt(0)
	v_mfma_f32_32x32x16_f16 v[98:113], v[146:149], v[246:249], v[98:113]
	v_mfma_f32_32x32x16_f16 v[82:97], v[150:153], v[242:245], v[82:97]
	v_mfma_f32_32x32x16_f16 v[66:81], v[150:153], v[246:249], v[66:81]
	v_mfma_f32_32x32x16_f16 v[50:65], v[154:157], v[242:245], v[50:65]
	v_mfma_f32_32x32x16_f16 v[34:49], v[154:157], v[246:249], v[34:49]
	v_mfma_f32_32x32x16_f16 v[18:33], v[162:165], v[242:245], v[18:33]
	v_mfma_f32_32x32x16_f16 v[2:17], v[162:165], v[246:249], v[2:17]
	s_waitcnt vmcnt(11)
	ds_write_b128 v144, v[170:173] offset:30720
	s_waitcnt vmcnt(10)
	ds_write_b128 v144, v[198:201] offset:35840
	s_waitcnt vmcnt(9)
	ds_write_b128 v144, v[204:207] offset:40960
	s_waitcnt vmcnt(8)
	ds_write_b128 v144, v[208:211] offset:46080
	s_waitcnt vmcnt(7)
	ds_write_b128 v144, v[212:215] offset:51200
	s_waitcnt vmcnt(6)
	ds_write_b128 v144, v[238:241] offset:56320
	s_waitcnt lgkmcnt(0)
	s_barrier
; template <class BR>
; DI void gemm_tile_w(const h16* __restrict__ A, int lda, const h16* __restrict__ B, int ldb, BR brow, int K, f32x16 (&acc)[4][2], h16* sm) {
;     ...
;   for (int kt = 0; kt < nk; kt += 2) {
;     WIDE_HALF(ra0, rb0, 0, kt)
;     WIDE_HALF(ra1, rb1, 1, kt + 1)
;   }
;     ...
;   __syncthreads();
	ds_read_b128 v[146:149], v130 offset:33280
	ds_read_b128 v[150:153], v130 offset:35840
	ds_read_b128 v[154:157], v130 offset:30720
	ds_read_b128 v[158:161], v130 offset:38400
	ds_read_b128 v[162:165], v0 offset:51200
	ds_read_b128 v[166:169], v0 offset:53760
	global_load_dwordx4 v[170:173], v[132:133], off offset:704
	s_nop 0
	global_load_dwordx4 v[132:135], v[134:135], off offset:704
	s_nop 0
	global_load_dwordx4 v[198:201], v[136:137], off offset:704
	s_nop 0
	global_load_dwordx4 v[136:139], v[138:139], off offset:704
	v_lshl_add_u64 v[140:141], s[14:15], 0, v[140:141]
	v_lshl_add_u64 v[204:205], s[14:15], 0, v[142:143]
	global_load_dwordx4 v[140:143], v[140:141], off
	s_nop 0
	global_load_dwordx4 v[204:207], v[204:205], off
	s_waitcnt lgkmcnt(1)
	v_mfma_f32_32x32x16_f16 v[114:129], v[154:157], v[162:165], v[114:129]
	s_waitcnt lgkmcnt(0)
	v_mfma_f32_32x32x16_f16 v[98:113], v[154:157], v[166:169], v[98:113]
	v_mfma_f32_32x32x16_f16 v[82:97], v[146:149], v[162:165], v[82:97]
	v_mfma_f32_32x32x16_f16 v[66:81], v[146:149], v[166:169], v[66:81]
	v_mfma_f32_32x32x16_f16 v[50:65], v[150:153], v[162:165], v[50:65]
	v_mfma_f32_32x32x16_f16 v[34:49], v[150:153], v[166:169], v[34:49]
	v_mfma_f32_32x32x16_f16 v[18:33], v[158:161], v[162:165], v[18:33]
	ds_read_b128 v[146:149], v130 offset:33312
	ds_read_b128 v[150:153], v130 offset:35872
	ds_read_b128 v[154:157], v130 offset:30752
	ds_read_b128 v[162:165], v130 offset:38432
	ds_read_b128 v[208:211], v0 offset:51232
	ds_read_b128 v[212:215], v0 offset:53792
	v_mfma_f32_32x32x16_f16 v[2:17], v[158:161], v[166:169], v[2:17]
	s_waitcnt lgkmcnt(1)
	v_mfma_f32_32x32x16_f16 v[114:129], v[154:157], v[208:211], v[114:129]
	s_waitcnt lgkmcnt(0)
	v_mfma_f32_32x32x16_f16 v[98:113], v[154:157], v[212:215], v[98:113]
	v_mfma_f32_32x32x16_f16 v[82:97], v[146:149], v[208:211], v[82:97]
	v_mfma_f32_32x32x16_f16 v[66:81], v[146:149], v[212:215], v[66:81]
	v_mfma_f32_32x32x16_f16 v[50:65], v[150:153], v[208:211], v[50:65]
	v_mfma_f32_32x32x16_f16 v[34:49], v[150:153], v[212:215], v[34:49]
	v_mfma_f32_32x32x16_f16 v[18:33], v[162:165], v[208:211], v[18:33]
	v_mfma_f32_32x32x16_f16 v[2:17], v[162:165], v[212:215], v[2:17]
	s_waitcnt vmcnt(11)
	ds_write_b128 v144, v[174:177]
	s_waitcnt vmcnt(10)
	ds_write_b128 v144, v[178:181] offset:5120
	s_waitcnt vmcnt(9)
	ds_write_b128 v144, v[182:185] offset:10240
	s_waitcnt vmcnt(8)
	ds_write_b128 v144, v[186:189] offset:15360
	s_waitcnt vmcnt(7)
	ds_write_b128 v144, v[190:193] offset:20480
	s_waitcnt vmcnt(6)
	ds_write_b128 v144, v[194:197] offset:25600
	s_waitcnt lgkmcnt(0)
	s_barrier
	ds_read_b128 v[146:149], v130
	ds_read_b128 v[150:153], v130 offset:2560
	ds_read_b128 v[154:157], v130 offset:5120
	ds_read_b128 v[158:161], v130 offset:7680
	ds_read_b128 v[162:165], v0 offset:20480
	ds_read_b128 v[166:169], v0 offset:23040
	s_waitcnt lgkmcnt(1)
	v_mfma_f32_32x32x16_f16 v[114:129], v[146:149], v[162:165], v[114:129]
	s_waitcnt lgkmcnt(0)
	v_mfma_f32_32x32x16_f16 v[98:113], v[146:149], v[166:169], v[98:113]
	v_mfma_f32_32x32x16_f16 v[82:97], v[150:153], v[162:165], v[82:97]
	v_mfma_f32_32x32x16_f16 v[66:81], v[150:153], v[166:169], v[66:81]
	v_mfma_f32_32x32x16_f16 v[50:65], v[154:157], v[162:165], v[50:65]
	v_mfma_f32_32x32x16_f16 v[34:49], v[154:157], v[166:169], v[34:49]
	v_mfma_f32_32x32x16_f16 v[18:33], v[158:161], v[162:165], v[18:33]
	ds_read_b128 v[146:149], v130 offset:32
	ds_read_b128 v[150:153], v130 offset:2592
	ds_read_b128 v[154:157], v130 offset:5152
	ds_read_b128 v[162:165], v130 offset:7712
	ds_read_b128 v[174:177], v0 offset:20512
	ds_read_b128 v[178:181], v0 offset:23072
	v_mfma_f32_32x32x16_f16 v[2:17], v[158:161], v[166:169], v[2:17]
	s_waitcnt lgkmcnt(1)
	v_mfma_f32_32x32x16_f16 v[114:129], v[146:149], v[174:177], v[114:129]
	s_waitcnt lgkmcnt(0)
	v_mfma_f32_32x32x16_f16 v[98:113], v[146:149], v[178:181], v[98:113]
	v_mfma_f32_32x32x16_f16 v[82:97], v[150:153], v[174:177], v[82:97]
	v_mfma_f32_32x32x16_f16 v[66:81], v[150:153], v[178:181], v[66:81]
	v_mfma_f32_32x32x16_f16 v[50:65], v[154:157], v[174:177], v[50:65]
	v_mfma_f32_32x32x16_f16 v[34:49], v[154:157], v[178:181], v[34:49]
	v_mfma_f32_32x32x16_f16 v[18:33], v[162:165], v[174:177], v[18:33]
	v_mfma_f32_32x32x16_f16 v[2:17], v[162:165], v[178:181], v[2:17]
	s_waitcnt vmcnt(5)
	ds_write_b128 v144, v[170:173] offset:30720
	s_waitcnt vmcnt(4)
	ds_write_b128 v144, v[132:135] offset:35840
	s_waitcnt vmcnt(3)
	ds_write_b128 v144, v[198:201] offset:40960
	s_waitcnt vmcnt(2)
	ds_write_b128 v144, v[136:139] offset:46080
	s_waitcnt vmcnt(1)
	ds_write_b128 v144, v[140:143] offset:51200
	s_waitcnt vmcnt(0)
	ds_write_b128 v144, v[204:207] offset:56320
	s_waitcnt lgkmcnt(0)
	s_barrier
	ds_read_b128 v[132:135], v130 offset:33280
	ds_read_b128 v[136:139], v130 offset:35840
	ds_read_b128 v[140:143], v130 offset:30720
	ds_read_b128 v[144:147], v130 offset:38400
	ds_read_b128 v[148:151], v0 offset:51200
	ds_read_b128 v[152:155], v0 offset:53760
	s_waitcnt lgkmcnt(1)
	v_mfma_f32_32x32x16_f16 v[114:129], v[140:143], v[148:151], v[114:129]
	s_waitcnt lgkmcnt(0)
	v_mfma_f32_32x32x16_f16 v[98:113], v[140:143], v[152:155], v[98:113]
	v_mfma_f32_32x32x16_f16 v[82:97], v[132:135], v[148:151], v[82:97]
	v_mfma_f32_32x32x16_f16 v[66:81], v[132:135], v[152:155], v[66:81]
	v_mfma_f32_32x32x16_f16 v[50:65], v[136:139], v[148:151], v[50:65]
	v_mfma_f32_32x32x16_f16 v[34:49], v[136:139], v[152:155], v[34:49]
	v_mfma_f32_32x32x16_f16 v[18:33], v[144:147], v[148:151], v[18:33]
	ds_read_b128 v[132:135], v130 offset:33312
	ds_read_b128 v[136:139], v130 offset:35872
	ds_read_b128 v[140:143], v130 offset:30752
	ds_read_b128 v[148:151], v130 offset:38432
	ds_read_b128 v[156:159], v0 offset:51232
	ds_read_b128 v[160:163], v0 offset:53792
	v_mfma_f32_32x32x16_f16 v[2:17], v[144:147], v[152:155], v[2:17]
	s_waitcnt lgkmcnt(1)
	v_mfma_f32_32x32x16_f16 v[114:129], v[140:143], v[156:159], v[114:129]
	s_waitcnt lgkmcnt(0)
	v_mfma_f32_32x32x16_f16 v[98:113], v[140:143], v[160:163], v[98:113]
	v_mfma_f32_32x32x16_f16 v[82:97], v[132:135], v[156:159], v[82:97]
	v_mfma_f32_32x32x16_f16 v[66:81], v[132:135], v[160:163], v[66:81]
	v_mfma_f32_32x32x16_f16 v[50:65], v[136:139], v[156:159], v[50:65]
	v_mfma_f32_32x32x16_f16 v[34:49], v[136:139], v[160:163], v[34:49]
	v_mfma_f32_32x32x16_f16 v[18:33], v[148:151], v[156:159], v[18:33]
	v_mfma_f32_32x32x16_f16 v[2:17], v[148:151], v[160:163], v[2:17]
	v_mov_b32_e32 v133, v203
	v_mov_b32_e32 v0, v203
	s_barrier
; DI int srow_of(int row) {
;   if (row < TL) return (row >> 12) * SA + (row & 4095);
;   int rc = row - TL;
;   return (rc >> 8) * SA + 4096 + (rc & 255);
; }
; DI void phase_uproj(const P& p, int l, char* smem, int boff, int geff) {
;     ...
;       epi_foreach_w(acc, m0, n0, [&](int rbase, int n, const f32x16& v) {
;         const int b = rbase < TL ? (rbase >> 12) : ((rbase - TL) >> 8);
;         const int srb = srow_of(rbase);
;         const int head = n / 96, dd = n - head * 96;
;         h16* q = Qm + ((size_t)(b * 7 + head) * SA) * 96 + dd;
;         if (dd < 64 || rbase >= TL) {
; #pragma unroll
;           for (int i = 0; i < 16; ++i) q[(size_t)EROW(srb, i) * 96] = (h16)(v[i] * qscale);
;         } else {
;           const int ii = dd - 64;
; #pragma unroll
	s_nop 0
	v_and_b32_e32 v130, 0xffffff80, v0
	v_add_u32_e32 v130, s21, v130
	v_lshrrev_b32_e32 v131, 3, v133
	v_and_or_b32 v136, v131, 4, v130
	v_mov_b32_e32 v139, v136
	s_nop 0
	v_add_u32_e32 v130, 0xffff8000, v139
	v_cmp_gt_i32_e32 vcc, s87, v139
	v_cmp_lt_i32_e64 s[0:1], s33, v139
	v_lshrrev_b32_e32 v130, 8, v130
	s_and_saveexec_b64 s[22:23], s[0:1]
	s_xor_b64 s[0:1], exec, s[22:23]
	v_mul_u32_u24_e32 v131, 0x1100, v130
	s_movk_i32 s2, 0xff
	v_and_or_b32 v131, v139, s2, v131
	v_add_u32_e32 v137, 0x1000, v131
	s_or_saveexec_b64 s[0:1], s[0:1]
	v_ashrrev_i32_e32 v131, 12, v139
	s_xor_b64 exec, exec, s[0:1]
	v_and_b32_e32 v132, 0xfff, v139
	v_mad_i32_i24 v137, v131, s64, v132
	s_or_b64 exec, exec, s[0:1]
	v_and_b32_e32 v0, 64, v0
	v_and_b32_e32 v132, 31, v133
	v_or3_b32 v132, v132, v0, s20
	s_mov_b32 s0, 0x2aaaaaab
	v_mul_hi_i32 v0, v132, s0
	v_cndmask_b32_e32 v134, v130, v131, vcc
	v_lshrrev_b32_e32 v130, 31, v0
	v_ashrrev_i32_e32 v0, 4, v0
	v_add_u32_e32 v0, v0, v130
	v_mad_u64_u32 v[130:131], s[0:1], v0, s82, v[132:133]
	v_mad_u64_u32 v[134:135], s[0:1], v134, 7, v[0:1]
	v_mov_b64_e32 v[140:141], s[42:43]
	s_mov_b32 s0, 0xcc000
	v_mad_i64_i32 v[134:135], s[0:1], v134, s0, v[140:141]
	v_ashrrev_i32_e32 v131, 31, v130
	v_cmp_lt_i32_e64 s[0:1], 63, v130
	v_cmp_gt_i32_e64 s[38:39], s87, v139
	v_lshl_add_u64 v[134:135], v[130:131], 1, v[134:135]
	v_cmp_gt_i32_e32 vcc, 64, v130
	s_and_b64 s[0:1], s[38:39], s[0:1]
	v_and_b32_e32 v133, 15, v133
	v_add_u32_e32 v152, 1, v137
	v_add_u32_e32 v151, 2, v137
	v_add_u32_e32 v150, 3, v137
	v_add_u32_e32 v149, 8, v137
	v_add_u32_e32 v148, 9, v137
	v_add_u32_e32 v147, 10, v137
	v_add_u32_e32 v146, 11, v137
	v_add_u32_e32 v145, 16, v137
	v_add_u32_e32 v144, 17, v137
	v_add_u32_e32 v143, 18, v137
	v_add_u32_e32 v142, 19, v137
	v_add_u32_e32 v141, 24, v137
	v_add_u32_e32 v140, 25, v137
	v_add_u32_e32 v138, 26, v137
	s_and_saveexec_b64 s[20:21], s[0:1]
	s_xor_b64 s[0:1], exec, s[20:21]
	s_cbranch_execz .LBB0_2189
; DI void phase_uproj(const P& p, int l, char* smem, int boff, int geff) {
;     ...
;         } else {
;           const int ii = dd - 64;
; #pragma unroll
;           for (int i = 0; i < 16; ++i) {
;             float x = v[i];
;             float o = shx(x, 16);
;             f32x2 cs = rm[(EROW(rbase, i) & 4095) * 16 + (ii & 15)];
;             float rr = ii < 16 ? (x * cs.x - o * cs.y) : (o * cs.y + x * cs.x);
;             q[(size_t)EROW(srb, i) * 96] = (h16)(rr * qscale);
;           }
;         }
	v_lshlrev_b32_e32 v213, 4, v139
	s_mov_b32 s2, 0xfff0
	v_and_or_b32 v213, v213, s2, v133
	v_lshlrev_b32_e32 v213, 3, v213
	global_load_dwordx2 v[164:165], v213, s[44:45]
	global_load_dwordx2 v[166:167], v213, s[44:45] offset:128
	global_load_dwordx2 v[168:169], v213, s[44:45] offset:256
	global_load_dwordx2 v[170:171], v213, s[44:45] offset:384
	global_load_dwordx2 v[172:173], v213, s[44:45] offset:1024
	global_load_dwordx2 v[174:175], v213, s[44:45] offset:1152
	global_load_dwordx2 v[176:177], v213, s[44:45] offset:1280
	global_load_dwordx2 v[178:179], v213, s[44:45] offset:1408
	global_load_dwordx2 v[180:181], v213, s[44:45] offset:2048
	global_load_dwordx2 v[182:183], v213, s[44:45] offset:2176
	global_load_dwordx2 v[184:185], v213, s[44:45] offset:2304
	global_load_dwordx2 v[186:187], v213, s[44:45] offset:2432
	global_load_dwordx2 v[188:189], v213, s[44:45] offset:3072
	global_load_dwordx2 v[190:191], v213, s[44:45] offset:3200
	global_load_dwordx2 v[192:193], v213, s[44:45] offset:3328
	global_load_dwordx2 v[194:195], v213, s[44:45] offset:3456
	v_lshlrev_b32_e32 v214, 2, v203
	v_bfrev_b32_e32 v215, 0.5
	v_bitop3_b32 v214, v214, 64, v215 bitop3:0x6c
	v_add_u32_e32 v216, 24, v137
	v_cmp_gt_u32_e64 s[38:39], s76, v130
	v_mad_i64_i32 v[218:219], s[20:21], v137, s29, v[134:135]
	v_mad_i64_i32 v[220:221], s[20:21], v216, s29, v[134:135]
	ds_bpermute_b32 v196, v214, v114
	ds_bpermute_b32 v197, v214, v115
	ds_bpermute_b32 v198, v214, v116
	ds_bpermute_b32 v199, v214, v117
	ds_bpermute_b32 v200, v214, v118
	ds_bpermute_b32 v201, v214, v119
	ds_bpermute_b32 v202, v214, v120
	ds_bpermute_b32 v204, v214, v121
	s_waitcnt vmcnt(15) lgkmcnt(7)
	v_mul_f32_e32 v196, v165, v196
	s_waitcnt vmcnt(14) lgkmcnt(6)
	v_mul_f32_e32 v197, v167, v197
	s_waitcnt vmcnt(13) lgkmcnt(5)
	v_mul_f32_e32 v198, v169, v198
	s_waitcnt vmcnt(12) lgkmcnt(4)
	v_mul_f32_e32 v199, v171, v199
	s_waitcnt vmcnt(11) lgkmcnt(3)
	v_mul_f32_e32 v200, v173, v200
	s_waitcnt vmcnt(10) lgkmcnt(2)
	v_mul_f32_e32 v201, v175, v201
	s_waitcnt vmcnt(9) lgkmcnt(1)
	v_mul_f32_e32 v202, v177, v202
	s_waitcnt vmcnt(8) lgkmcnt(0)
	v_mul_f32_e32 v204, v179, v204
	v_cndmask_b32_e64 v196, v196, -v196, s[38:39]
	v_cndmask_b32_e64 v197, v197, -v197, s[38:39]
	v_cndmask_b32_e64 v198, v198, -v198, s[38:39]
	v_cndmask_b32_e64 v199, v199, -v199, s[38:39]
	v_cndmask_b32_e64 v200, v200, -v200, s[38:39]
	v_cndmask_b32_e64 v201, v201, -v201, s[38:39]
	v_cndmask_b32_e64 v202, v202, -v202, s[38:39]
	v_cndmask_b32_e64 v204, v204, -v204, s[38:39]
	v_fmac_f32_e32 v196, v114, v164
	v_fmac_f32_e32 v197, v115, v166
	v_fmac_f32_e32 v198, v116, v168
	v_fmac_f32_e32 v199, v117, v170
	v_fmac_f32_e32 v200, v118, v172
	v_fmac_f32_e32 v201, v119, v174
	v_fmac_f32_e32 v202, v120, v176
	v_fmac_f32_e32 v204, v121, v178
	v_fma_mixlo_f16 v196, v196, s30, 0
	v_fma_mixlo_f16 v197, v197, s30, 0
	v_fma_mixlo_f16 v198, v198, s30, 0
	v_fma_mixlo_f16 v199, v199, s30, 0
	v_fma_mixlo_f16 v200, v200, s30, 0
	v_fma_mixlo_f16 v201, v201, s30, 0
	v_fma_mixlo_f16 v202, v202, s30, 0
	v_fma_mixlo_f16 v204, v204, s30, 0
	ds_bpermute_b32 v205, v214, v122
	ds_bpermute_b32 v206, v214, v123
	ds_bpermute_b32 v207, v214, v124
	ds_bpermute_b32 v208, v214, v125
	ds_bpermute_b32 v209, v214, v126
	ds_bpermute_b32 v210, v214, v127
	ds_bpermute_b32 v211, v214, v128
	ds_bpermute_b32 v212, v214, v129
	s_waitcnt vmcnt(7) lgkmcnt(7)
	v_mul_f32_e32 v205, v181, v205
	s_waitcnt vmcnt(6) lgkmcnt(6)
	v_mul_f32_e32 v206, v183, v206
	s_waitcnt vmcnt(5) lgkmcnt(5)
	v_mul_f32_e32 v207, v185, v207
	s_waitcnt vmcnt(4) lgkmcnt(4)
	v_mul_f32_e32 v208, v187, v208
	s_waitcnt vmcnt(3) lgkmcnt(3)
	v_mul_f32_e32 v209, v189, v209
	s_waitcnt vmcnt(2) lgkmcnt(2)
	v_mul_f32_e32 v210, v191, v210
	s_waitcnt vmcnt(1) lgkmcnt(1)
	v_mul_f32_e32 v211, v193, v211
	s_waitcnt vmcnt(0) lgkmcnt(0)
	v_mul_f32_e32 v212, v195, v212
	v_cndmask_b32_e64 v205, v205, -v205, s[38:39]
	v_cndmask_b32_e64 v206, v206, -v206, s[38:39]
	v_cndmask_b32_e64 v207, v207, -v207, s[38:39]
	v_cndmask_b32_e64 v208, v208, -v208, s[38:39]
	v_cndmask_b32_e64 v209, v209, -v209, s[38:39]
	v_cndmask_b32_e64 v210, v210, -v210, s[38:39]
	v_cndmask_b32_e64 v211, v211, -v211, s[38:39]
	v_cndmask_b32_e64 v212, v212, -v212, s[38:39]
	v_fmac_f32_e32 v205, v122, v180
	v_fmac_f32_e32 v206, v123, v182
	v_fmac_f32_e32 v207, v124, v184
	v_fmac_f32_e32 v208, v125, v186
	v_fmac_f32_e32 v209, v126, v188
	v_fmac_f32_e32 v210, v127, v190
	v_fmac_f32_e32 v211, v128, v192
	v_fmac_f32_e32 v212, v129, v194
	v_fma_mixlo_f16 v205, v205, s30, 0
	v_fma_mixlo_f16 v206, v206, s30, 0
	v_fma_mixlo_f16 v207, v207, s30, 0
	v_fma_mixlo_f16 v208, v208, s30, 0
	v_fma_mixlo_f16 v209, v209, s30, 0
	v_fma_mixlo_f16 v210, v210, s30, 0
	v_fma_mixlo_f16 v211, v211, s30, 0
	v_mov_b32_e32 v129, v212
	global_store_short v[218:219], v196, off
	global_store_short v[218:219], v197, off offset:192
	global_store_short v[218:219], v198, off offset:384
	global_store_short v[218:219], v199, off offset:576
	global_store_short v[218:219], v200, off offset:1536
	global_store_short v[218:219], v201, off offset:1728
	global_store_short v[218:219], v202, off offset:1920
	global_store_short v[218:219], v204, off offset:2112
	global_store_short v[218:219], v205, off offset:3072
	global_store_short v[218:219], v206, off offset:3264
	global_store_short v[218:219], v207, off offset:3456
	global_store_short v[218:219], v208, off offset:3648
	global_store_short v[220:221], v209, off
	global_store_short v[220:221], v210, off offset:192
	global_store_short v[220:221], v211, off offset:384

; DI void phase_uproj(const P& p, int l, char* smem, int boff, int geff) {
;     ...
;       epi_foreach_w(acc, m0, n0, [&](int rbase, int n, const f32x16& v) {
;         const int b = rbase < TL ? (rbase >> 12) : ((rbase - TL) >> 8);
;         const int srb = srow_of(rbase);
;         const int head = n / 96, dd = n - head * 96;
;         h16* q = Qm + ((size_t)(b * 7 + head) * SA) * 96 + dd;
;         if (dd < 64 || rbase >= TL) {
; #pragma unroll
;           for (int i = 0; i < 16; ++i) q[(size_t)EROW(srb, i) * 96] = (h16)(v[i] * qscale);
;         } else {
;           const int ii = dd - 64;
; #pragma unroll
;           for (int i = 0; i < 16; ++i) {
;             float x = v[i];
;             float o = shx(x, 16);
;             f32x2 cs = rm[(EROW(rbase, i) & 4095) * 16 + (ii & 15)];
;             float rr = ii < 16 ? (x * cs.x - o * cs.y) : (o * cs.y + x * cs.x);
;             q[(size_t)EROW(srb, i) * 96] = (h16)(rr * qscale);
;           }
;         }
.LBB0_2191:
	s_or_b64 exec, exec, s[0:1]
	v_add_u32_e32 v114, 27, v137
	v_fma_mixlo_f16 v116, v129, s30, 0
	v_mad_i64_i32 v[114:115], s[0:1], v114, s29, v[134:135]
	v_mov_b32_e32 v121, v136
	global_store_short v[114:115], v116, off
	s_nop 0
	v_add_u32_e32 v114, 0xffff8000, v121
	v_cmp_gt_i32_e64 s[0:1], s87, v121
	v_cmp_lt_i32_e64 s[38:39], s33, v121
	v_lshrrev_b32_e32 v114, 8, v114
	s_and_saveexec_b64 s[20:21], s[38:39]
	s_xor_b64 s[38:39], exec, s[20:21]
	v_mul_u32_u24_e32 v115, 0x1100, v114
	s_movk_i32 s2, 0xff
	v_and_or_b32 v115, v121, s2, v115
	v_add_u32_e32 v117, 0x1000, v115
	s_or_saveexec_b64 s[38:39], s[38:39]
	v_ashrrev_i32_e32 v115, 12, v121
	s_xor_b64 exec, exec, s[38:39]
	v_and_b32_e32 v116, 0xfff, v121
	v_mad_i32_i24 v117, v115, s64, v116
	s_or_b64 exec, exec, s[38:39]
	v_or_b32_e32 v118, 32, v132
	v_cndmask_b32_e64 v119, v114, v115, s[0:1]
	s_mov_b32 s0, 0x2aaaaaab
	v_mul_hi_i32 v114, v118, s0
	v_lshrrev_b32_e32 v115, 31, v114
	v_ashrrev_i32_e32 v114, 4, v114
	v_add_u32_e32 v116, v114, v115
	v_mad_u64_u32 v[114:115], s[0:1], v116, s82, v[118:119]
	v_mad_u64_u32 v[118:119], s[0:1], v119, 7, v[116:117]
	v_mov_b64_e32 v[122:123], s[42:43]
	s_mov_b32 s0, 0xcc000
	v_mad_i64_i32 v[118:119], s[0:1], v118, s0, v[122:123]
	v_ashrrev_i32_e32 v115, 31, v114
	v_cmp_lt_i32_e64 s[0:1], 63, v114
	v_cmp_gt_i32_e64 s[40:41], s87, v121
	v_lshl_add_u64 v[118:119], v[114:115], 1, v[118:119]
	v_cmp_gt_i32_e64 s[38:39], 64, v114
	s_and_b64 s[0:1], s[0:1], s[40:41]
	v_add_u32_e32 v138, 1, v117
	v_add_u32_e32 v137, 2, v117
	v_add_u32_e32 v135, 3, v117
	v_add_u32_e32 v134, 8, v117
	v_add_u32_e32 v132, 9, v117
	v_add_u32_e32 v129, 10, v117
	v_add_u32_e32 v128, 11, v117
	v_add_u32_e32 v127, 16, v117
	v_add_u32_e32 v126, 17, v117
	v_add_u32_e32 v125, 18, v117
	v_add_u32_e32 v124, 19, v117
	v_add_u32_e32 v123, 24, v117
	v_add_u32_e32 v122, 25, v117
	v_add_u32_e32 v120, 26, v117
	s_and_saveexec_b64 s[20:21], s[0:1]
	s_xor_b64 s[0:1], exec, s[20:21]
	s_cbranch_execz .LBB0_2197
; DI void phase_uproj(const P& p, int l, char* smem, int boff, int geff) {
;     ...
;         } else {
;           const int ii = dd - 64;
; #pragma unroll
;           for (int i = 0; i < 16; ++i) {
;             float x = v[i];
;             float o = shx(x, 16);
;             f32x2 cs = rm[(EROW(rbase, i) & 4095) * 16 + (ii & 15)];
;             float rr = ii < 16 ? (x * cs.x - o * cs.y) : (o * cs.y + x * cs.x);
;             q[(size_t)EROW(srb, i) * 96] = (h16)(rr * qscale);
;           }
;         }
	v_lshlrev_b32_e32 v213, 4, v121
	s_mov_b32 s2, 0xfff0
	v_and_or_b32 v213, v213, s2, v133
	v_lshlrev_b32_e32 v213, 3, v213
	global_load_dwordx2 v[164:165], v213, s[44:45]
	global_load_dwordx2 v[166:167], v213, s[44:45] offset:128
	global_load_dwordx2 v[168:169], v213, s[44:45] offset:256
	global_load_dwordx2 v[170:171], v213, s[44:45] offset:384
	global_load_dwordx2 v[172:173], v213, s[44:45] offset:1024
	global_load_dwordx2 v[174:175], v213, s[44:45] offset:1152
	global_load_dwordx2 v[176:177], v213, s[44:45] offset:1280
	global_load_dwordx2 v[178:179], v213, s[44:45] offset:1408
	global_load_dwordx2 v[180:181], v213, s[44:45] offset:2048
	global_load_dwordx2 v[182:183], v213, s[44:45] offset:2176
	global_load_dwordx2 v[184:185], v213, s[44:45] offset:2304
	global_load_dwordx2 v[186:187], v213, s[44:45] offset:2432
	global_load_dwordx2 v[188:189], v213, s[44:45] offset:3072
	global_load_dwordx2 v[190:191], v213, s[44:45] offset:3200
	global_load_dwordx2 v[192:193], v213, s[44:45] offset:3328
	global_load_dwordx2 v[194:195], v213, s[44:45] offset:3456
	v_lshlrev_b32_e32 v214, 2, v203
	v_bfrev_b32_e32 v215, 0.5
	v_bitop3_b32 v214, v214, 64, v215 bitop3:0x6c
	v_add_u32_e32 v216, 24, v117
	v_cmp_gt_u32_e64 s[40:41], s76, v114
	v_mad_i64_i32 v[218:219], s[20:21], v117, s29, v[118:119]
	v_mad_i64_i32 v[220:221], s[20:21], v216, s29, v[118:119]
	ds_bpermute_b32 v196, v214, v98
	ds_bpermute_b32 v197, v214, v99
	ds_bpermute_b32 v198, v214, v100
	ds_bpermute_b32 v199, v214, v101
	ds_bpermute_b32 v200, v214, v102
	ds_bpermute_b32 v201, v214, v103
	ds_bpermute_b32 v202, v214, v104
	ds_bpermute_b32 v204, v214, v105
	s_waitcnt vmcnt(15) lgkmcnt(7)
	v_mul_f32_e32 v196, v165, v196
	s_waitcnt vmcnt(14) lgkmcnt(6)
	v_mul_f32_e32 v197, v167, v197
	s_waitcnt vmcnt(13) lgkmcnt(5)
	v_mul_f32_e32 v198, v169, v198
	s_waitcnt vmcnt(12) lgkmcnt(4)
	v_mul_f32_e32 v199, v171, v199
	s_waitcnt vmcnt(11) lgkmcnt(3)
	v_mul_f32_e32 v200, v173, v200
	s_waitcnt vmcnt(10) lgkmcnt(2)
	v_mul_f32_e32 v201, v175, v201
	s_waitcnt vmcnt(9) lgkmcnt(1)
	v_mul_f32_e32 v202, v177, v202
	s_waitcnt vmcnt(8) lgkmcnt(0)
	v_mul_f32_e32 v204, v179, v204
	v_cndmask_b32_e64 v196, v196, -v196, s[40:41]
	v_cndmask_b32_e64 v197, v197, -v197, s[40:41]
	v_cndmask_b32_e64 v198, v198, -v198, s[40:41]
	v_cndmask_b32_e64 v199, v199, -v199, s[40:41]
	v_cndmask_b32_e64 v200, v200, -v200, s[40:41]
	v_cndmask_b32_e64 v201, v201, -v201, s[40:41]
	v_cndmask_b32_e64 v202, v202, -v202, s[40:41]
	v_cndmask_b32_e64 v204, v204, -v204, s[40:41]
	v_fmac_f32_e32 v196, v98, v164
	v_fmac_f32_e32 v197, v99, v166
	v_fmac_f32_e32 v198, v100, v168
	v_fmac_f32_e32 v199, v101, v170
	v_fmac_f32_e32 v200, v102, v172
	v_fmac_f32_e32 v201, v103, v174
	v_fmac_f32_e32 v202, v104, v176
	v_fmac_f32_e32 v204, v105, v178
	v_fma_mixlo_f16 v196, v196, s30, 0
	v_fma_mixlo_f16 v197, v197, s30, 0
	v_fma_mixlo_f16 v198, v198, s30, 0
	v_fma_mixlo_f16 v199, v199, s30, 0
	v_fma_mixlo_f16 v200, v200, s30, 0
	v_fma_mixlo_f16 v201, v201, s30, 0
	v_fma_mixlo_f16 v202, v202, s30, 0
	v_fma_mixlo_f16 v204, v204, s30, 0
	ds_bpermute_b32 v205, v214, v106
	ds_bpermute_b32 v206, v214, v107
	ds_bpermute_b32 v207, v214, v108
	ds_bpermute_b32 v208, v214, v109
	ds_bpermute_b32 v209, v214, v110
	ds_bpermute_b32 v210, v214, v111
	ds_bpermute_b32 v211, v214, v112
	ds_bpermute_b32 v212, v214, v113
	s_waitcnt vmcnt(7) lgkmcnt(7)
	v_mul_f32_e32 v205, v181, v205
	s_waitcnt vmcnt(6) lgkmcnt(6)
	v_mul_f32_e32 v206, v183, v206
	s_waitcnt vmcnt(5) lgkmcnt(5)
	v_mul_f32_e32 v207, v185, v207
	s_waitcnt vmcnt(4) lgkmcnt(4)
	v_mul_f32_e32 v208, v187, v208
	s_waitcnt vmcnt(3) lgkmcnt(3)
	v_mul_f32_e32 v209, v189, v209
	s_waitcnt vmcnt(2) lgkmcnt(2)
	v_mul_f32_e32 v210, v191, v210
	s_waitcnt vmcnt(1) lgkmcnt(1)
	v_mul_f32_e32 v211, v193, v211
	s_waitcnt vmcnt(0) lgkmcnt(0)
	v_mul_f32_e32 v212, v195, v212
	v_cndmask_b32_e64 v205, v205, -v205, s[40:41]
	v_cndmask_b32_e64 v206, v206, -v206, s[40:41]
	v_cndmask_b32_e64 v207, v207, -v207, s[40:41]
	v_cndmask_b32_e64 v208, v208, -v208, s[40:41]
	v_cndmask_b32_e64 v209, v209, -v209, s[40:41]
	v_cndmask_b32_e64 v210, v210, -v210, s[40:41]
	v_cndmask_b32_e64 v211, v211, -v211, s[40:41]
	v_cndmask_b32_e64 v212, v212, -v212, s[40:41]
	v_fmac_f32_e32 v205, v106, v180
	v_fmac_f32_e32 v206, v107, v182
	v_fmac_f32_e32 v207, v108, v184
	v_fmac_f32_e32 v208, v109, v186
	v_fmac_f32_e32 v209, v110, v188
	v_fmac_f32_e32 v210, v111, v190
	v_fmac_f32_e32 v211, v112, v192
	v_fmac_f32_e32 v212, v113, v194
	v_fma_mixlo_f16 v205, v205, s30, 0
	v_fma_mixlo_f16 v206, v206, s30, 0
	v_fma_mixlo_f16 v207, v207, s30, 0
	v_fma_mixlo_f16 v208, v208, s30, 0
	v_fma_mixlo_f16 v209, v209, s30, 0
	v_fma_mixlo_f16 v210, v210, s30, 0
	v_fma_mixlo_f16 v211, v211, s30, 0
	v_mov_b32_e32 v113, v212
	global_store_short v[218:219], v196, off
	global_store_short v[218:219], v197, off offset:192
	global_store_short v[218:219], v198, off offset:384
	global_store_short v[218:219], v199, off offset:576
	global_store_short v[218:219], v200, off offset:1536
	global_store_short v[218:219], v201, off offset:1728
	global_store_short v[218:219], v202, off offset:1920
	global_store_short v[218:219], v204, off offset:2112
	global_store_short v[218:219], v205, off offset:3072
	global_store_short v[218:219], v206, off offset:3264
	global_store_short v[218:219], v207, off offset:3456
	global_store_short v[218:219], v208, off offset:3648
	global_store_short v[220:221], v209, off
	global_store_short v[220:221], v210, off offset:192
	global_store_short v[220:221], v211, off offset:384

; DI void phase_uproj(const P& p, int l, char* smem, int boff, int geff) {
;     ...
;       epi_foreach_w(acc, m0, n0, [&](int rbase, int n, const f32x16& v) {
;         const int b = rbase < TL ? (rbase >> 12) : ((rbase - TL) >> 8);
;         const int srb = srow_of(rbase);
;         const int head = n / 96, dd = n - head * 96;
;         h16* q = Qm + ((size_t)(b * 7 + head) * SA) * 96 + dd;
;         if (dd < 64 || rbase >= TL) {
; #pragma unroll
;           for (int i = 0; i < 16; ++i) q[(size_t)EROW(srb, i) * 96] = (h16)(v[i] * qscale);
;         } else {
;           const int ii = dd - 64;
; #pragma unroll
.LBB0_2199:
	s_or_b64 exec, exec, s[0:1]
	v_add_u32_e32 v98, 27, v117
	v_fma_mixlo_f16 v100, v113, s30, 0
	v_mad_i64_i32 v[98:99], s[0:1], v98, s29, v[118:119]
	global_store_short v[98:99], v100, off
	v_or_b32_e32 v100, 32, v136
	v_mov_b32_e32 v103, v100
	s_nop 0
	v_add_u32_e32 v98, 0xffff8000, v103
	v_cmp_gt_i32_e64 s[0:1], s87, v103
	v_cmp_lt_i32_e64 s[40:41], s33, v103
	v_lshrrev_b32_e32 v98, 8, v98
	s_and_saveexec_b64 s[20:21], s[40:41]
	s_xor_b64 s[40:41], exec, s[20:21]
	v_mul_u32_u24_e32 v99, 0x1100, v98
	s_movk_i32 s2, 0xff
	v_and_or_b32 v99, v103, s2, v99
	v_add_u32_e32 v101, 0x1000, v99
	s_or_saveexec_b64 s[40:41], s[40:41]
	v_ashrrev_i32_e32 v99, 12, v103
	s_xor_b64 exec, exec, s[40:41]
	v_and_b32_e32 v101, 0xfff, v103
	v_mad_i32_i24 v101, v99, s64, v101
	s_or_b64 exec, exec, s[40:41]
	v_cndmask_b32_e64 v98, v98, v99, s[0:1]
	v_mad_u64_u32 v[98:99], s[0:1], v98, 7, v[0:1]
	v_mov_b64_e32 v[104:105], s[42:43]
	s_mov_b32 s0, 0xcc000
	v_mad_i64_i32 v[98:99], s[0:1], v98, s0, v[104:105]
	v_cmp_gt_i32_e64 s[0:1], s87, v103
	s_xor_b64 s[40:41], vcc, -1
	v_lshl_add_u64 v[98:99], v[130:131], 1, v[98:99]
	s_and_b64 s[0:1], s[40:41], s[0:1]
	v_add_u32_e32 v119, 1, v101
	v_add_u32_e32 v118, 2, v101
	v_add_u32_e32 v117, 3, v101
	v_add_u32_e32 v113, 8, v101
	v_add_u32_e32 v112, 9, v101
	v_add_u32_e32 v111, 10, v101
	v_add_u32_e32 v110, 11, v101
	v_add_u32_e32 v109, 16, v101
	v_add_u32_e32 v108, 17, v101
	v_add_u32_e32 v107, 18, v101
	v_add_u32_e32 v106, 19, v101
	v_add_u32_e32 v105, 24, v101
	v_add_u32_e32 v104, 25, v101
	v_add_u32_e32 v102, 26, v101
	s_and_saveexec_b64 s[20:21], s[0:1]
	s_xor_b64 s[0:1], exec, s[20:21]
	s_cbranch_execz .LBB0_2205
; DI void phase_uproj(const P& p, int l, char* smem, int boff, int geff) {
;     ...
;         } else {
;           const int ii = dd - 64;
; #pragma unroll
;           for (int i = 0; i < 16; ++i) {
;             float x = v[i];
;             float o = shx(x, 16);
;             f32x2 cs = rm[(EROW(rbase, i) & 4095) * 16 + (ii & 15)];
;             float rr = ii < 16 ? (x * cs.x - o * cs.y) : (o * cs.y + x * cs.x);
;             q[(size_t)EROW(srb, i) * 96] = (h16)(rr * qscale);
;           }
;         }
	v_lshlrev_b32_e32 v213, 4, v103
	s_mov_b32 s2, 0xfff0
	v_and_or_b32 v213, v213, s2, v133
	v_lshlrev_b32_e32 v213, 3, v213
	global_load_dwordx2 v[164:165], v213, s[44:45]
	global_load_dwordx2 v[166:167], v213, s[44:45] offset:128
	global_load_dwordx2 v[168:169], v213, s[44:45] offset:256
	global_load_dwordx2 v[170:171], v213, s[44:45] offset:384
	global_load_dwordx2 v[172:173], v213, s[44:45] offset:1024
	global_load_dwordx2 v[174:175], v213, s[44:45] offset:1152
	global_load_dwordx2 v[176:177], v213, s[44:45] offset:1280
	global_load_dwordx2 v[178:179], v213, s[44:45] offset:1408
	global_load_dwordx2 v[180:181], v213, s[44:45] offset:2048
	global_load_dwordx2 v[182:183], v213, s[44:45] offset:2176
	global_load_dwordx2 v[184:185], v213, s[44:45] offset:2304
	global_load_dwordx2 v[186:187], v213, s[44:45] offset:2432
	global_load_dwordx2 v[188:189], v213, s[44:45] offset:3072
	global_load_dwordx2 v[190:191], v213, s[44:45] offset:3200
	global_load_dwordx2 v[192:193], v213, s[44:45] offset:3328
	global_load_dwordx2 v[194:195], v213, s[44:45] offset:3456
	v_lshlrev_b32_e32 v214, 2, v203
	v_bfrev_b32_e32 v215, 0.5
	v_bitop3_b32 v214, v214, 64, v215 bitop3:0x6c
	v_add_u32_e32 v216, 24, v101
	v_cmp_gt_u32_e64 vcc, s76, v130
	v_mad_i64_i32 v[218:219], s[20:21], v101, s29, v[98:99]
	v_mad_i64_i32 v[220:221], s[20:21], v216, s29, v[98:99]
	ds_bpermute_b32 v196, v214, v82
	ds_bpermute_b32 v197, v214, v83
	ds_bpermute_b32 v198, v214, v84
	ds_bpermute_b32 v199, v214, v85
	ds_bpermute_b32 v200, v214, v86
	ds_bpermute_b32 v201, v214, v87
	ds_bpermute_b32 v202, v214, v88
	ds_bpermute_b32 v204, v214, v89
	s_waitcnt vmcnt(15) lgkmcnt(7)
	v_mul_f32_e32 v196, v165, v196
	s_waitcnt vmcnt(14) lgkmcnt(6)
	v_mul_f32_e32 v197, v167, v197
	s_waitcnt vmcnt(13) lgkmcnt(5)
	v_mul_f32_e32 v198, v169, v198
	s_waitcnt vmcnt(12) lgkmcnt(4)
	v_mul_f32_e32 v199, v171, v199
	s_waitcnt vmcnt(11) lgkmcnt(3)
	v_mul_f32_e32 v200, v173, v200
	s_waitcnt vmcnt(10) lgkmcnt(2)
	v_mul_f32_e32 v201, v175, v201
	s_waitcnt vmcnt(9) lgkmcnt(1)
	v_mul_f32_e32 v202, v177, v202
	s_waitcnt vmcnt(8) lgkmcnt(0)
	v_mul_f32_e32 v204, v179, v204
	v_cndmask_b32_e64 v196, v196, -v196, vcc
	v_cndmask_b32_e64 v197, v197, -v197, vcc
	v_cndmask_b32_e64 v198, v198, -v198, vcc
	v_cndmask_b32_e64 v199, v199, -v199, vcc
	v_cndmask_b32_e64 v200, v200, -v200, vcc
	v_cndmask_b32_e64 v201, v201, -v201, vcc
	v_cndmask_b32_e64 v202, v202, -v202, vcc
	v_cndmask_b32_e64 v204, v204, -v204, vcc
	v_fmac_f32_e32 v196, v82, v164
	v_fmac_f32_e32 v197, v83, v166
	v_fmac_f32_e32 v198, v84, v168
	v_fmac_f32_e32 v199, v85, v170
	v_fmac_f32_e32 v200, v86, v172
	v_fmac_f32_e32 v201, v87, v174
	v_fmac_f32_e32 v202, v88, v176
	v_fmac_f32_e32 v204, v89, v178
	v_fma_mixlo_f16 v196, v196, s30, 0
	v_fma_mixlo_f16 v197, v197, s30, 0
	v_fma_mixlo_f16 v198, v198, s30, 0
	v_fma_mixlo_f16 v199, v199, s30, 0
	v_fma_mixlo_f16 v200, v200, s30, 0
	v_fma_mixlo_f16 v201, v201, s30, 0
	v_fma_mixlo_f16 v202, v202, s30, 0
	v_fma_mixlo_f16 v204, v204, s30, 0
	ds_bpermute_b32 v205, v214, v90
	ds_bpermute_b32 v206, v214, v91
	ds_bpermute_b32 v207, v214, v92
	ds_bpermute_b32 v208, v214, v93
	ds_bpermute_b32 v209, v214, v94
	ds_bpermute_b32 v210, v214, v95
	ds_bpermute_b32 v211, v214, v96
	ds_bpermute_b32 v212, v214, v97
	s_waitcnt vmcnt(7) lgkmcnt(7)
	v_mul_f32_e32 v205, v181, v205
	s_waitcnt vmcnt(6) lgkmcnt(6)
	v_mul_f32_e32 v206, v183, v206
	s_waitcnt vmcnt(5) lgkmcnt(5)
	v_mul_f32_e32 v207, v185, v207
	s_waitcnt vmcnt(4) lgkmcnt(4)
	v_mul_f32_e32 v208, v187, v208
	s_waitcnt vmcnt(3) lgkmcnt(3)
	v_mul_f32_e32 v209, v189, v209
	s_waitcnt vmcnt(2) lgkmcnt(2)
	v_mul_f32_e32 v210, v191, v210
	s_waitcnt vmcnt(1) lgkmcnt(1)
	v_mul_f32_e32 v211, v193, v211
	s_waitcnt vmcnt(0) lgkmcnt(0)
	v_mul_f32_e32 v212, v195, v212
	v_cndmask_b32_e64 v205, v205, -v205, vcc
	v_cndmask_b32_e64 v206, v206, -v206, vcc
	v_cndmask_b32_e64 v207, v207, -v207, vcc
	v_cndmask_b32_e64 v208, v208, -v208, vcc
	v_cndmask_b32_e64 v209, v209, -v209, vcc
	v_cndmask_b32_e64 v210, v210, -v210, vcc
	v_cndmask_b32_e64 v211, v211, -v211, vcc
	v_cndmask_b32_e64 v212, v212, -v212, vcc
	v_fmac_f32_e32 v205, v90, v180
	v_fmac_f32_e32 v206, v91, v182
	v_fmac_f32_e32 v207, v92, v184
	v_fmac_f32_e32 v208, v93, v186
	v_fmac_f32_e32 v209, v94, v188
	v_fmac_f32_e32 v210, v95, v190
	v_fmac_f32_e32 v211, v96, v192
	v_fmac_f32_e32 v212, v97, v194
	v_fma_mixlo_f16 v205, v205, s30, 0
	v_fma_mixlo_f16 v206, v206, s30, 0
	v_fma_mixlo_f16 v207, v207, s30, 0
	v_fma_mixlo_f16 v208, v208, s30, 0
	v_fma_mixlo_f16 v209, v209, s30, 0
	v_fma_mixlo_f16 v210, v210, s30, 0
	v_fma_mixlo_f16 v211, v211, s30, 0
	v_mov_b32_e32 v97, v212
	global_store_short v[218:219], v196, off
	global_store_short v[218:219], v197, off offset:192
	global_store_short v[218:219], v198, off offset:384
	global_store_short v[218:219], v199, off offset:576
	global_store_short v[218:219], v200, off offset:1536
	global_store_short v[218:219], v201, off offset:1728
	global_store_short v[218:219], v202, off offset:1920
	global_store_short v[218:219], v204, off offset:2112
	global_store_short v[218:219], v205, off offset:3072
	global_store_short v[218:219], v206, off offset:3264
	global_store_short v[218:219], v207, off offset:3456
	global_store_short v[218:219], v208, off offset:3648
	global_store_short v[220:221], v209, off
	global_store_short v[220:221], v210, off offset:192
	global_store_short v[220:221], v211, off offset:384

; DI void phase_uproj(const P& p, int l, char* smem, int boff, int geff) {
;     ...
;       epi_foreach_w(acc, m0, n0, [&](int rbase, int n, const f32x16& v) {
;         const int b = rbase < TL ? (rbase >> 12) : ((rbase - TL) >> 8);
;         const int srb = srow_of(rbase);
;         const int head = n / 96, dd = n - head * 96;
;         h16* q = Qm + ((size_t)(b * 7 + head) * SA) * 96 + dd;
;         if (dd < 64 || rbase >= TL) {
; #pragma unroll
;           for (int i = 0; i < 16; ++i) q[(size_t)EROW(srb, i) * 96] = (h16)(v[i] * qscale);
;         } else {
;           const int ii = dd - 64;
; #pragma unroll
;           for (int i = 0; i < 16; ++i) {
;             float x = v[i];
;             float o = shx(x, 16);
;             f32x2 cs = rm[(EROW(rbase, i) & 4095) * 16 + (ii & 15)];
;             float rr = ii < 16 ? (x * cs.x - o * cs.y) : (o * cs.y + x * cs.x);
;             q[(size_t)EROW(srb, i) * 96] = (h16)(rr * qscale);
;           }
;         }
.LBB0_2207:
	s_or_b64 exec, exec, s[0:1]
	v_add_u32_e32 v82, 27, v101
	v_fma_mixlo_f16 v84, v97, s30, 0
	v_mad_i64_i32 v[82:83], s[0:1], v82, s29, v[98:99]
	global_store_short v[82:83], v84, off
	s_nop 0
	v_add_u32_e32 v82, 0xffff8000, v100
	v_cmp_gt_i32_e32 vcc, s87, v100
	v_cmp_lt_i32_e64 s[0:1], s33, v100
	v_lshrrev_b32_e32 v82, 8, v82
	s_and_saveexec_b64 s[20:21], s[0:1]
	s_xor_b64 s[0:1], exec, s[20:21]
	v_mul_u32_u24_e32 v83, 0x1100, v82
	s_movk_i32 s2, 0xff
	v_and_or_b32 v83, v100, s2, v83
	v_add_u32_e32 v84, 0x1000, v83
	s_or_saveexec_b64 s[0:1], s[0:1]
	v_ashrrev_i32_e32 v83, 12, v100
	s_xor_b64 exec, exec, s[0:1]
	v_and_b32_e32 v84, 0xfff, v100
	v_mad_i32_i24 v84, v83, s64, v84
	s_or_b64 exec, exec, s[0:1]
	v_cndmask_b32_e32 v82, v82, v83, vcc
	v_mad_u64_u32 v[82:83], s[0:1], v82, 7, v[116:117]
	v_mov_b64_e32 v[86:87], s[42:43]
	s_mov_b32 s0, 0xcc000
	v_mad_i64_i32 v[82:83], s[0:1], v82, s0, v[86:87]
	v_cmp_gt_i32_e32 vcc, s87, v100
	s_xor_b64 s[38:39], s[38:39], -1
	v_lshl_add_u64 v[82:83], v[114:115], 1, v[82:83]
	s_and_b64 s[0:1], s[38:39], vcc
	v_add_u32_e32 v99, 1, v84
	v_add_u32_e32 v98, 2, v84
	v_add_u32_e32 v97, 3, v84
	v_add_u32_e32 v96, 8, v84
	v_add_u32_e32 v95, 9, v84
	v_add_u32_e32 v94, 10, v84
	v_add_u32_e32 v93, 11, v84
	v_add_u32_e32 v92, 16, v84
	v_add_u32_e32 v91, 17, v84
	v_add_u32_e32 v90, 18, v84
	v_add_u32_e32 v89, 19, v84
	v_add_u32_e32 v88, 24, v84
	v_add_u32_e32 v87, 25, v84
	v_add_u32_e32 v85, 26, v84
	s_and_saveexec_b64 s[20:21], s[0:1]
	s_xor_b64 s[0:1], exec, s[20:21]
	s_cbranch_execz .LBB0_2213
	v_lshlrev_b32_e32 v213, 4, v100
	s_mov_b32 s2, 0xfff0
	v_and_or_b32 v213, v213, s2, v133
	v_lshlrev_b32_e32 v213, 3, v213
	global_load_dwordx2 v[164:165], v213, s[44:45]
	global_load_dwordx2 v[166:167], v213, s[44:45] offset:128
	global_load_dwordx2 v[168:169], v213, s[44:45] offset:256
	global_load_dwordx2 v[170:171], v213, s[44:45] offset:384
	global_load_dwordx2 v[172:173], v213, s[44:45] offset:1024
	global_load_dwordx2 v[174:175], v213, s[44:45] offset:1152
	global_load_dwordx2 v[176:177], v213, s[44:45] offset:1280
	global_load_dwordx2 v[178:179], v213, s[44:45] offset:1408
	global_load_dwordx2 v[180:181], v213, s[44:45] offset:2048
	global_load_dwordx2 v[182:183], v213, s[44:45] offset:2176
	global_load_dwordx2 v[184:185], v213, s[44:45] offset:2304
	global_load_dwordx2 v[186:187], v213, s[44:45] offset:2432
	global_load_dwordx2 v[188:189], v213, s[44:45] offset:3072
	global_load_dwordx2 v[190:191], v213, s[44:45] offset:3200
	global_load_dwordx2 v[192:193], v213, s[44:45] offset:3328
	global_load_dwordx2 v[194:195], v213, s[44:45] offset:3456
	v_lshlrev_b32_e32 v214, 2, v203
	v_bfrev_b32_e32 v215, 0.5
	v_bitop3_b32 v214, v214, 64, v215 bitop3:0x6c
	v_add_u32_e32 v216, 24, v84
	v_cmp_gt_u32_e64 vcc, s76, v114
	v_mad_i64_i32 v[218:219], s[20:21], v84, s29, v[82:83]
	v_mad_i64_i32 v[220:221], s[20:21], v216, s29, v[82:83]
	ds_bpermute_b32 v196, v214, v66
	ds_bpermute_b32 v197, v214, v67
	ds_bpermute_b32 v198, v214, v68
	ds_bpermute_b32 v199, v214, v69
	ds_bpermute_b32 v200, v214, v70
	ds_bpermute_b32 v201, v214, v71
	ds_bpermute_b32 v202, v214, v72
	ds_bpermute_b32 v204, v214, v73
	s_waitcnt vmcnt(15) lgkmcnt(7)
	v_mul_f32_e32 v196, v165, v196
	s_waitcnt vmcnt(14) lgkmcnt(6)
	v_mul_f32_e32 v197, v167, v197
	s_waitcnt vmcnt(13) lgkmcnt(5)
	v_mul_f32_e32 v198, v169, v198
	s_waitcnt vmcnt(12) lgkmcnt(4)
	v_mul_f32_e32 v199, v171, v199
	s_waitcnt vmcnt(11) lgkmcnt(3)
	v_mul_f32_e32 v200, v173, v200
	s_waitcnt vmcnt(10) lgkmcnt(2)
	v_mul_f32_e32 v201, v175, v201
	s_waitcnt vmcnt(9) lgkmcnt(1)
	v_mul_f32_e32 v202, v177, v202
	s_waitcnt vmcnt(8) lgkmcnt(0)
	v_mul_f32_e32 v204, v179, v204
	v_cndmask_b32_e64 v196, v196, -v196, vcc
	v_cndmask_b32_e64 v197, v197, -v197, vcc
	v_cndmask_b32_e64 v198, v198, -v198, vcc
	v_cndmask_b32_e64 v199, v199, -v199, vcc
	v_cndmask_b32_e64 v200, v200, -v200, vcc
	v_cndmask_b32_e64 v201, v201, -v201, vcc
	v_cndmask_b32_e64 v202, v202, -v202, vcc
	v_cndmask_b32_e64 v204, v204, -v204, vcc
	v_fmac_f32_e32 v196, v66, v164
	v_fmac_f32_e32 v197, v67, v166
	v_fmac_f32_e32 v198, v68, v168
	v_fmac_f32_e32 v199, v69, v170
	v_fmac_f32_e32 v200, v70, v172
	v_fmac_f32_e32 v201, v71, v174
	v_fmac_f32_e32 v202, v72, v176
	v_fmac_f32_e32 v204, v73, v178
	v_fma_mixlo_f16 v196, v196, s30, 0
	v_fma_mixlo_f16 v197, v197, s30, 0
	v_fma_mixlo_f16 v198, v198, s30, 0
	v_fma_mixlo_f16 v199, v199, s30, 0
	v_fma_mixlo_f16 v200, v200, s30, 0
	v_fma_mixlo_f16 v201, v201, s30, 0
	v_fma_mixlo_f16 v202, v202, s30, 0
	v_fma_mixlo_f16 v204, v204, s30, 0
	ds_bpermute_b32 v205, v214, v74
	ds_bpermute_b32 v206, v214, v75
	ds_bpermute_b32 v207, v214, v76
	ds_bpermute_b32 v208, v214, v77
	ds_bpermute_b32 v209, v214, v78
	ds_bpermute_b32 v210, v214, v79
	ds_bpermute_b32 v211, v214, v80
	ds_bpermute_b32 v212, v214, v81
	s_waitcnt vmcnt(7) lgkmcnt(7)
	v_mul_f32_e32 v205, v181, v205
	s_waitcnt vmcnt(6) lgkmcnt(6)
	v_mul_f32_e32 v206, v183, v206
	s_waitcnt vmcnt(5) lgkmcnt(5)
	v_mul_f32_e32 v207, v185, v207
	s_waitcnt vmcnt(4) lgkmcnt(4)
	v_mul_f32_e32 v208, v187, v208
	s_waitcnt vmcnt(3) lgkmcnt(3)
	v_mul_f32_e32 v209, v189, v209
	s_waitcnt vmcnt(2) lgkmcnt(2)
	v_mul_f32_e32 v210, v191, v210
	s_waitcnt vmcnt(1) lgkmcnt(1)
	v_mul_f32_e32 v211, v193, v211
	s_waitcnt vmcnt(0) lgkmcnt(0)
	v_mul_f32_e32 v212, v195, v212
	v_cndmask_b32_e64 v205, v205, -v205, vcc
	v_cndmask_b32_e64 v206, v206, -v206, vcc
	v_cndmask_b32_e64 v207, v207, -v207, vcc
	v_cndmask_b32_e64 v208, v208, -v208, vcc
	v_cndmask_b32_e64 v209, v209, -v209, vcc
	v_cndmask_b32_e64 v210, v210, -v210, vcc
	v_cndmask_b32_e64 v211, v211, -v211, vcc
	v_cndmask_b32_e64 v212, v212, -v212, vcc
	v_fmac_f32_e32 v205, v74, v180
	v_fmac_f32_e32 v206, v75, v182
	v_fmac_f32_e32 v207, v76, v184
	v_fmac_f32_e32 v208, v77, v186
	v_fmac_f32_e32 v209, v78, v188
	v_fmac_f32_e32 v210, v79, v190
	v_fmac_f32_e32 v211, v80, v192
	v_fmac_f32_e32 v212, v81, v194
	v_fma_mixlo_f16 v205, v205, s30, 0
	v_fma_mixlo_f16 v206, v206, s30, 0
	v_fma_mixlo_f16 v207, v207, s30, 0
	v_fma_mixlo_f16 v208, v208, s30, 0
	v_fma_mixlo_f16 v209, v209, s30, 0
	v_fma_mixlo_f16 v210, v210, s30, 0
	v_fma_mixlo_f16 v211, v211, s30, 0
	v_mov_b32_e32 v81, v212
	global_store_short v[218:219], v196, off
	global_store_short v[218:219], v197, off offset:192
	global_store_short v[218:219], v198, off offset:384
	global_store_short v[218:219], v199, off offset:576
	global_store_short v[218:219], v200, off offset:1536
	global_store_short v[218:219], v201, off offset:1728
	global_store_short v[218:219], v202, off offset:1920
	global_store_short v[218:219], v204, off offset:2112
	global_store_short v[218:219], v205, off offset:3072
	global_store_short v[218:219], v206, off offset:3264
	global_store_short v[218:219], v207, off offset:3456
	global_store_short v[218:219], v208, off offset:3648
	global_store_short v[220:221], v209, off
	global_store_short v[220:221], v210, off offset:192
	global_store_short v[220:221], v211, off offset:384

; DI void phase_uproj(const P& p, int l, char* smem, int boff, int geff) {
;     ...
;       epi_foreach_w(acc, m0, n0, [&](int rbase, int n, const f32x16& v) {
;         const int b = rbase < TL ? (rbase >> 12) : ((rbase - TL) >> 8);
;         const int srb = srow_of(rbase);
;         const int head = n / 96, dd = n - head * 96;
;         h16* q = Qm + ((size_t)(b * 7 + head) * SA) * 96 + dd;
;         if (dd < 64 || rbase >= TL) {
; #pragma unroll
;           for (int i = 0; i < 16; ++i) q[(size_t)EROW(srb, i) * 96] = (h16)(v[i] * qscale);
;         } else {
;           const int ii = dd - 64;
; #pragma unroll
;           for (int i = 0; i < 16; ++i) {
;             float x = v[i];
;             float o = shx(x, 16);
;             f32x2 cs = rm[(EROW(rbase, i) & 4095) * 16 + (ii & 15)];
;             float rr = ii < 16 ? (x * cs.x - o * cs.y) : (o * cs.y + x * cs.x);
;             q[(size_t)EROW(srb, i) * 96] = (h16)(rr * qscale);
;           }
;         }
.LBB0_2215:
	s_or_b64 exec, exec, s[0:1]
	v_add_u32_e32 v66, 27, v84
	v_fma_mixlo_f16 v68, v81, s30, 0
	v_mad_i64_i32 v[66:67], s[0:1], v66, s29, v[82:83]
	global_store_short v[66:67], v68, off
	v_or_b32_e32 v68, 64, v136
	v_mov_b32_e32 v71, v68
	s_nop 0
	v_add_u32_e32 v66, 0xffff8000, v71
	v_cmp_gt_i32_e32 vcc, s87, v71
	v_cmp_lt_i32_e64 s[0:1], s33, v71
	v_lshrrev_b32_e32 v66, 8, v66
	s_and_saveexec_b64 s[20:21], s[0:1]
	s_xor_b64 s[0:1], exec, s[20:21]
	v_mul_u32_u24_e32 v67, 0x1100, v66
	s_movk_i32 s2, 0xff
	v_and_or_b32 v67, v71, s2, v67
	v_add_u32_e32 v69, 0x1000, v67
	s_or_saveexec_b64 s[0:1], s[0:1]
	v_ashrrev_i32_e32 v67, 12, v71
	s_xor_b64 exec, exec, s[0:1]
	v_and_b32_e32 v69, 0xfff, v71
	v_mad_i32_i24 v69, v67, s64, v69
	s_or_b64 exec, exec, s[0:1]
	v_cndmask_b32_e32 v66, v66, v67, vcc
	v_mad_u64_u32 v[66:67], s[0:1], v66, 7, v[0:1]
	v_mov_b64_e32 v[72:73], s[42:43]
	s_mov_b32 s0, 0xcc000
	v_mad_i64_i32 v[66:67], s[0:1], v66, s0, v[72:73]
	v_cmp_gt_i32_e32 vcc, s87, v71
	v_lshl_add_u64 v[66:67], v[130:131], 1, v[66:67]
	s_and_b64 s[0:1], s[40:41], vcc
	v_add_u32_e32 v84, 1, v69
	v_add_u32_e32 v83, 2, v69
	v_add_u32_e32 v82, 3, v69
	v_add_u32_e32 v81, 8, v69
	v_add_u32_e32 v80, 9, v69
	v_add_u32_e32 v79, 10, v69
	v_add_u32_e32 v78, 11, v69
	v_add_u32_e32 v77, 16, v69
	v_add_u32_e32 v76, 17, v69
	v_add_u32_e32 v75, 18, v69
	v_add_u32_e32 v74, 19, v69
	v_add_u32_e32 v73, 24, v69
	v_add_u32_e32 v72, 25, v69
	v_add_u32_e32 v70, 26, v69
	s_and_saveexec_b64 s[20:21], s[0:1]
	s_xor_b64 s[0:1], exec, s[20:21]
	s_cbranch_execz .LBB0_2221
	v_lshlrev_b32_e32 v213, 4, v71
	s_mov_b32 s2, 0xfff0
	v_and_or_b32 v213, v213, s2, v133
	v_lshlrev_b32_e32 v213, 3, v213
	global_load_dwordx2 v[164:165], v213, s[44:45]
	global_load_dwordx2 v[166:167], v213, s[44:45] offset:128
	global_load_dwordx2 v[168:169], v213, s[44:45] offset:256
	global_load_dwordx2 v[170:171], v213, s[44:45] offset:384
	global_load_dwordx2 v[172:173], v213, s[44:45] offset:1024
	global_load_dwordx2 v[174:175], v213, s[44:45] offset:1152
	global_load_dwordx2 v[176:177], v213, s[44:45] offset:1280
	global_load_dwordx2 v[178:179], v213, s[44:45] offset:1408
	global_load_dwordx2 v[180:181], v213, s[44:45] offset:2048
	global_load_dwordx2 v[182:183], v213, s[44:45] offset:2176
	global_load_dwordx2 v[184:185], v213, s[44:45] offset:2304
	global_load_dwordx2 v[186:187], v213, s[44:45] offset:2432
	global_load_dwordx2 v[188:189], v213, s[44:45] offset:3072
	global_load_dwordx2 v[190:191], v213, s[44:45] offset:3200
	global_load_dwordx2 v[192:193], v213, s[44:45] offset:3328
	global_load_dwordx2 v[194:195], v213, s[44:45] offset:3456
	v_lshlrev_b32_e32 v214, 2, v203
	v_bfrev_b32_e32 v215, 0.5
	v_bitop3_b32 v214, v214, 64, v215 bitop3:0x6c
	v_add_u32_e32 v216, 24, v69
	v_cmp_gt_u32_e64 vcc, s76, v130
	v_mad_i64_i32 v[218:219], s[20:21], v69, s29, v[66:67]
	v_mad_i64_i32 v[220:221], s[20:21], v216, s29, v[66:67]
	ds_bpermute_b32 v196, v214, v50
	ds_bpermute_b32 v197, v214, v51
	ds_bpermute_b32 v198, v214, v52
	ds_bpermute_b32 v199, v214, v53
	ds_bpermute_b32 v200, v214, v54
	ds_bpermute_b32 v201, v214, v55
	ds_bpermute_b32 v202, v214, v56
	ds_bpermute_b32 v204, v214, v57
	s_waitcnt vmcnt(15) lgkmcnt(7)
	v_mul_f32_e32 v196, v165, v196
	s_waitcnt vmcnt(14) lgkmcnt(6)
	v_mul_f32_e32 v197, v167, v197
	s_waitcnt vmcnt(13) lgkmcnt(5)
	v_mul_f32_e32 v198, v169, v198
	s_waitcnt vmcnt(12) lgkmcnt(4)
	v_mul_f32_e32 v199, v171, v199
	s_waitcnt vmcnt(11) lgkmcnt(3)
	v_mul_f32_e32 v200, v173, v200
	s_waitcnt vmcnt(10) lgkmcnt(2)
	v_mul_f32_e32 v201, v175, v201
	s_waitcnt vmcnt(9) lgkmcnt(1)
	v_mul_f32_e32 v202, v177, v202
	s_waitcnt vmcnt(8) lgkmcnt(0)
	v_mul_f32_e32 v204, v179, v204
	v_cndmask_b32_e64 v196, v196, -v196, vcc
	v_cndmask_b32_e64 v197, v197, -v197, vcc
	v_cndmask_b32_e64 v198, v198, -v198, vcc
	v_cndmask_b32_e64 v199, v199, -v199, vcc
	v_cndmask_b32_e64 v200, v200, -v200, vcc
	v_cndmask_b32_e64 v201, v201, -v201, vcc
	v_cndmask_b32_e64 v202, v202, -v202, vcc
	v_cndmask_b32_e64 v204, v204, -v204, vcc
	v_fmac_f32_e32 v196, v50, v164
	v_fmac_f32_e32 v197, v51, v166
	v_fmac_f32_e32 v198, v52, v168
	v_fmac_f32_e32 v199, v53, v170
	v_fmac_f32_e32 v200, v54, v172
	v_fmac_f32_e32 v201, v55, v174
	v_fmac_f32_e32 v202, v56, v176
	v_fmac_f32_e32 v204, v57, v178
	v_fma_mixlo_f16 v196, v196, s30, 0
	v_fma_mixlo_f16 v197, v197, s30, 0
	v_fma_mixlo_f16 v198, v198, s30, 0
	v_fma_mixlo_f16 v199, v199, s30, 0
	v_fma_mixlo_f16 v200, v200, s30, 0
	v_fma_mixlo_f16 v201, v201, s30, 0
	v_fma_mixlo_f16 v202, v202, s30, 0
	v_fma_mixlo_f16 v204, v204, s30, 0
	ds_bpermute_b32 v205, v214, v58
	ds_bpermute_b32 v206, v214, v59
	ds_bpermute_b32 v207, v214, v60
	ds_bpermute_b32 v208, v214, v61
	ds_bpermute_b32 v209, v214, v62
	ds_bpermute_b32 v210, v214, v63
	ds_bpermute_b32 v211, v214, v64
	ds_bpermute_b32 v212, v214, v65
	s_waitcnt vmcnt(7) lgkmcnt(7)
	v_mul_f32_e32 v205, v181, v205
	s_waitcnt vmcnt(6) lgkmcnt(6)
	v_mul_f32_e32 v206, v183, v206
	s_waitcnt vmcnt(5) lgkmcnt(5)
	v_mul_f32_e32 v207, v185, v207
	s_waitcnt vmcnt(4) lgkmcnt(4)
	v_mul_f32_e32 v208, v187, v208
	s_waitcnt vmcnt(3) lgkmcnt(3)
	v_mul_f32_e32 v209, v189, v209
	s_waitcnt vmcnt(2) lgkmcnt(2)
	v_mul_f32_e32 v210, v191, v210
	s_waitcnt vmcnt(1) lgkmcnt(1)
	v_mul_f32_e32 v211, v193, v211
	s_waitcnt vmcnt(0) lgkmcnt(0)
	v_mul_f32_e32 v212, v195, v212
	v_cndmask_b32_e64 v205, v205, -v205, vcc
	v_cndmask_b32_e64 v206, v206, -v206, vcc
	v_cndmask_b32_e64 v207, v207, -v207, vcc
	v_cndmask_b32_e64 v208, v208, -v208, vcc
	v_cndmask_b32_e64 v209, v209, -v209, vcc
	v_cndmask_b32_e64 v210, v210, -v210, vcc
	v_cndmask_b32_e64 v211, v211, -v211, vcc
	v_cndmask_b32_e64 v212, v212, -v212, vcc
	v_fmac_f32_e32 v205, v58, v180
	v_fmac_f32_e32 v206, v59, v182
	v_fmac_f32_e32 v207, v60, v184
	v_fmac_f32_e32 v208, v61, v186
	v_fmac_f32_e32 v209, v62, v188
	v_fmac_f32_e32 v210, v63, v190
	v_fmac_f32_e32 v211, v64, v192
	v_fmac_f32_e32 v212, v65, v194
	v_fma_mixlo_f16 v205, v205, s30, 0
	v_fma_mixlo_f16 v206, v206, s30, 0
	v_fma_mixlo_f16 v207, v207, s30, 0
	v_fma_mixlo_f16 v208, v208, s30, 0
	v_fma_mixlo_f16 v209, v209, s30, 0
	v_fma_mixlo_f16 v210, v210, s30, 0
	v_fma_mixlo_f16 v211, v211, s30, 0
	v_mov_b32_e32 v65, v212
	global_store_short v[218:219], v196, off
	global_store_short v[218:219], v197, off offset:192
	global_store_short v[218:219], v198, off offset:384
	global_store_short v[218:219], v199, off offset:576
	global_store_short v[218:219], v200, off offset:1536
	global_store_short v[218:219], v201, off offset:1728
	global_store_short v[218:219], v202, off offset:1920
	global_store_short v[218:219], v204, off offset:2112
	global_store_short v[218:219], v205, off offset:3072
	global_store_short v[218:219], v206, off offset:3264
	global_store_short v[218:219], v207, off offset:3456
	global_store_short v[218:219], v208, off offset:3648
	global_store_short v[220:221], v209, off
	global_store_short v[220:221], v210, off offset:192
	global_store_short v[220:221], v211, off offset:384

; DI void phase_uproj(const P& p, int l, char* smem, int boff, int geff) {
;     ...
;         const int b = rbase < TL ? (rbase >> 12) : ((rbase - TL) >> 8);
;         const int srb = srow_of(rbase);
;         const int head = n / 96, dd = n - head * 96;
;         h16* q = Qm + ((size_t)(b * 7 + head) * SA) * 96 + dd;
;         if (dd < 64 || rbase >= TL) {
; #pragma unroll
;           for (int i = 0; i < 16; ++i) q[(size_t)EROW(srb, i) * 96] = (h16)(v[i] * qscale);
;         } else {
;           const int ii = dd - 64;
; #pragma unroll
;           for (int i = 0; i < 16; ++i) {
;             float x = v[i];
;             float o = shx(x, 16);
;             f32x2 cs = rm[(EROW(rbase, i) & 4095) * 16 + (ii & 15)];
;             float rr = ii < 16 ? (x * cs.x - o * cs.y) : (o * cs.y + x * cs.x);
;             q[(size_t)EROW(srb, i) * 96] = (h16)(rr * qscale);
;           }
.LBB0_2223:
	s_or_b64 exec, exec, s[0:1]
	v_add_u32_e32 v50, 27, v69
	v_fma_mixlo_f16 v52, v65, s30, 0
	v_mad_i64_i32 v[50:51], s[0:1], v50, s29, v[66:67]
	global_store_short v[50:51], v52, off
	s_nop 0
	v_add_u32_e32 v50, 0xffff8000, v68
	v_cmp_gt_i32_e32 vcc, s87, v68
	v_cmp_lt_i32_e64 s[0:1], s33, v68
	v_lshrrev_b32_e32 v50, 8, v50
	s_and_saveexec_b64 s[20:21], s[0:1]
	s_xor_b64 s[0:1], exec, s[20:21]
	v_mul_u32_u24_e32 v51, 0x1100, v50
	s_movk_i32 s2, 0xff
	v_and_or_b32 v51, v68, s2, v51
	v_add_u32_e32 v52, 0x1000, v51
	s_or_saveexec_b64 s[0:1], s[0:1]
	v_ashrrev_i32_e32 v51, 12, v68
	s_xor_b64 exec, exec, s[0:1]
	v_and_b32_e32 v52, 0xfff, v68
	v_mad_i32_i24 v52, v51, s64, v52
	s_or_b64 exec, exec, s[0:1]
	v_cndmask_b32_e32 v50, v50, v51, vcc
	v_mad_u64_u32 v[50:51], s[0:1], v50, 7, v[116:117]
	v_mov_b64_e32 v[54:55], s[42:43]
	s_mov_b32 s0, 0xcc000
	v_mad_i64_i32 v[50:51], s[0:1], v50, s0, v[54:55]
	v_cmp_gt_i32_e32 vcc, s87, v68
	v_lshl_add_u64 v[50:51], v[114:115], 1, v[50:51]
	s_and_b64 s[0:1], s[38:39], vcc
	v_add_u32_e32 v67, 1, v52
	v_add_u32_e32 v66, 2, v52
	v_add_u32_e32 v65, 3, v52
	v_add_u32_e32 v64, 8, v52
	v_add_u32_e32 v63, 9, v52
	v_add_u32_e32 v62, 10, v52
	v_add_u32_e32 v61, 11, v52
	v_add_u32_e32 v60, 16, v52
	v_add_u32_e32 v59, 17, v52
	v_add_u32_e32 v58, 18, v52
	v_add_u32_e32 v57, 19, v52
	v_add_u32_e32 v56, 24, v52
	v_add_u32_e32 v55, 25, v52
	v_add_u32_e32 v53, 26, v52
	s_and_saveexec_b64 s[20:21], s[0:1]
	s_xor_b64 s[0:1], exec, s[20:21]
	s_cbranch_execz .LBB0_2229
	v_lshlrev_b32_e32 v213, 4, v68
	s_mov_b32 s2, 0xfff0
	v_and_or_b32 v213, v213, s2, v133
	v_lshlrev_b32_e32 v213, 3, v213
	global_load_dwordx2 v[164:165], v213, s[44:45]
	global_load_dwordx2 v[166:167], v213, s[44:45] offset:128
	global_load_dwordx2 v[168:169], v213, s[44:45] offset:256
	global_load_dwordx2 v[170:171], v213, s[44:45] offset:384
	global_load_dwordx2 v[172:173], v213, s[44:45] offset:1024
	global_load_dwordx2 v[174:175], v213, s[44:45] offset:1152
	global_load_dwordx2 v[176:177], v213, s[44:45] offset:1280
	global_load_dwordx2 v[178:179], v213, s[44:45] offset:1408
	global_load_dwordx2 v[180:181], v213, s[44:45] offset:2048
	global_load_dwordx2 v[182:183], v213, s[44:45] offset:2176
	global_load_dwordx2 v[184:185], v213, s[44:45] offset:2304
	global_load_dwordx2 v[186:187], v213, s[44:45] offset:2432
	global_load_dwordx2 v[188:189], v213, s[44:45] offset:3072
	global_load_dwordx2 v[190:191], v213, s[44:45] offset:3200
	global_load_dwordx2 v[192:193], v213, s[44:45] offset:3328
	global_load_dwordx2 v[194:195], v213, s[44:45] offset:3456
	v_lshlrev_b32_e32 v214, 2, v203
	v_bfrev_b32_e32 v215, 0.5
	v_bitop3_b32 v214, v214, 64, v215 bitop3:0x6c
	v_add_u32_e32 v216, 24, v52
	v_cmp_gt_u32_e64 vcc, s76, v114
	v_mad_i64_i32 v[218:219], s[20:21], v52, s29, v[50:51]
	v_mad_i64_i32 v[220:221], s[20:21], v216, s29, v[50:51]
	ds_bpermute_b32 v196, v214, v34
	ds_bpermute_b32 v197, v214, v35
	ds_bpermute_b32 v198, v214, v36
	ds_bpermute_b32 v199, v214, v37
	ds_bpermute_b32 v200, v214, v38
	ds_bpermute_b32 v201, v214, v39
	ds_bpermute_b32 v202, v214, v40
	ds_bpermute_b32 v204, v214, v41
	s_waitcnt vmcnt(15) lgkmcnt(7)
	v_mul_f32_e32 v196, v165, v196
	s_waitcnt vmcnt(14) lgkmcnt(6)
	v_mul_f32_e32 v197, v167, v197
	s_waitcnt vmcnt(13) lgkmcnt(5)
	v_mul_f32_e32 v198, v169, v198
	s_waitcnt vmcnt(12) lgkmcnt(4)
	v_mul_f32_e32 v199, v171, v199
	s_waitcnt vmcnt(11) lgkmcnt(3)
	v_mul_f32_e32 v200, v173, v200
	s_waitcnt vmcnt(10) lgkmcnt(2)
	v_mul_f32_e32 v201, v175, v201
	s_waitcnt vmcnt(9) lgkmcnt(1)
	v_mul_f32_e32 v202, v177, v202
	s_waitcnt vmcnt(8) lgkmcnt(0)
	v_mul_f32_e32 v204, v179, v204
	v_cndmask_b32_e64 v196, v196, -v196, vcc
	v_cndmask_b32_e64 v197, v197, -v197, vcc
	v_cndmask_b32_e64 v198, v198, -v198, vcc
	v_cndmask_b32_e64 v199, v199, -v199, vcc
	v_cndmask_b32_e64 v200, v200, -v200, vcc
	v_cndmask_b32_e64 v201, v201, -v201, vcc
	v_cndmask_b32_e64 v202, v202, -v202, vcc
	v_cndmask_b32_e64 v204, v204, -v204, vcc
	v_fmac_f32_e32 v196, v34, v164
	v_fmac_f32_e32 v197, v35, v166
	v_fmac_f32_e32 v198, v36, v168
	v_fmac_f32_e32 v199, v37, v170
	v_fmac_f32_e32 v200, v38, v172
	v_fmac_f32_e32 v201, v39, v174
	v_fmac_f32_e32 v202, v40, v176
	v_fmac_f32_e32 v204, v41, v178
	v_fma_mixlo_f16 v196, v196, s30, 0
	v_fma_mixlo_f16 v197, v197, s30, 0
	v_fma_mixlo_f16 v198, v198, s30, 0
	v_fma_mixlo_f16 v199, v199, s30, 0
	v_fma_mixlo_f16 v200, v200, s30, 0
	v_fma_mixlo_f16 v201, v201, s30, 0
	v_fma_mixlo_f16 v202, v202, s30, 0
	v_fma_mixlo_f16 v204, v204, s30, 0
	ds_bpermute_b32 v205, v214, v42
	ds_bpermute_b32 v206, v214, v43
	ds_bpermute_b32 v207, v214, v44
	ds_bpermute_b32 v208, v214, v45
	ds_bpermute_b32 v209, v214, v46
	ds_bpermute_b32 v210, v214, v47
	ds_bpermute_b32 v211, v214, v48
	ds_bpermute_b32 v212, v214, v49
	s_waitcnt vmcnt(7) lgkmcnt(7)
	v_mul_f32_e32 v205, v181, v205
	s_waitcnt vmcnt(6) lgkmcnt(6)
	v_mul_f32_e32 v206, v183, v206
	s_waitcnt vmcnt(5) lgkmcnt(5)
	v_mul_f32_e32 v207, v185, v207
	s_waitcnt vmcnt(4) lgkmcnt(4)
	v_mul_f32_e32 v208, v187, v208
	s_waitcnt vmcnt(3) lgkmcnt(3)
	v_mul_f32_e32 v209, v189, v209
	s_waitcnt vmcnt(2) lgkmcnt(2)
	v_mul_f32_e32 v210, v191, v210
	s_waitcnt vmcnt(1) lgkmcnt(1)
	v_mul_f32_e32 v211, v193, v211
	s_waitcnt vmcnt(0) lgkmcnt(0)
	v_mul_f32_e32 v212, v195, v212
	v_cndmask_b32_e64 v205, v205, -v205, vcc
	v_cndmask_b32_e64 v206, v206, -v206, vcc
	v_cndmask_b32_e64 v207, v207, -v207, vcc
	v_cndmask_b32_e64 v208, v208, -v208, vcc
	v_cndmask_b32_e64 v209, v209, -v209, vcc
	v_cndmask_b32_e64 v210, v210, -v210, vcc
	v_cndmask_b32_e64 v211, v211, -v211, vcc
	v_cndmask_b32_e64 v212, v212, -v212, vcc
	v_fmac_f32_e32 v205, v42, v180
	v_fmac_f32_e32 v206, v43, v182
	v_fmac_f32_e32 v207, v44, v184
	v_fmac_f32_e32 v208, v45, v186
	v_fmac_f32_e32 v209, v46, v188
	v_fmac_f32_e32 v210, v47, v190
	v_fmac_f32_e32 v211, v48, v192
	v_fmac_f32_e32 v212, v49, v194
	v_fma_mixlo_f16 v205, v205, s30, 0
	v_fma_mixlo_f16 v206, v206, s30, 0
	v_fma_mixlo_f16 v207, v207, s30, 0
	v_fma_mixlo_f16 v208, v208, s30, 0
	v_fma_mixlo_f16 v209, v209, s30, 0
	v_fma_mixlo_f16 v210, v210, s30, 0
	v_fma_mixlo_f16 v211, v211, s30, 0
	v_mov_b32_e32 v49, v212
	global_store_short v[218:219], v196, off
	global_store_short v[218:219], v197, off offset:192
	global_store_short v[218:219], v198, off offset:384
	global_store_short v[218:219], v199, off offset:576
	global_store_short v[218:219], v200, off offset:1536
	global_store_short v[218:219], v201, off offset:1728
	global_store_short v[218:219], v202, off offset:1920
	global_store_short v[218:219], v204, off offset:2112
	global_store_short v[218:219], v205, off offset:3072
	global_store_short v[218:219], v206, off offset:3264
	global_store_short v[218:219], v207, off offset:3456
	global_store_short v[218:219], v208, off offset:3648
	global_store_short v[220:221], v209, off
	global_store_short v[220:221], v210, off offset:192
	global_store_short v[220:221], v211, off offset:384

; DI void phase_uproj(const P& p, int l, char* smem, int boff, int geff) {
;     ...
;         const int b = rbase < TL ? (rbase >> 12) : ((rbase - TL) >> 8);
;         const int srb = srow_of(rbase);
;         const int head = n / 96, dd = n - head * 96;
;         h16* q = Qm + ((size_t)(b * 7 + head) * SA) * 96 + dd;
;         if (dd < 64 || rbase >= TL) {
; #pragma unroll
;           for (int i = 0; i < 16; ++i) q[(size_t)EROW(srb, i) * 96] = (h16)(v[i] * qscale);
;         } else {
;           const int ii = dd - 64;
; #pragma unroll
;           for (int i = 0; i < 16; ++i) {
;             float x = v[i];
;             float o = shx(x, 16);
;             f32x2 cs = rm[(EROW(rbase, i) & 4095) * 16 + (ii & 15)];
;             float rr = ii < 16 ? (x * cs.x - o * cs.y) : (o * cs.y + x * cs.x);
;             q[(size_t)EROW(srb, i) * 96] = (h16)(rr * qscale);
;           }
.LBB0_2231:
	s_or_b64 exec, exec, s[0:1]
	v_add_u32_e32 v34, 27, v52
	v_fma_mixlo_f16 v36, v49, s30, 0
	v_mad_i64_i32 v[34:35], s[0:1], v34, s29, v[50:51]
	global_store_short v[34:35], v36, off
	v_or_b32_e32 v36, 0x60, v136
	v_mov_b32_e32 v38, v36
	s_nop 0
	v_add_u32_e32 v34, 0xffff8000, v38
	v_cmp_gt_i32_e32 vcc, s87, v38
	v_cmp_lt_i32_e64 s[0:1], s33, v38
	v_lshrrev_b32_e32 v34, 8, v34
	s_and_saveexec_b64 s[20:21], s[0:1]
	s_xor_b64 s[0:1], exec, s[20:21]
	v_mul_u32_u24_e32 v35, 0x1100, v34
	s_movk_i32 s2, 0xff
	v_and_or_b32 v35, v38, s2, v35
	v_add_u32_e32 v37, 0x1000, v35
	s_or_saveexec_b64 s[0:1], s[0:1]
	v_ashrrev_i32_e32 v35, 12, v38
	s_xor_b64 exec, exec, s[0:1]
	v_and_b32_e32 v37, 0xfff, v38
	v_mad_i32_i24 v37, v35, s64, v37
	s_or_b64 exec, exec, s[0:1]
	v_cndmask_b32_e32 v34, v34, v35, vcc
	v_mad_u64_u32 v[34:35], s[0:1], v34, 7, v[0:1]
	v_mov_b64_e32 v[40:41], s[42:43]
	s_mov_b32 s0, 0xcc000
	v_mad_i64_i32 v[34:35], s[0:1], v34, s0, v[40:41]
	v_cmp_gt_i32_e32 vcc, s87, v38
	v_lshl_add_u64 v[34:35], v[130:131], 1, v[34:35]
	s_and_b64 s[0:1], s[40:41], vcc
	v_add_u32_e32 v51, 1, v37
	v_add_u32_e32 v50, 2, v37
	v_add_u32_e32 v49, 3, v37
	v_add_u32_e32 v48, 8, v37
	v_add_u32_e32 v47, 9, v37
	v_add_u32_e32 v46, 10, v37
	v_add_u32_e32 v45, 11, v37
	v_add_u32_e32 v44, 16, v37
	v_add_u32_e32 v43, 17, v37
	v_add_u32_e32 v42, 18, v37
	v_add_u32_e32 v41, 19, v37
	v_add_u32_e32 v40, 24, v37
	v_add_u32_e32 v39, 25, v37
	v_add_u32_e32 v0, 26, v37
	s_and_saveexec_b64 s[20:21], s[0:1]
	s_xor_b64 s[0:1], exec, s[20:21]
	s_cbranch_execz .LBB0_2237
	v_lshlrev_b32_e32 v213, 4, v38
	s_mov_b32 s2, 0xfff0
	v_and_or_b32 v213, v213, s2, v133
	v_lshlrev_b32_e32 v213, 3, v213
	global_load_dwordx2 v[164:165], v213, s[44:45]
	global_load_dwordx2 v[166:167], v213, s[44:45] offset:128
	global_load_dwordx2 v[168:169], v213, s[44:45] offset:256
	global_load_dwordx2 v[170:171], v213, s[44:45] offset:384
	global_load_dwordx2 v[172:173], v213, s[44:45] offset:1024
	global_load_dwordx2 v[174:175], v213, s[44:45] offset:1152
	global_load_dwordx2 v[176:177], v213, s[44:45] offset:1280
	global_load_dwordx2 v[178:179], v213, s[44:45] offset:1408
	global_load_dwordx2 v[180:181], v213, s[44:45] offset:2048
	global_load_dwordx2 v[182:183], v213, s[44:45] offset:2176
	global_load_dwordx2 v[184:185], v213, s[44:45] offset:2304
	global_load_dwordx2 v[186:187], v213, s[44:45] offset:2432
	global_load_dwordx2 v[188:189], v213, s[44:45] offset:3072
	global_load_dwordx2 v[190:191], v213, s[44:45] offset:3200
	global_load_dwordx2 v[192:193], v213, s[44:45] offset:3328
	global_load_dwordx2 v[194:195], v213, s[44:45] offset:3456
	v_lshlrev_b32_e32 v214, 2, v203
	v_bfrev_b32_e32 v215, 0.5
	v_bitop3_b32 v214, v214, 64, v215 bitop3:0x6c
	v_add_u32_e32 v216, 24, v37
	v_cmp_gt_u32_e64 vcc, s76, v130
	v_mad_i64_i32 v[218:219], s[20:21], v37, s29, v[34:35]
	v_mad_i64_i32 v[220:221], s[20:21], v216, s29, v[34:35]
	ds_bpermute_b32 v196, v214, v18
	ds_bpermute_b32 v197, v214, v19
	ds_bpermute_b32 v198, v214, v20
	ds_bpermute_b32 v199, v214, v21
	ds_bpermute_b32 v200, v214, v22
	ds_bpermute_b32 v201, v214, v23
	ds_bpermute_b32 v202, v214, v24
	ds_bpermute_b32 v204, v214, v25
	s_waitcnt vmcnt(15) lgkmcnt(7)
	v_mul_f32_e32 v196, v165, v196
	s_waitcnt vmcnt(14) lgkmcnt(6)
	v_mul_f32_e32 v197, v167, v197
	s_waitcnt vmcnt(13) lgkmcnt(5)
	v_mul_f32_e32 v198, v169, v198
	s_waitcnt vmcnt(12) lgkmcnt(4)
	v_mul_f32_e32 v199, v171, v199
	s_waitcnt vmcnt(11) lgkmcnt(3)
	v_mul_f32_e32 v200, v173, v200
	s_waitcnt vmcnt(10) lgkmcnt(2)
	v_mul_f32_e32 v201, v175, v201
	s_waitcnt vmcnt(9) lgkmcnt(1)
	v_mul_f32_e32 v202, v177, v202
	s_waitcnt vmcnt(8) lgkmcnt(0)
	v_mul_f32_e32 v204, v179, v204
	v_cndmask_b32_e64 v196, v196, -v196, vcc
	v_cndmask_b32_e64 v197, v197, -v197, vcc
	v_cndmask_b32_e64 v198, v198, -v198, vcc
	v_cndmask_b32_e64 v199, v199, -v199, vcc
	v_cndmask_b32_e64 v200, v200, -v200, vcc
	v_cndmask_b32_e64 v201, v201, -v201, vcc
	v_cndmask_b32_e64 v202, v202, -v202, vcc
	v_cndmask_b32_e64 v204, v204, -v204, vcc
	v_fmac_f32_e32 v196, v18, v164
	v_fmac_f32_e32 v197, v19, v166
	v_fmac_f32_e32 v198, v20, v168
	v_fmac_f32_e32 v199, v21, v170
	v_fmac_f32_e32 v200, v22, v172
	v_fmac_f32_e32 v201, v23, v174
	v_fmac_f32_e32 v202, v24, v176
	v_fmac_f32_e32 v204, v25, v178
	v_fma_mixlo_f16 v196, v196, s30, 0
	v_fma_mixlo_f16 v197, v197, s30, 0
	v_fma_mixlo_f16 v198, v198, s30, 0
	v_fma_mixlo_f16 v199, v199, s30, 0
	v_fma_mixlo_f16 v200, v200, s30, 0
	v_fma_mixlo_f16 v201, v201, s30, 0
	v_fma_mixlo_f16 v202, v202, s30, 0
	v_fma_mixlo_f16 v204, v204, s30, 0
	ds_bpermute_b32 v205, v214, v26
	ds_bpermute_b32 v206, v214, v27
	ds_bpermute_b32 v207, v214, v28
	ds_bpermute_b32 v208, v214, v29
	ds_bpermute_b32 v209, v214, v30
	ds_bpermute_b32 v210, v214, v31
	ds_bpermute_b32 v211, v214, v32
	ds_bpermute_b32 v212, v214, v33
	s_waitcnt vmcnt(7) lgkmcnt(7)
	v_mul_f32_e32 v205, v181, v205
	s_waitcnt vmcnt(6) lgkmcnt(6)
	v_mul_f32_e32 v206, v183, v206
	s_waitcnt vmcnt(5) lgkmcnt(5)
	v_mul_f32_e32 v207, v185, v207
	s_waitcnt vmcnt(4) lgkmcnt(4)
	v_mul_f32_e32 v208, v187, v208
	s_waitcnt vmcnt(3) lgkmcnt(3)
	v_mul_f32_e32 v209, v189, v209
	s_waitcnt vmcnt(2) lgkmcnt(2)
	v_mul_f32_e32 v210, v191, v210
	s_waitcnt vmcnt(1) lgkmcnt(1)
	v_mul_f32_e32 v211, v193, v211
	s_waitcnt vmcnt(0) lgkmcnt(0)
	v_mul_f32_e32 v212, v195, v212
	v_cndmask_b32_e64 v205, v205, -v205, vcc
	v_cndmask_b32_e64 v206, v206, -v206, vcc
	v_cndmask_b32_e64 v207, v207, -v207, vcc
	v_cndmask_b32_e64 v208, v208, -v208, vcc
	v_cndmask_b32_e64 v209, v209, -v209, vcc
	v_cndmask_b32_e64 v210, v210, -v210, vcc
	v_cndmask_b32_e64 v211, v211, -v211, vcc
	v_cndmask_b32_e64 v212, v212, -v212, vcc
	v_fmac_f32_e32 v205, v26, v180
	v_fmac_f32_e32 v206, v27, v182
	v_fmac_f32_e32 v207, v28, v184
	v_fmac_f32_e32 v208, v29, v186
	v_fmac_f32_e32 v209, v30, v188
	v_fmac_f32_e32 v210, v31, v190
	v_fmac_f32_e32 v211, v32, v192
	v_fmac_f32_e32 v212, v33, v194
	v_fma_mixlo_f16 v205, v205, s30, 0
	v_fma_mixlo_f16 v206, v206, s30, 0
	v_fma_mixlo_f16 v207, v207, s30, 0
	v_fma_mixlo_f16 v208, v208, s30, 0
	v_fma_mixlo_f16 v209, v209, s30, 0
	v_fma_mixlo_f16 v210, v210, s30, 0
	v_fma_mixlo_f16 v211, v211, s30, 0
	v_mov_b32_e32 v33, v212
	global_store_short v[218:219], v196, off
	global_store_short v[218:219], v197, off offset:192
	global_store_short v[218:219], v198, off offset:384
	global_store_short v[218:219], v199, off offset:576
	global_store_short v[218:219], v200, off offset:1536
	global_store_short v[218:219], v201, off offset:1728
	global_store_short v[218:219], v202, off offset:1920
	global_store_short v[218:219], v204, off offset:2112
	global_store_short v[218:219], v205, off offset:3072
	global_store_short v[218:219], v206, off offset:3264
	global_store_short v[218:219], v207, off offset:3456
	global_store_short v[218:219], v208, off offset:3648
	global_store_short v[220:221], v209, off
	global_store_short v[220:221], v210, off offset:192
	global_store_short v[220:221], v211, off offset:384

; DI void phase_uproj(const P& p, int l, char* smem, int boff, int geff) {
;     ...
;         const int b = rbase < TL ? (rbase >> 12) : ((rbase - TL) >> 8);
;         const int srb = srow_of(rbase);
;         const int head = n / 96, dd = n - head * 96;
;         h16* q = Qm + ((size_t)(b * 7 + head) * SA) * 96 + dd;
;         if (dd < 64 || rbase >= TL) {
; #pragma unroll
;           for (int i = 0; i < 16; ++i) q[(size_t)EROW(srb, i) * 96] = (h16)(v[i] * qscale);
;         } else {
;           const int ii = dd - 64;
; #pragma unroll
;           for (int i = 0; i < 16; ++i) {
;             float x = v[i];
;             float o = shx(x, 16);
;             f32x2 cs = rm[(EROW(rbase, i) & 4095) * 16 + (ii & 15)];
;             float rr = ii < 16 ? (x * cs.x - o * cs.y) : (o * cs.y + x * cs.x);
;             q[(size_t)EROW(srb, i) * 96] = (h16)(rr * qscale);
;           }
.LBB0_2239:
	s_or_b64 exec, exec, s[0:1]
	v_add_u32_e32 v18, 27, v37
	v_fma_mixlo_f16 v0, v33, s30, 0
	v_mad_i64_i32 v[18:19], s[0:1], v18, s29, v[34:35]
	global_store_short v[18:19], v0, off
	s_nop 0
	v_add_u32_e32 v0, 0xffff8000, v36
	v_cmp_gt_i32_e32 vcc, s87, v36
	v_cmp_lt_i32_e64 s[0:1], s33, v36
	v_lshrrev_b32_e32 v18, 8, v0
	s_and_saveexec_b64 s[20:21], s[0:1]
	s_xor_b64 s[0:1], exec, s[20:21]
	v_mul_u32_u24_e32 v0, 0x1100, v18
	s_movk_i32 s2, 0xff
	v_and_or_b32 v0, v36, s2, v0
	v_add_u32_e32 v0, 0x1000, v0
	s_or_saveexec_b64 s[0:1], s[0:1]
	v_ashrrev_i32_e32 v19, 12, v36
	s_xor_b64 exec, exec, s[0:1]
	v_and_b32_e32 v0, 0xfff, v36
	v_mad_i32_i24 v0, v19, s64, v0
	s_or_b64 exec, exec, s[0:1]
	v_cndmask_b32_e32 v18, v18, v19, vcc
	v_mad_u64_u32 v[18:19], s[0:1], v18, 7, v[116:117]
	v_mov_b64_e32 v[20:21], s[42:43]
	s_mov_b32 s0, 0xcc000
	v_mad_i64_i32 v[18:19], s[0:1], v18, s0, v[20:21]
	v_cmp_gt_i32_e32 vcc, s87, v36
	v_lshl_add_u64 v[18:19], v[114:115], 1, v[18:19]
	s_and_b64 s[0:1], s[38:39], vcc
	v_add_u32_e32 v34, 1, v0
	v_add_u32_e32 v33, 2, v0
	v_add_u32_e32 v32, 3, v0
	v_add_u32_e32 v31, 8, v0
	v_add_u32_e32 v30, 9, v0
	v_add_u32_e32 v29, 10, v0
	v_add_u32_e32 v28, 11, v0
	v_add_u32_e32 v27, 16, v0
	v_add_u32_e32 v26, 17, v0
	v_add_u32_e32 v25, 18, v0
	v_add_u32_e32 v24, 19, v0
	v_add_u32_e32 v23, 24, v0
	v_add_u32_e32 v22, 25, v0
	v_add_u32_e32 v20, 26, v0
	s_and_saveexec_b64 s[20:21], s[0:1]
	s_xor_b64 s[0:1], exec, s[20:21]
	s_cbranch_execz .LBB0_2245
	v_lshlrev_b32_e32 v213, 4, v36
	s_mov_b32 s2, 0xfff0
	v_and_or_b32 v213, v213, s2, v133
	v_lshlrev_b32_e32 v213, 3, v213
	global_load_dwordx2 v[164:165], v213, s[44:45]
	global_load_dwordx2 v[166:167], v213, s[44:45] offset:128
	global_load_dwordx2 v[168:169], v213, s[44:45] offset:256
	global_load_dwordx2 v[170:171], v213, s[44:45] offset:384
	global_load_dwordx2 v[172:173], v213, s[44:45] offset:1024
	global_load_dwordx2 v[174:175], v213, s[44:45] offset:1152
	global_load_dwordx2 v[176:177], v213, s[44:45] offset:1280
	global_load_dwordx2 v[178:179], v213, s[44:45] offset:1408
	global_load_dwordx2 v[180:181], v213, s[44:45] offset:2048
	global_load_dwordx2 v[182:183], v213, s[44:45] offset:2176
	global_load_dwordx2 v[184:185], v213, s[44:45] offset:2304
	global_load_dwordx2 v[186:187], v213, s[44:45] offset:2432
	global_load_dwordx2 v[188:189], v213, s[44:45] offset:3072
	global_load_dwordx2 v[190:191], v213, s[44:45] offset:3200
	global_load_dwordx2 v[192:193], v213, s[44:45] offset:3328
	global_load_dwordx2 v[194:195], v213, s[44:45] offset:3456
	v_lshlrev_b32_e32 v214, 2, v203
	v_bfrev_b32_e32 v215, 0.5
	v_bitop3_b32 v214, v214, 64, v215 bitop3:0x6c
	v_add_u32_e32 v216, 24, v0
	v_cmp_gt_u32_e64 vcc, s76, v114
	v_mad_i64_i32 v[218:219], s[20:21], v0, s29, v[18:19]
	v_mad_i64_i32 v[220:221], s[20:21], v216, s29, v[18:19]
	ds_bpermute_b32 v196, v214, v2
	ds_bpermute_b32 v197, v214, v3
	ds_bpermute_b32 v198, v214, v4
	ds_bpermute_b32 v199, v214, v5
	ds_bpermute_b32 v200, v214, v6
	ds_bpermute_b32 v201, v214, v7
	ds_bpermute_b32 v202, v214, v8
	ds_bpermute_b32 v204, v214, v9
	s_waitcnt vmcnt(15) lgkmcnt(7)
	v_mul_f32_e32 v196, v165, v196
	s_waitcnt vmcnt(14) lgkmcnt(6)
	v_mul_f32_e32 v197, v167, v197
	s_waitcnt vmcnt(13) lgkmcnt(5)
	v_mul_f32_e32 v198, v169, v198
	s_waitcnt vmcnt(12) lgkmcnt(4)
	v_mul_f32_e32 v199, v171, v199
	s_waitcnt vmcnt(11) lgkmcnt(3)
	v_mul_f32_e32 v200, v173, v200
	s_waitcnt vmcnt(10) lgkmcnt(2)
	v_mul_f32_e32 v201, v175, v201
	s_waitcnt vmcnt(9) lgkmcnt(1)
	v_mul_f32_e32 v202, v177, v202
	s_waitcnt vmcnt(8) lgkmcnt(0)
	v_mul_f32_e32 v204, v179, v204
	v_cndmask_b32_e64 v196, v196, -v196, vcc
	v_cndmask_b32_e64 v197, v197, -v197, vcc
	v_cndmask_b32_e64 v198, v198, -v198, vcc
	v_cndmask_b32_e64 v199, v199, -v199, vcc
	v_cndmask_b32_e64 v200, v200, -v200, vcc
	v_cndmask_b32_e64 v201, v201, -v201, vcc
	v_cndmask_b32_e64 v202, v202, -v202, vcc
	v_cndmask_b32_e64 v204, v204, -v204, vcc
	v_fmac_f32_e32 v196, v2, v164
	v_fmac_f32_e32 v197, v3, v166
	v_fmac_f32_e32 v198, v4, v168
	v_fmac_f32_e32 v199, v5, v170
	v_fmac_f32_e32 v200, v6, v172
	v_fmac_f32_e32 v201, v7, v174
	v_fmac_f32_e32 v202, v8, v176
	v_fmac_f32_e32 v204, v9, v178
	v_fma_mixlo_f16 v196, v196, s30, 0
	v_fma_mixlo_f16 v197, v197, s30, 0
	v_fma_mixlo_f16 v198, v198, s30, 0
	v_fma_mixlo_f16 v199, v199, s30, 0
	v_fma_mixlo_f16 v200, v200, s30, 0
	v_fma_mixlo_f16 v201, v201, s30, 0
	v_fma_mixlo_f16 v202, v202, s30, 0
	v_fma_mixlo_f16 v204, v204, s30, 0
	ds_bpermute_b32 v205, v214, v10
	ds_bpermute_b32 v206, v214, v11
	ds_bpermute_b32 v207, v214, v12
	ds_bpermute_b32 v208, v214, v13
	ds_bpermute_b32 v209, v214, v14
	ds_bpermute_b32 v210, v214, v15
	ds_bpermute_b32 v211, v214, v16
	ds_bpermute_b32 v212, v214, v17
	s_waitcnt vmcnt(7) lgkmcnt(7)
	v_mul_f32_e32 v205, v181, v205
	s_waitcnt vmcnt(6) lgkmcnt(6)
	v_mul_f32_e32 v206, v183, v206
	s_waitcnt vmcnt(5) lgkmcnt(5)
	v_mul_f32_e32 v207, v185, v207
	s_waitcnt vmcnt(4) lgkmcnt(4)
	v_mul_f32_e32 v208, v187, v208
	s_waitcnt vmcnt(3) lgkmcnt(3)
	v_mul_f32_e32 v209, v189, v209
	s_waitcnt vmcnt(2) lgkmcnt(2)
	v_mul_f32_e32 v210, v191, v210
	s_waitcnt vmcnt(1) lgkmcnt(1)
	v_mul_f32_e32 v211, v193, v211
	s_waitcnt vmcnt(0) lgkmcnt(0)
	v_mul_f32_e32 v212, v195, v212
	v_cndmask_b32_e64 v205, v205, -v205, vcc
	v_cndmask_b32_e64 v206, v206, -v206, vcc
	v_cndmask_b32_e64 v207, v207, -v207, vcc
	v_cndmask_b32_e64 v208, v208, -v208, vcc
	v_cndmask_b32_e64 v209, v209, -v209, vcc
	v_cndmask_b32_e64 v210, v210, -v210, vcc
	v_cndmask_b32_e64 v211, v211, -v211, vcc
	v_cndmask_b32_e64 v212, v212, -v212, vcc
	v_fmac_f32_e32 v205, v10, v180
	v_fmac_f32_e32 v206, v11, v182
	v_fmac_f32_e32 v207, v12, v184
	v_fmac_f32_e32 v208, v13, v186
	v_fmac_f32_e32 v209, v14, v188
	v_fmac_f32_e32 v210, v15, v190
	v_fmac_f32_e32 v211, v16, v192
	v_fmac_f32_e32 v212, v17, v194
	v_fma_mixlo_f16 v205, v205, s30, 0
	v_fma_mixlo_f16 v206, v206, s30, 0
	v_fma_mixlo_f16 v207, v207, s30, 0
	v_fma_mixlo_f16 v208, v208, s30, 0
	v_fma_mixlo_f16 v209, v209, s30, 0
	v_fma_mixlo_f16 v210, v210, s30, 0
	v_fma_mixlo_f16 v211, v211, s30, 0
	v_mov_b32_e32 v17, v212
	global_store_short v[218:219], v196, off
	global_store_short v[218:219], v197, off offset:192
	global_store_short v[218:219], v198, off offset:384
	global_store_short v[218:219], v199, off offset:576
	global_store_short v[218:219], v200, off offset:1536
	global_store_short v[218:219], v201, off offset:1728
	global_store_short v[218:219], v202, off offset:1920
	global_store_short v[218:219], v204, off offset:2112
	global_store_short v[218:219], v205, off offset:3072
	global_store_short v[218:219], v206, off offset:3264
	global_store_short v[218:219], v207, off offset:3456
	global_store_short v[218:219], v208, off offset:3648
	global_store_short v[220:221], v209, off
	global_store_short v[220:221], v210, off offset:192
	global_store_short v[220:221], v211, off offset:384

; DI float sigmoidf_(float x) { return __builtin_amdgcn_rcpf(1.f + __expf(-x)); }
; #define L(ph, l, hf) hipLaunchKernelGGL(k_phase<ph>, dim3(G), dim3(256), 0, stream, p, l, hf)
; DI void scan_chain_c(const P& p, int l, int chain, char* smem, const XcdBarrier* xb, const int* hint, int nhs) {
;     ...
;     const int arrived = *sflag;
;     float lw[8], kkv[8], bbv[8], kmv[8], rrv[8], vvv[8], cl[8];
;     float run = 0.f;
;     const int cc = h * 64 + lane;
;     const float w0 = p.in[I_W0][(l * 2 + d) * 512 + cc], a0 = p.in[I_A0][(l * 2 + d) * 512 + cc];
;     const float kkc = p.in[I_KK][l * 512 + cc], kac = p.in[I_KA][l * 512 + cc], rkc = p.in[I_RK][l * 512 + cc];
;     const float trA = cvp[(d ? 3072 : 0) + cc], tr1 = cvp[1536 + cc], trC = cvp[(d ? 0 : 3072) + cc];
;     const float tkA = cvp[(d ? 3072 : 0) + 512 + cc], tk1 = cvp[1536 + 512 + cc], tkC = cvp[(d ? 0 : 3072) + 512 + cc];
;     const float tvA = cvp[(d ? 3072 : 0) + 1024 + cc], tv1 = cvp[1536 + 1024 + cc], tvC = cvp[(d ? 0 : 3072) + 1024 + cc];
; #pragma unroll
;     for (int e = 0; e < 8; ++e) {
;       const int tt = 8 * w + e;
;       const int n = nn + tt;
;       const int pos = d ? (L - 1 - n) : n;
;       const size_t row = (size_t)rowbase + pos;
;       const float rr = trA * (float)xr[e] + tr1 * (float)xr[e + 1] + trC * (float)xr[e + 2];
;       const float kx = tkA * (float)xk[e] + tk1 * (float)xk[e + 1] + tkC * (float)xk[e + 2];
;       const float vv = tvA * (float)xv[e] + tv1 * (float)xv[e + 1] + tvC * (float)xv[e + 2];
;       const float wr = w0 + raw[tt * 64 + lane], ar = a0 + raw[2048 + tt * 64 + lane];
;       const float z = -wr;
;       const float sp = fmaxf(z, 0.f) + __logf(1.f + __expf(-fabsf(z)));
;       const float lgw = -__expf(-sp - 0.5f);
;       const float aa = sigmoidf_(ar);
;       const float kkr = kx * kkc;
;       const float kkn = kkr * __builtin_amdgcn_rsqf(fmaxf(wave_sum(kkr * kkr), 1e-24f));
;       const float km = kx * (1.f + (aa - 1.f) * kac);
;       const float bon = wave_sum(rr * km * rkc);
.Lscan_consts_ready:
	s_cmpk_gt_u32 s25, 0xff
	s_cselect_b32 s7, s0, 0x100
	s_cselect_b32 s36, s70, s31
	s_add_i32 s0, s25, 0xffffff00
	s_min_u32 s11, s0, s25
	v_readlane_b32 s65, v252, 46
	s_add_u32 s0, s23, s36
	s_movk_i32 s65, 0x1000
	s_addc_u32 s1, s22, 0
	v_readlane_b32 s53, v252, 34
	v_readlane_b32 s54, v252, 35
	v_readlane_b32 s55, v252, 36
	v_readlane_b32 s58, v252, 39
	v_readlane_b32 s59, v252, 40
	v_readlane_b32 s62, v252, 43
	v_readlane_b32 s63, v252, 44
	v_readlane_b32 s64, v252, 45
	v_readlane_b32 s84, v253, 8
	v_readlane_b32 s85, v253, 9
	v_readlane_b32 s86, v253, 10
	v_readlane_b32 s87, v253, 11
	v_readlane_b32 s88, v253, 12
	v_readlane_b32 s89, v253, 13
	v_readlane_b32 s90, v253, 14
	v_readlane_b32 s91, v253, 15
	v_readlane_b32 s92, v253, 16
	v_readlane_b32 s93, v253, 17
	v_readlane_b32 s94, v253, 18
	v_readlane_b32 s95, v253, 19
	s_mov_b64 s[92:93], s[16:17]
	s_mov_b64 s[94:95], s[18:19]
	s_mov_b64 s[90:91], s[26:27]
	s_mov_b32 s87, 0x8000
	s_mov_b32 s64, 0x800000
	v_mov_b32_e32 v20, 0x11ff4
	ds_read_b32 v149, v20
	v_lshlrev_b32_e32 v33, 2, v80
	v_lshl_add_u32 v33, v122, 2, v33
	ds_read_b32 v192, v33
	ds_read_b32 v193, v33 offset:256
	ds_read_b32 v194, v33 offset:512
	ds_read_b32 v195, v33 offset:768
	ds_read_b32 v196, v33 offset:1024
	ds_read_b32 v197, v33 offset:1280
	ds_read_b32 v198, v33 offset:1536
	ds_read_b32 v199, v33 offset:1792
	v_cvt_f32_f16_e32 v212, v87
	v_cvt_f32_f16_e32 v213, v94
	v_cvt_f32_f16_e32 v214, v93
	v_cvt_f32_f16_e32 v215, v100
	v_cvt_f32_f16_e32 v216, v99
	v_cvt_f32_f16_e32 v217, v106
	v_cvt_f32_f16_e32 v218, v105
	v_cvt_f32_f16_e32 v219, v117
	v_cvt_f32_f16_e32 v238, v91
	v_cvt_f32_f16_e32 v239, v95
	v_cvt_f32_f16_e32 v240, v97
	v_cvt_f32_f16_e32 v241, v101
	v_cvt_f32_f16_e32 v242, v103
	v_cvt_f32_f16_e32 v243, v107
	v_cvt_f32_f16_e32 v244, v110
	v_cvt_f32_f16_e32 v245, v120
	v_mul_f32_e32 v212, v222, v212
	v_mul_f32_e32 v213, v222, v213
	v_mul_f32_e32 v214, v222, v214
	v_mul_f32_e32 v215, v222, v215
	v_mul_f32_e32 v216, v222, v216
	v_mul_f32_e32 v217, v222, v217
	v_mul_f32_e32 v218, v222, v218
	v_mul_f32_e32 v219, v222, v219
	v_mul_f32_e32 v238, v228, v238
	v_mul_f32_e32 v239, v228, v239
	v_mul_f32_e32 v240, v228, v240
	v_mul_f32_e32 v241, v228, v241
	v_mul_f32_e32 v242, v228, v242
	v_mul_f32_e32 v243, v228, v243
	v_mul_f32_e32 v244, v228, v244
	v_mul_f32_e32 v245, v228, v245
	v_fma_mix_f32 v212, v221, v88, v212 op_sel_hi:[0,1,0]
	v_fma_mix_f32 v213, v221, v87, v213 op_sel_hi:[0,1,0]
	v_fma_mix_f32 v214, v221, v94, v214 op_sel_hi:[0,1,0]
	v_fma_mix_f32 v215, v221, v93, v215 op_sel_hi:[0,1,0]
	v_fma_mix_f32 v216, v221, v100, v216 op_sel_hi:[0,1,0]
	v_fma_mix_f32 v217, v221, v99, v217 op_sel_hi:[0,1,0]
	v_fma_mix_f32 v218, v221, v106, v218 op_sel_hi:[0,1,0]
	v_fma_mix_f32 v219, v221, v105, v219 op_sel_hi:[0,1,0]
	v_fma_mix_f32 v238, v232, v89, v238 op_sel_hi:[0,1,0]
	v_fma_mix_f32 v239, v232, v91, v239 op_sel_hi:[0,1,0]
	v_fma_mix_f32 v240, v232, v95, v240 op_sel_hi:[0,1,0]
	v_fma_mix_f32 v241, v232, v97, v241 op_sel_hi:[0,1,0]
	v_fma_mix_f32 v242, v232, v101, v242 op_sel_hi:[0,1,0]
	v_fma_mix_f32 v243, v232, v103, v243 op_sel_hi:[0,1,0]
	v_fma_mix_f32 v244, v232, v107, v244 op_sel_hi:[0,1,0]
	v_fma_mix_f32 v245, v232, v110, v245 op_sel_hi:[0,1,0]
	v_fma_mix_f32 v212, v223, v94, v212 op_sel_hi:[0,1,0]
	v_fma_mix_f32 v213, v223, v93, v213 op_sel_hi:[0,1,0]
	v_fma_mix_f32 v214, v223, v100, v214 op_sel_hi:[0,1,0]
	v_fma_mix_f32 v215, v223, v99, v215 op_sel_hi:[0,1,0]
	v_fma_mix_f32 v216, v223, v106, v216 op_sel_hi:[0,1,0]
	v_fma_mix_f32 v217, v223, v105, v217 op_sel_hi:[0,1,0]
	v_fma_mix_f32 v218, v223, v117, v218 op_sel_hi:[0,1,0]
	v_fma_mix_f32 v219, v223, v145, v219 op_sel_hi:[0,1,0]
	v_fma_mix_f32 v238, v229, v95, v238 op_sel_hi:[0,1,0]
	v_fma_mix_f32 v239, v229, v97, v239 op_sel_hi:[0,1,0]
	v_fma_mix_f32 v240, v229, v101, v240 op_sel_hi:[0,1,0]
	v_fma_mix_f32 v241, v229, v103, v241 op_sel_hi:[0,1,0]
	v_fma_mix_f32 v242, v229, v107, v242 op_sel_hi:[0,1,0]
	v_fma_mix_f32 v243, v229, v110, v243 op_sel_hi:[0,1,0]
	v_fma_mix_f32 v244, v229, v120, v244 op_sel_hi:[0,1,0]
	v_fma_mix_f32 v245, v229, v146, v245 op_sel_hi:[0,1,0]
	s_waitcnt lgkmcnt(0)
	ds_read_b32 v204, v33 offset:8192
	ds_read_b32 v205, v33 offset:8448
	ds_read_b32 v206, v33 offset:8704
	ds_read_b32 v207, v33 offset:8960
	ds_read_b32 v208, v33 offset:9216
	ds_read_b32 v209, v33 offset:9472
	ds_read_b32 v210, v33 offset:9728
	ds_read_b32 v211, v33 offset:9984
	s_mov_b32 s13, 0xbfb8aa3b
	s_mov_b32 s14, 0x3f317217
	v_add_f32_e32 v192, v236, v192
	v_add_f32_e32 v193, v236, v193
	v_add_f32_e32 v194, v236, v194
	v_add_f32_e32 v195, v236, v195
	v_add_f32_e32 v196, v236, v196
	v_add_f32_e32 v197, v236, v197
	v_add_f32_e32 v198, v236, v198
	v_add_f32_e32 v199, v236, v199
	v_mul_f32_e64 v24, |v192|, s13
	v_mul_f32_e64 v25, |v193|, s13
	v_mul_f32_e64 v26, |v194|, s13
	v_mul_f32_e64 v27, |v195|, s13
	v_mul_f32_e64 v28, |v196|, s13
	v_mul_f32_e64 v29, |v197|, s13
	v_mul_f32_e64 v30, |v198|, s13
	v_mul_f32_e64 v31, |v199|, s13
	v_exp_f32_e32 v24, v24
	v_exp_f32_e32 v25, v25
	v_exp_f32_e32 v26, v26
	v_exp_f32_e32 v27, v27
	v_exp_f32_e32 v28, v28
	v_exp_f32_e32 v29, v29
	v_exp_f32_e32 v30, v30
	v_exp_f32_e32 v31, v31
	v_add_f32_e32 v24, 1.0, v24
	v_add_f32_e32 v25, 1.0, v25
	v_add_f32_e32 v26, 1.0, v26
	v_add_f32_e32 v27, 1.0, v27
	v_add_f32_e32 v28, 1.0, v28
	v_add_f32_e32 v29, 1.0, v29
	v_add_f32_e32 v30, 1.0, v30
	v_add_f32_e32 v31, 1.0, v31
	v_log_f32_e32 v24, v24
	v_log_f32_e32 v25, v25
	v_log_f32_e32 v26, v26
	v_log_f32_e32 v27, v27
	v_log_f32_e32 v28, v28
	v_log_f32_e32 v29, v29
	v_log_f32_e32 v30, v30
	v_log_f32_e32 v31, v31
; DI float sigmoidf_(float x) { return __builtin_amdgcn_rcpf(1.f + __expf(-x)); }
; DI void scan_chain_c(const P& p, int l, int chain, char* smem, const XcdBarrier* xb, const int* hint, int nhs) {
;     ...
;       const float z = -wr;
;       const float sp = fmaxf(z, 0.f) + __logf(1.f + __expf(-fabsf(z)));
;       const float lgw = -__expf(-sp - 0.5f);
;       const float aa = sigmoidf_(ar);
;       const float kkr = kx * kkc;
;       const float kkn = kkr * __builtin_amdgcn_rsqf(fmaxf(wave_sum(kkr * kkr), 1e-24f));
;       const float km = kx * (1.f + (aa - 1.f) * kac);
	v_mul_f32_e32 v180, 0x3f317217, v24
	v_mul_f32_e32 v181, 0x3f317217, v25
	v_mul_f32_e32 v182, 0x3f317217, v26
	v_mul_f32_e32 v183, 0x3f317217, v27
	v_mul_f32_e32 v184, 0x3f317217, v28
	v_mul_f32_e32 v185, 0x3f317217, v29
	v_mul_f32_e32 v186, 0x3f317217, v30
	v_mul_f32_e32 v187, 0x3f317217, v31
	v_fma_f32 v180, v24, s14, -v180
	v_fma_f32 v181, v25, s14, -v181
	v_fma_f32 v182, v26, s14, -v182
	v_fma_f32 v183, v27, s14, -v183
	v_fma_f32 v184, v28, s14, -v184
	v_fma_f32 v185, v29, s14, -v185
	v_fma_f32 v186, v30, s14, -v186
	v_fma_f32 v187, v31, s14, -v187
	v_fmac_f32_e32 v180, 0x3377d1cf, v24
	v_fmac_f32_e32 v181, 0x3377d1cf, v25
	v_fmac_f32_e32 v182, 0x3377d1cf, v26
	v_fmac_f32_e32 v183, 0x3377d1cf, v27
	v_fmac_f32_e32 v184, 0x3377d1cf, v28
	v_fmac_f32_e32 v185, 0x3377d1cf, v29
	v_fmac_f32_e32 v186, 0x3377d1cf, v30
	v_fmac_f32_e32 v187, 0x3377d1cf, v31
	v_fmac_f32_e32 v180, 0x3f317217, v24
	v_fmac_f32_e32 v181, 0x3f317217, v25
	v_fmac_f32_e32 v182, 0x3f317217, v26
	v_fmac_f32_e32 v183, 0x3f317217, v27
	v_fmac_f32_e32 v184, 0x3f317217, v28
	v_fmac_f32_e32 v185, 0x3f317217, v29
	v_fmac_f32_e32 v186, 0x3f317217, v30
	v_fmac_f32_e32 v187, 0x3f317217, v31
	v_max_f32_e64 v192, -v192, 0
	v_max_f32_e64 v193, -v193, 0
	v_max_f32_e64 v194, -v194, 0
	v_max_f32_e64 v195, -v195, 0
	v_max_f32_e64 v196, -v196, 0
	v_max_f32_e64 v197, -v197, 0
	v_max_f32_e64 v198, -v198, 0
	v_max_f32_e64 v199, -v199, 0
	v_add_f32_e32 v192, v192, v180
	v_add_f32_e32 v193, v193, v181
	v_add_f32_e32 v194, v194, v182
	v_add_f32_e32 v195, v195, v183
	v_add_f32_e32 v196, v196, v184
	v_add_f32_e32 v197, v197, v185
	v_add_f32_e32 v198, v198, v186
	v_add_f32_e32 v199, v199, v187
	v_sub_f32_e32 v192, -0.5, v192
	v_sub_f32_e32 v193, -0.5, v193
	v_sub_f32_e32 v194, -0.5, v194
	v_sub_f32_e32 v195, -0.5, v195
	v_sub_f32_e32 v196, -0.5, v196
	v_sub_f32_e32 v197, -0.5, v197
	v_sub_f32_e32 v198, -0.5, v198
	v_sub_f32_e32 v199, -0.5, v199
	v_mul_f32_e32 v192, 0x3fb8aa3b, v192
	v_mul_f32_e32 v193, 0x3fb8aa3b, v193
	v_mul_f32_e32 v194, 0x3fb8aa3b, v194
	v_mul_f32_e32 v195, 0x3fb8aa3b, v195
	v_mul_f32_e32 v196, 0x3fb8aa3b, v196
	v_mul_f32_e32 v197, 0x3fb8aa3b, v197
	v_mul_f32_e32 v198, 0x3fb8aa3b, v198
	v_mul_f32_e32 v199, 0x3fb8aa3b, v199
	v_exp_f32_e32 v192, v192
	v_exp_f32_e32 v193, v193
	v_exp_f32_e32 v194, v194
	v_exp_f32_e32 v195, v195
	v_exp_f32_e32 v196, v196
	v_exp_f32_e32 v197, v197
	v_exp_f32_e32 v198, v198
	v_exp_f32_e32 v199, v199
	s_waitcnt lgkmcnt(0)
	v_add_f32_e32 v204, v220, v204
	v_add_f32_e32 v205, v220, v205
	v_add_f32_e32 v206, v220, v206
	v_add_f32_e32 v207, v220, v207
	v_add_f32_e32 v208, v220, v208
	v_add_f32_e32 v209, v220, v209
	v_add_f32_e32 v210, v220, v210
	v_add_f32_e32 v211, v220, v211
	v_mul_f32_e32 v204, 0xbfb8aa3b, v204
	v_mul_f32_e32 v205, 0xbfb8aa3b, v205
	v_mul_f32_e32 v206, 0xbfb8aa3b, v206
	v_mul_f32_e32 v207, 0xbfb8aa3b, v207
	v_mul_f32_e32 v208, 0xbfb8aa3b, v208
	v_mul_f32_e32 v209, 0xbfb8aa3b, v209
	v_mul_f32_e32 v210, 0xbfb8aa3b, v210
	v_mul_f32_e32 v211, 0xbfb8aa3b, v211
	v_exp_f32_e32 v204, v204
	v_exp_f32_e32 v205, v205
	v_exp_f32_e32 v206, v206
	v_exp_f32_e32 v207, v207
	v_exp_f32_e32 v208, v208
	v_exp_f32_e32 v209, v209
	v_exp_f32_e32 v210, v210
	v_exp_f32_e32 v211, v211
	v_add_f32_e32 v204, 1.0, v204
	v_add_f32_e32 v205, 1.0, v205
	v_add_f32_e32 v206, 1.0, v206
	v_add_f32_e32 v207, 1.0, v207
	v_add_f32_e32 v208, 1.0, v208
	v_add_f32_e32 v209, 1.0, v209
	v_add_f32_e32 v210, 1.0, v210
	v_add_f32_e32 v211, 1.0, v211
	v_rcp_f32_e32 v204, v204
	v_rcp_f32_e32 v205, v205
	v_rcp_f32_e32 v206, v206
	v_rcp_f32_e32 v207, v207
	v_rcp_f32_e32 v208, v208
	v_rcp_f32_e32 v209, v209
	v_rcp_f32_e32 v210, v210
	v_rcp_f32_e32 v211, v211
	v_mul_f32_e32 v246, v233, v238
	v_mul_f32_e32 v247, v233, v239
	v_mul_f32_e32 v248, v233, v240
	v_mul_f32_e32 v249, v233, v241
	v_mul_f32_e32 v250, v233, v242
	v_mul_f32_e32 v251, v233, v243
	v_mul_f32_e32 v226, v233, v244
	v_mul_f32_e32 v227, v233, v245
	v_mul_f32_e32 v24, v246, v246
	v_mul_f32_e32 v25, v247, v247
	v_mul_f32_e32 v26, v248, v248
	v_mul_f32_e32 v27, v249, v249
	v_mul_f32_e32 v28, v250, v250
	v_mul_f32_e32 v29, v251, v251
	v_mul_f32_e32 v30, v226, v226
	v_mul_f32_e32 v31, v227, v227
	v_mov_b32_dpp v24, v24 quad_perm:[1,0,3,2] row_mask:0xf bank_mask:0xf bound_ctrl:1
	v_mov_b32_dpp v25, v25 quad_perm:[1,0,3,2] row_mask:0xf bank_mask:0xf bound_ctrl:1
	v_mov_b32_dpp v26, v26 quad_perm:[1,0,3,2] row_mask:0xf bank_mask:0xf bound_ctrl:1
	v_mov_b32_dpp v27, v27 quad_perm:[1,0,3,2] row_mask:0xf bank_mask:0xf bound_ctrl:1
	v_mov_b32_dpp v28, v28 quad_perm:[1,0,3,2] row_mask:0xf bank_mask:0xf bound_ctrl:1
	v_mov_b32_dpp v29, v29 quad_perm:[1,0,3,2] row_mask:0xf bank_mask:0xf bound_ctrl:1
	v_mov_b32_dpp v30, v30 quad_perm:[1,0,3,2] row_mask:0xf bank_mask:0xf bound_ctrl:1
	v_mov_b32_dpp v31, v31 quad_perm:[1,0,3,2] row_mask:0xf bank_mask:0xf bound_ctrl:1
	v_fmac_f32_e32 v24, v246, v246
	v_fmac_f32_e32 v25, v247, v247
	v_fmac_f32_e32 v26, v248, v248
	v_fmac_f32_e32 v27, v249, v249
	v_fmac_f32_e32 v28, v250, v250
	v_fmac_f32_e32 v29, v251, v251
	v_fmac_f32_e32 v30, v226, v226
	v_fmac_f32_e32 v31, v227, v227
	v_add_f32_dpp v24, v24, v24 quad_perm:[2,3,0,1] row_mask:0xf bank_mask:0xf bound_ctrl:1
	v_add_f32_dpp v25, v25, v25 quad_perm:[2,3,0,1] row_mask:0xf bank_mask:0xf bound_ctrl:1
	v_add_f32_dpp v26, v26, v26 quad_perm:[2,3,0,1] row_mask:0xf bank_mask:0xf bound_ctrl:1
	v_add_f32_dpp v27, v27, v27 quad_perm:[2,3,0,1] row_mask:0xf bank_mask:0xf bound_ctrl:1
	v_add_f32_dpp v28, v28, v28 quad_perm:[2,3,0,1] row_mask:0xf bank_mask:0xf bound_ctrl:1
	v_add_f32_dpp v29, v29, v29 quad_perm:[2,3,0,1] row_mask:0xf bank_mask:0xf bound_ctrl:1
; DI void scan_chain_c(const P& p, int l, int chain, char* smem, const XcdBarrier* xb, const int* hint, int nhs) {
;     ...
;       const float kkr = kx * kkc;
;       const float kkn = kkr * __builtin_amdgcn_rsqf(fmaxf(wave_sum(kkr * kkr), 1e-24f));
;       const float km = kx * (1.f + (aa - 1.f) * kac);
;       const float bon = wave_sum(rr * km * rkc);
	v_add_f32_dpp v30, v30, v30 quad_perm:[2,3,0,1] row_mask:0xf bank_mask:0xf bound_ctrl:1
	v_add_f32_dpp v31, v31, v31 quad_perm:[2,3,0,1] row_mask:0xf bank_mask:0xf bound_ctrl:1
	v_add_f32_dpp v24, v24, v24 row_half_mirror row_mask:0xf bank_mask:0xf bound_ctrl:1
	v_add_f32_dpp v25, v25, v25 row_half_mirror row_mask:0xf bank_mask:0xf bound_ctrl:1
	v_add_f32_dpp v26, v26, v26 row_half_mirror row_mask:0xf bank_mask:0xf bound_ctrl:1
	v_add_f32_dpp v27, v27, v27 row_half_mirror row_mask:0xf bank_mask:0xf bound_ctrl:1
	v_add_f32_dpp v28, v28, v28 row_half_mirror row_mask:0xf bank_mask:0xf bound_ctrl:1
	v_add_f32_dpp v29, v29, v29 row_half_mirror row_mask:0xf bank_mask:0xf bound_ctrl:1
	v_add_f32_dpp v30, v30, v30 row_half_mirror row_mask:0xf bank_mask:0xf bound_ctrl:1
	v_add_f32_dpp v31, v31, v31 row_half_mirror row_mask:0xf bank_mask:0xf bound_ctrl:1
	v_add_f32_dpp v24, v24, v24 row_mirror row_mask:0xf bank_mask:0xf bound_ctrl:1
	v_add_f32_dpp v25, v25, v25 row_mirror row_mask:0xf bank_mask:0xf bound_ctrl:1
	v_add_f32_dpp v26, v26, v26 row_mirror row_mask:0xf bank_mask:0xf bound_ctrl:1
	v_add_f32_dpp v27, v27, v27 row_mirror row_mask:0xf bank_mask:0xf bound_ctrl:1
	v_add_f32_dpp v28, v28, v28 row_mirror row_mask:0xf bank_mask:0xf bound_ctrl:1
	v_add_f32_dpp v29, v29, v29 row_mirror row_mask:0xf bank_mask:0xf bound_ctrl:1
	v_add_f32_dpp v30, v30, v30 row_mirror row_mask:0xf bank_mask:0xf bound_ctrl:1
	v_add_f32_dpp v31, v31, v31 row_mirror row_mask:0xf bank_mask:0xf bound_ctrl:1
	ds_swizzle_b32 v180, v24 offset:swizzle(SWAP,16)
	ds_swizzle_b32 v181, v25 offset:swizzle(SWAP,16)
	ds_swizzle_b32 v182, v26 offset:swizzle(SWAP,16)
	ds_swizzle_b32 v183, v27 offset:swizzle(SWAP,16)
	ds_swizzle_b32 v184, v28 offset:swizzle(SWAP,16)
	ds_swizzle_b32 v185, v29 offset:swizzle(SWAP,16)
	ds_swizzle_b32 v186, v30 offset:swizzle(SWAP,16)
	ds_swizzle_b32 v187, v31 offset:swizzle(SWAP,16)
	s_waitcnt lgkmcnt(7)
	v_add_f32_e32 v24, v24, v180
	s_waitcnt lgkmcnt(6)
	v_add_f32_e32 v25, v25, v181
	s_waitcnt lgkmcnt(5)
	v_add_f32_e32 v26, v26, v182
	s_waitcnt lgkmcnt(4)
	v_add_f32_e32 v27, v27, v183
	s_waitcnt lgkmcnt(3)
	v_add_f32_e32 v28, v28, v184
	s_waitcnt lgkmcnt(2)
	v_add_f32_e32 v29, v29, v185
	s_waitcnt lgkmcnt(1)
	v_add_f32_e32 v30, v30, v186
	s_waitcnt lgkmcnt(0)
	v_add_f32_e32 v31, v31, v187
	v_mov_b32_e32 v180, v24
	v_mov_b32_e32 v181, v25
	v_mov_b32_e32 v182, v26
	v_mov_b32_e32 v183, v27
	v_mov_b32_e32 v184, v28
	v_mov_b32_e32 v185, v29
	v_mov_b32_e32 v186, v30
	v_mov_b32_e32 v187, v31
	v_permlane32_swap_b32_e32 v24, v180
	v_permlane32_swap_b32_e32 v25, v181
	v_permlane32_swap_b32_e32 v26, v182
	v_permlane32_swap_b32_e32 v27, v183
	v_permlane32_swap_b32_e32 v28, v184
	v_permlane32_swap_b32_e32 v29, v185
	v_permlane32_swap_b32_e32 v30, v186
	v_permlane32_swap_b32_e32 v31, v187
	v_add_f32_e32 v24, v24, v180
	v_add_f32_e32 v25, v25, v181
	v_add_f32_e32 v26, v26, v182
	v_add_f32_e32 v27, v27, v183
	v_add_f32_e32 v28, v28, v184
	v_add_f32_e32 v29, v29, v185
	v_add_f32_e32 v30, v30, v186
	v_add_f32_e32 v31, v31, v187
	v_max_f32_e32 v24, 0x179abe15, v24
	v_max_f32_e32 v25, 0x179abe15, v25
	v_max_f32_e32 v26, 0x179abe15, v26
	v_max_f32_e32 v27, 0x179abe15, v27
	v_max_f32_e32 v28, 0x179abe15, v28
	v_max_f32_e32 v29, 0x179abe15, v29
	v_max_f32_e32 v30, 0x179abe15, v30
	v_max_f32_e32 v31, 0x179abe15, v31
	v_rsq_f32_e32 v24, v24
	v_rsq_f32_e32 v25, v25
	v_rsq_f32_e32 v26, v26
	v_rsq_f32_e32 v27, v27
	v_rsq_f32_e32 v28, v28
	v_rsq_f32_e32 v29, v29
	v_rsq_f32_e32 v30, v30
	v_rsq_f32_e32 v31, v31
	v_add_f32_e32 v180, -1.0, v204
	v_add_f32_e32 v181, -1.0, v205
	v_add_f32_e32 v182, -1.0, v206
	v_add_f32_e32 v183, -1.0, v207
	v_add_f32_e32 v184, -1.0, v208
	v_add_f32_e32 v185, -1.0, v209
	v_add_f32_e32 v186, -1.0, v210
	v_add_f32_e32 v187, -1.0, v211
	v_fma_f32 v180, v234, v180, 1.0
	v_fma_f32 v181, v234, v181, 1.0
	v_fma_f32 v182, v234, v182, 1.0
	v_fma_f32 v183, v234, v183, 1.0
	v_fma_f32 v184, v234, v184, 1.0
	v_fma_f32 v185, v234, v185, 1.0
	v_fma_f32 v186, v234, v186, 1.0
	v_fma_f32 v187, v234, v187, 1.0
	v_mul_f32_e32 v246, v246, v24
	v_mul_f32_e32 v247, v247, v25
	v_mul_f32_e32 v248, v248, v26
	v_mul_f32_e32 v249, v249, v27
	v_mul_f32_e32 v250, v250, v28
	v_mul_f32_e32 v251, v251, v29
	v_mul_f32_e32 v226, v226, v30
	v_mul_f32_e32 v227, v227, v31
	v_mul_f32_e32 v238, v238, v180
	v_mul_f32_e32 v239, v239, v181
	v_mul_f32_e32 v240, v240, v182
	v_mul_f32_e32 v241, v241, v183
	v_mul_f32_e32 v242, v242, v184
	v_mul_f32_e32 v243, v243, v185
	v_mul_f32_e32 v244, v244, v186
	v_mul_f32_e32 v245, v245, v187
	v_mul_f32_e32 v24, v212, v238
	v_mul_f32_e32 v25, v213, v239
	v_mul_f32_e32 v26, v214, v240
	v_mul_f32_e32 v27, v215, v241
	v_mul_f32_e32 v28, v216, v242
	v_mul_f32_e32 v29, v217, v243
	v_mul_f32_e32 v30, v218, v244
	v_mul_f32_e32 v31, v219, v245
	v_mul_f32_e32 v180, v235, v24
	v_mul_f32_e32 v181, v235, v25
	v_mul_f32_e32 v182, v235, v26
	v_mul_f32_e32 v183, v235, v27
	v_mul_f32_e32 v184, v235, v28
	v_mul_f32_e32 v185, v235, v29
	v_mul_f32_e32 v186, v235, v30
	v_mul_f32_e32 v187, v235, v31
	v_mov_b32_dpp v180, v180 quad_perm:[1,0,3,2] row_mask:0xf bank_mask:0xf bound_ctrl:1
	v_mov_b32_dpp v181, v181 quad_perm:[1,0,3,2] row_mask:0xf bank_mask:0xf bound_ctrl:1
	v_mov_b32_dpp v182, v182 quad_perm:[1,0,3,2] row_mask:0xf bank_mask:0xf bound_ctrl:1
	v_mov_b32_dpp v183, v183 quad_perm:[1,0,3,2] row_mask:0xf bank_mask:0xf bound_ctrl:1
	v_mov_b32_dpp v184, v184 quad_perm:[1,0,3,2] row_mask:0xf bank_mask:0xf bound_ctrl:1
	v_mov_b32_dpp v185, v185 quad_perm:[1,0,3,2] row_mask:0xf bank_mask:0xf bound_ctrl:1
	v_mov_b32_dpp v186, v186 quad_perm:[1,0,3,2] row_mask:0xf bank_mask:0xf bound_ctrl:1
; DI void scan_chain_c(const P& p, int l, int chain, char* smem, const XcdBarrier* xb, const int* hint, int nhs) {
;     ...
;       const float bon = wave_sum(rr * km * rkc);
;       if (lane == 0) bs[((size_t)d * TA + row) * 8 + h] = bon;
	v_mov_b32_dpp v187, v187 quad_perm:[1,0,3,2] row_mask:0xf bank_mask:0xf bound_ctrl:1
	v_fmac_f32_e32 v180, v235, v24
	v_fmac_f32_e32 v181, v235, v25
	v_fmac_f32_e32 v182, v235, v26
	v_fmac_f32_e32 v183, v235, v27
	v_fmac_f32_e32 v184, v235, v28
	v_fmac_f32_e32 v185, v235, v29
	v_fmac_f32_e32 v186, v235, v30
	v_fmac_f32_e32 v187, v235, v31
	v_add_f32_dpp v180, v180, v180 quad_perm:[2,3,0,1] row_mask:0xf bank_mask:0xf bound_ctrl:1
	v_add_f32_dpp v181, v181, v181 quad_perm:[2,3,0,1] row_mask:0xf bank_mask:0xf bound_ctrl:1
	v_add_f32_dpp v182, v182, v182 quad_perm:[2,3,0,1] row_mask:0xf bank_mask:0xf bound_ctrl:1
	v_add_f32_dpp v183, v183, v183 quad_perm:[2,3,0,1] row_mask:0xf bank_mask:0xf bound_ctrl:1
	v_add_f32_dpp v184, v184, v184 quad_perm:[2,3,0,1] row_mask:0xf bank_mask:0xf bound_ctrl:1
	v_add_f32_dpp v185, v185, v185 quad_perm:[2,3,0,1] row_mask:0xf bank_mask:0xf bound_ctrl:1
	v_add_f32_dpp v186, v186, v186 quad_perm:[2,3,0,1] row_mask:0xf bank_mask:0xf bound_ctrl:1
	v_add_f32_dpp v187, v187, v187 quad_perm:[2,3,0,1] row_mask:0xf bank_mask:0xf bound_ctrl:1
	v_add_f32_dpp v180, v180, v180 row_half_mirror row_mask:0xf bank_mask:0xf bound_ctrl:1
	v_add_f32_dpp v181, v181, v181 row_half_mirror row_mask:0xf bank_mask:0xf bound_ctrl:1
	v_add_f32_dpp v182, v182, v182 row_half_mirror row_mask:0xf bank_mask:0xf bound_ctrl:1
	v_add_f32_dpp v183, v183, v183 row_half_mirror row_mask:0xf bank_mask:0xf bound_ctrl:1
	v_add_f32_dpp v184, v184, v184 row_half_mirror row_mask:0xf bank_mask:0xf bound_ctrl:1
	v_add_f32_dpp v185, v185, v185 row_half_mirror row_mask:0xf bank_mask:0xf bound_ctrl:1
	v_add_f32_dpp v186, v186, v186 row_half_mirror row_mask:0xf bank_mask:0xf bound_ctrl:1
	v_add_f32_dpp v187, v187, v187 row_half_mirror row_mask:0xf bank_mask:0xf bound_ctrl:1
	v_add_f32_dpp v180, v180, v180 row_mirror row_mask:0xf bank_mask:0xf bound_ctrl:1
	v_add_f32_dpp v181, v181, v181 row_mirror row_mask:0xf bank_mask:0xf bound_ctrl:1
	v_add_f32_dpp v182, v182, v182 row_mirror row_mask:0xf bank_mask:0xf bound_ctrl:1
	v_add_f32_dpp v183, v183, v183 row_mirror row_mask:0xf bank_mask:0xf bound_ctrl:1
	v_add_f32_dpp v184, v184, v184 row_mirror row_mask:0xf bank_mask:0xf bound_ctrl:1
	v_add_f32_dpp v185, v185, v185 row_mirror row_mask:0xf bank_mask:0xf bound_ctrl:1
	v_add_f32_dpp v186, v186, v186 row_mirror row_mask:0xf bank_mask:0xf bound_ctrl:1
	v_add_f32_dpp v187, v187, v187 row_mirror row_mask:0xf bank_mask:0xf bound_ctrl:1
	ds_swizzle_b32 v24, v180 offset:swizzle(SWAP,16)
	ds_swizzle_b32 v25, v181 offset:swizzle(SWAP,16)
	ds_swizzle_b32 v26, v182 offset:swizzle(SWAP,16)
	ds_swizzle_b32 v27, v183 offset:swizzle(SWAP,16)
	ds_swizzle_b32 v28, v184 offset:swizzle(SWAP,16)
	ds_swizzle_b32 v29, v185 offset:swizzle(SWAP,16)
	ds_swizzle_b32 v30, v186 offset:swizzle(SWAP,16)
	ds_swizzle_b32 v31, v187 offset:swizzle(SWAP,16)
	s_waitcnt lgkmcnt(7)
	v_add_f32_e32 v180, v180, v24
	s_waitcnt lgkmcnt(6)
	v_add_f32_e32 v181, v181, v25
	s_waitcnt lgkmcnt(5)
	v_add_f32_e32 v182, v182, v26
	s_waitcnt lgkmcnt(4)
	v_add_f32_e32 v183, v183, v27
	s_waitcnt lgkmcnt(3)
	v_add_f32_e32 v184, v184, v28
	s_waitcnt lgkmcnt(2)
	v_add_f32_e32 v185, v185, v29
	s_waitcnt lgkmcnt(1)
	v_add_f32_e32 v186, v186, v30
	s_waitcnt lgkmcnt(0)
	v_add_f32_e32 v187, v187, v31
	v_mov_b32_e32 v24, v180
	v_mov_b32_e32 v25, v181
	v_mov_b32_e32 v26, v182
	v_mov_b32_e32 v27, v183
	v_mov_b32_e32 v28, v184
	v_mov_b32_e32 v29, v185
	v_mov_b32_e32 v30, v186
	v_mov_b32_e32 v31, v187
	v_permlane32_swap_b32_e32 v180, v24
	v_permlane32_swap_b32_e32 v181, v25
	v_permlane32_swap_b32_e32 v182, v26
	v_permlane32_swap_b32_e32 v183, v27
	v_permlane32_swap_b32_e32 v184, v28
	v_permlane32_swap_b32_e32 v185, v29
	v_permlane32_swap_b32_e32 v186, v30
	v_permlane32_swap_b32_e32 v187, v31
	v_add_f32_e32 v180, v180, v24
	v_add_f32_e32 v181, v181, v25
	v_add_f32_e32 v182, v182, v26
	v_add_f32_e32 v183, v183, v27
	v_add_f32_e32 v184, v184, v28
	v_add_f32_e32 v185, v185, v29
	v_add_f32_e32 v186, v186, v30
	v_add_f32_e32 v187, v187, v31
	v_cmp_eq_u32_e64 s[12:13], 0, v80
	v_add_u32_e32 v188, s11, v86
	s_nop 1
	s_and_saveexec_b64 s[12:13], s[12:13]
	s_cbranch_execz .Lscan_s1_bonus_done
	v_add_u32_e32 v24, 0, v188
	v_xad_u32 v25, v24, -1, s7
	v_cndmask_b32_e64 v24, v25, v24, s[38:39]
	v_ashrrev_i32_e32 v25, 31, v24
	v_lshl_add_u64 v[24:25], s[0:1], 0, v[24:25]
	v_lshlrev_b64 v[24:25], 5, v[24:25]
	v_lshl_add_u64 v[24:25], s[8:9], 0, v[24:25]
	global_store_dword v[24:25], v180, off
	v_add_u32_e32 v26, 1, v188
	v_xad_u32 v27, v26, -1, s7
	v_cndmask_b32_e64 v26, v27, v26, s[38:39]
	v_ashrrev_i32_e32 v27, 31, v26
	v_lshl_add_u64 v[26:27], s[0:1], 0, v[26:27]
	v_lshlrev_b64 v[26:27], 5, v[26:27]
	v_lshl_add_u64 v[26:27], s[8:9], 0, v[26:27]
	global_store_dword v[26:27], v181, off
	v_add_u32_e32 v28, 2, v188
	v_xad_u32 v29, v28, -1, s7
	v_cndmask_b32_e64 v28, v29, v28, s[38:39]
	v_ashrrev_i32_e32 v29, 31, v28
	v_lshl_add_u64 v[28:29], s[0:1], 0, v[28:29]
	v_lshlrev_b64 v[28:29], 5, v[28:29]
	v_lshl_add_u64 v[28:29], s[8:9], 0, v[28:29]
	global_store_dword v[28:29], v182, off
	v_add_u32_e32 v30, 3, v188
	v_xad_u32 v31, v30, -1, s7
	v_cndmask_b32_e64 v30, v31, v30, s[38:39]
	v_ashrrev_i32_e32 v31, 31, v30
	v_lshl_add_u64 v[30:31], s[0:1], 0, v[30:31]
	v_lshlrev_b64 v[30:31], 5, v[30:31]
	v_lshl_add_u64 v[30:31], s[8:9], 0, v[30:31]
	global_store_dword v[30:31], v183, off
	v_add_u32_e32 v24, 4, v188
	v_xad_u32 v25, v24, -1, s7
	v_cndmask_b32_e64 v24, v25, v24, s[38:39]
	v_ashrrev_i32_e32 v25, 31, v24
	v_lshl_add_u64 v[24:25], s[0:1], 0, v[24:25]
	v_lshlrev_b64 v[24:25], 5, v[24:25]
	v_lshl_add_u64 v[24:25], s[8:9], 0, v[24:25]
	global_store_dword v[24:25], v184, off
	v_add_u32_e32 v26, 5, v188
	v_xad_u32 v27, v26, -1, s7
	v_cndmask_b32_e64 v26, v27, v26, s[38:39]
	v_ashrrev_i32_e32 v27, 31, v26
	v_lshl_add_u64 v[26:27], s[0:1], 0, v[26:27]
	v_lshlrev_b64 v[26:27], 5, v[26:27]
	v_lshl_add_u64 v[26:27], s[8:9], 0, v[26:27]
	global_store_dword v[26:27], v185, off
	v_add_u32_e32 v28, 6, v188
	v_xad_u32 v29, v28, -1, s7
	v_cndmask_b32_e64 v28, v29, v28, s[38:39]
	v_ashrrev_i32_e32 v29, 31, v28
	v_lshl_add_u64 v[28:29], s[0:1], 0, v[28:29]
	v_lshlrev_b64 v[28:29], 5, v[28:29]
	v_lshl_add_u64 v[28:29], s[8:9], 0, v[28:29]
	global_store_dword v[28:29], v186, off
	v_add_u32_e32 v30, 7, v188
	v_xad_u32 v31, v30, -1, s7
	v_cndmask_b32_e64 v30, v31, v30, s[38:39]
	v_ashrrev_i32_e32 v31, 31, v30
	v_lshl_add_u64 v[30:31], s[0:1], 0, v[30:31]
	v_lshlrev_b64 v[30:31], 5, v[30:31]
	v_lshl_add_u64 v[30:31], s[8:9], 0, v[30:31]
	global_store_dword v[30:31], v187, off
; DI void scan_chain_c(const P& p, int l, int chain, char* smem, const XcdBarrier* xb, const int* hint, int nhs) {
;     ...
;       run += lgw;
;       lw[e] = lgw; cl[e] = run; kkv[e] = kkn; bbv[e] = kkn * aa; kmv[e] = km; rrv[e] = rr; vvv[e] = vv;
;     }
;     tot[w * 64 + lane] = run;
;     __syncthreads();
;     {
;       const float t0 = tot[lane], t1 = tot[64 + lane], t2 = tot[128 + lane], t3 = tot[192 + lane];
;       const float total = t0 + t1 + t2 + t3;
;       const float prefix = (w > 0 ? t0 : 0.f) + (w > 1 ? t1 : 0.f) + (w > 2 ? t2 : 0.f);
;       if (w == 0) GL[lane] = __expf(total);
;       b16x8 bgv, kgv, vtv;
; #pragma unroll
;       for (int e = 0; e < 8; ++e) {
;         const int tt = 8 * w + e;
;         const float g = prefix + cl[e];
;         const float eg = __expf(g), ege = __expf(g - lw[e]);
;         const float eng = __builtin_amdgcn_rcpf(eg);
;         const float egl = __expf(total - g);
;         Qt[tt * 72 + lane] = (b16)(kkv[e] * ege);
;         Rt[tt * 72 + lane] = (b16)(rrv[e] * eg);
;         Bt[tt * 72 + lane] = (b16)(bbv[e] * eng);
;         Kt[tt * 72 + lane] = (b16)(kmv[e] * eng);
;         bgv[e] = (b16)(bbv[e] * egl);
;         kgv[e] = (b16)(kmv[e] * egl);
;         vtv[e] = (b16)vvv[e];
;       }
.Lscan_s1_bonus_done:
	s_or_b64 exec, exec, s[12:13]
	v_sub_f32_e32 v24, 0, v192
	v_sub_f32_e32 v25, v24, v193
	v_sub_f32_e32 v26, v25, v194
	v_sub_f32_e32 v27, v26, v195
	v_sub_f32_e32 v28, v27, v196
	v_sub_f32_e32 v29, v28, v197
	v_sub_f32_e32 v30, v29, v198
	v_sub_f32_e32 v31, v30, v199
	v_lshl_add_u32 v188, v80, 2, v113
	ds_write_b32 v188, v31 offset:16384
	s_waitcnt lgkmcnt(0)
	s_barrier
	v_lshlrev_b32_e32 v188, 2, v80
	ds_read2st64_b32 v[180:181], v188 offset0:64 offset1:65
	ds_read2st64_b32 v[182:183], v188 offset0:66 offset1:67
	v_add_lshl_u32 v19, v80, v144, 1
	v_mad_u32_u24 v78, v80, s76, v66
	s_waitcnt lgkmcnt(1)
	v_add_f32_e32 v151, v180, v181
	s_waitcnt lgkmcnt(0)
	v_add_f32_e32 v151, v151, v182
	v_add_f32_e32 v151, v151, v183
	s_and_saveexec_b64 s[0:1], s[48:49]
	s_cbranch_execz .Lscan_s2_gl_done
	v_mul_f32_e32 v184, 0x3fb8aa3b, v151
	v_exp_f32_e32 v184, v184
	v_mov_b32_e32 v185, 0x11c00
	v_lshl_add_u32 v185, v80, 2, v185
	ds_write_b32 v185, v184
.Lscan_s2_gl_done:
	s_or_b64 exec, exec, s[0:1]
	v_cndmask_b32_e64 v180, 0, v180, s[42:43]
	v_cndmask_b32_e64 v181, 0, v181, s[44:45]
	v_cndmask_b32_e64 v182, 0, v182, s[46:47]
	v_add_f32_e32 v18, v180, v181
	v_add_f32_e32 v18, v18, v182
	v_add_f32_e32 v24, v24, v18
	v_add_f32_e32 v25, v25, v18
	v_add_f32_e32 v26, v26, v18
	v_add_f32_e32 v27, v27, v18
	v_add_f32_e32 v28, v28, v18
	v_add_f32_e32 v29, v29, v18
	v_add_f32_e32 v30, v30, v18
	v_add_f32_e32 v31, v31, v18
	v_mul_f32_e32 v180, 0x3fb8aa3b, v24
	v_mul_f32_e32 v184, 0x3fb8aa3b, v25
	v_mul_f32_e32 v188, 0x3fb8aa3b, v26
	v_mul_f32_e32 v200, 0x3fb8aa3b, v27
	v_add_f32_e32 v181, v192, v24
	v_add_f32_e32 v185, v193, v25
	v_add_f32_e32 v189, v194, v26
	v_add_f32_e32 v201, v195, v27
	v_sub_f32_e32 v183, v151, v24
	v_sub_f32_e32 v187, v151, v25
	v_sub_f32_e32 v191, v151, v26
	v_sub_f32_e32 v32, v151, v27
	v_exp_f32_e32 v180, v180
	v_exp_f32_e32 v184, v184
	v_exp_f32_e32 v188, v188
	v_exp_f32_e32 v200, v200
	v_mul_f32_e32 v181, 0x3fb8aa3b, v181
	v_mul_f32_e32 v185, 0x3fb8aa3b, v185
	v_mul_f32_e32 v189, 0x3fb8aa3b, v189
	v_mul_f32_e32 v201, 0x3fb8aa3b, v201
	v_mul_f32_e32 v183, 0x3fb8aa3b, v183
	v_mul_f32_e32 v187, 0x3fb8aa3b, v187
	v_mul_f32_e32 v191, 0x3fb8aa3b, v191
	v_mul_f32_e32 v32, 0x3fb8aa3b, v32
	v_exp_f32_e32 v181, v181
	v_exp_f32_e32 v185, v185
	v_exp_f32_e32 v189, v189
	v_exp_f32_e32 v201, v201
	v_exp_f32_e32 v183, v183
	v_exp_f32_e32 v187, v187
	v_exp_f32_e32 v191, v191
	v_exp_f32_e32 v32, v32
	v_rcp_f32_e32 v182, v180
	v_rcp_f32_e32 v186, v184
	v_rcp_f32_e32 v190, v188
	v_rcp_f32_e32 v202, v200
	v_mul_f32_e32 v204, v204, v246
	v_mul_f32_e32 v205, v205, v247
	v_mul_f32_e32 v206, v206, v248
	v_mul_f32_e32 v207, v207, v249
	v_mul_f32_e32 v180, v212, v180
	v_mul_f32_e32 v184, v213, v184
	v_mul_f32_e32 v188, v214, v188
	v_mul_f32_e32 v200, v215, v200
	v_mul_f32_e32 v181, v246, v181
	v_mul_f32_e32 v185, v247, v185
	v_mul_f32_e32 v189, v248, v189
	v_mul_f32_e32 v201, v249, v201
	v_cvt_pk_bf16_f32 v180, v180, v180
	v_cvt_pk_bf16_f32 v184, v184, v184
	v_cvt_pk_bf16_f32 v188, v188, v188
	v_cvt_pk_bf16_f32 v200, v200, v200
	v_cvt_pk_bf16_f32 v181, v181, v181
	v_cvt_pk_bf16_f32 v185, v185, v185
	v_cvt_pk_bf16_f32 v189, v189, v189
	v_cvt_pk_bf16_f32 v201, v201, v201
	ds_write_b16 v19, v180 offset:22016
	ds_write_b16 v19, v184 offset:22160
	ds_write_b16 v19, v188 offset:22304
	ds_write_b16 v19, v200 offset:22448
	ds_write_b16 v19, v181 offset:17408
	ds_write_b16 v19, v185 offset:17552
	ds_write_b16 v19, v189 offset:17696
	ds_write_b16 v19, v201 offset:17840
	v_mul_f32_e32 v180, v204, v182
	v_mul_f32_e32 v184, v205, v186
	v_mul_f32_e32 v188, v206, v190
	v_mul_f32_e32 v200, v207, v202
	v_mul_f32_e32 v181, v238, v182
	v_mul_f32_e32 v185, v239, v186
	v_mul_f32_e32 v189, v240, v190
	v_mul_f32_e32 v201, v241, v202
	v_mul_f32_e32 v204, v204, v183
	v_mul_f32_e32 v205, v205, v187
	v_mul_f32_e32 v206, v206, v191
	v_mul_f32_e32 v207, v207, v32
	v_mul_f32_e32 v238, v238, v183
	v_mul_f32_e32 v239, v239, v187
	v_mul_f32_e32 v240, v240, v191
	v_mul_f32_e32 v241, v241, v32
	v_cvt_pk_bf16_f32 v180, v180, v180
	v_cvt_pk_bf16_f32 v184, v184, v184
	v_cvt_pk_bf16_f32 v188, v188, v188
	v_cvt_pk_bf16_f32 v200, v200, v200
	v_cvt_pk_bf16_f32 v181, v181, v181
	v_cvt_pk_bf16_f32 v185, v185, v185
	v_cvt_pk_bf16_f32 v189, v189, v189
	v_cvt_pk_bf16_f32 v201, v201, v201
	ds_write_b16 v19, v180 offset:26624
	ds_write_b16 v19, v184 offset:26768
	ds_write_b16 v19, v188 offset:26912
	ds_write_b16 v19, v200 offset:27056
	ds_write_b16 v19, v181 offset:31232
	ds_write_b16 v19, v185 offset:31376
	ds_write_b16 v19, v189 offset:31520
	ds_write_b16 v19, v201 offset:31664
	v_mul_f32_e32 v180, 0x3fb8aa3b, v28
	v_mul_f32_e32 v184, 0x3fb8aa3b, v29
	v_mul_f32_e32 v188, 0x3fb8aa3b, v30
	v_mul_f32_e32 v200, 0x3fb8aa3b, v31
	v_add_f32_e32 v181, v196, v28
	v_add_f32_e32 v185, v197, v29
	v_add_f32_e32 v189, v198, v30
	v_add_f32_e32 v201, v199, v31
	v_sub_f32_e32 v183, v151, v28
	v_sub_f32_e32 v187, v151, v29
	v_sub_f32_e32 v191, v151, v30
	v_sub_f32_e32 v32, v151, v31
	v_exp_f32_e32 v180, v180
	v_exp_f32_e32 v184, v184
	v_exp_f32_e32 v188, v188
	v_exp_f32_e32 v200, v200
	v_mul_f32_e32 v181, 0x3fb8aa3b, v181
	v_mul_f32_e32 v185, 0x3fb8aa3b, v185
	v_mul_f32_e32 v189, 0x3fb8aa3b, v189
	v_mul_f32_e32 v201, 0x3fb8aa3b, v201
	v_mul_f32_e32 v183, 0x3fb8aa3b, v183
	v_mul_f32_e32 v187, 0x3fb8aa3b, v187
	v_mul_f32_e32 v191, 0x3fb8aa3b, v191
	v_mul_f32_e32 v32, 0x3fb8aa3b, v32
	v_exp_f32_e32 v181, v181
	v_exp_f32_e32 v185, v185
	v_exp_f32_e32 v189, v189
	v_exp_f32_e32 v201, v201
	v_exp_f32_e32 v183, v183
	v_exp_f32_e32 v187, v187
	v_exp_f32_e32 v191, v191
	v_exp_f32_e32 v32, v32
	v_rcp_f32_e32 v182, v180
; DI void scan_chain_c(const P& p, int l, int chain, char* smem, const XcdBarrier* xb, const int* hint, int nhs) {
;     ...
;       b16x8 bgv, kgv, vtv;
; #pragma unroll
;       for (int e = 0; e < 8; ++e) {
;         const int tt = 8 * w + e;
;         const float g = prefix + cl[e];
;         const float eg = __expf(g), ege = __expf(g - lw[e]);
;         const float eng = __builtin_amdgcn_rcpf(eg);
;         const float egl = __expf(total - g);
;         Qt[tt * 72 + lane] = (b16)(kkv[e] * ege);
;         Rt[tt * 72 + lane] = (b16)(rrv[e] * eg);
;         Bt[tt * 72 + lane] = (b16)(bbv[e] * eng);
;         Kt[tt * 72 + lane] = (b16)(kmv[e] * eng);
;         bgv[e] = (b16)(bbv[e] * egl);
;         kgv[e] = (b16)(kmv[e] * egl);
;         vtv[e] = (b16)vvv[e];
;       }
;       *(b16x8*)(BgT + lane * 40 + 8 * w) = bgv;
;       *(b16x8*)(KgT + lane * 40 + 8 * w) = kgv;
;       *(b16x8*)(VT + lane * 40 + 8 * w) = vtv;
	v_rcp_f32_e32 v186, v184
	v_rcp_f32_e32 v190, v188
	v_rcp_f32_e32 v202, v200
	v_mul_f32_e32 v208, v208, v250
	v_mul_f32_e32 v209, v209, v251
	v_mul_f32_e32 v210, v210, v226
	v_mul_f32_e32 v211, v211, v227
	v_mul_f32_e32 v180, v216, v180
	v_mul_f32_e32 v184, v217, v184
	v_mul_f32_e32 v188, v218, v188
	v_mul_f32_e32 v200, v219, v200
	v_mul_f32_e32 v181, v250, v181
	v_mul_f32_e32 v185, v251, v185
	v_mul_f32_e32 v189, v226, v189
	v_mul_f32_e32 v201, v227, v201
	v_cvt_pk_bf16_f32 v180, v180, v180
	v_cvt_pk_bf16_f32 v184, v184, v184
	v_cvt_pk_bf16_f32 v188, v188, v188
	v_cvt_pk_bf16_f32 v200, v200, v200
	v_cvt_pk_bf16_f32 v181, v181, v181
	v_cvt_pk_bf16_f32 v185, v185, v185
	v_cvt_pk_bf16_f32 v189, v189, v189
	v_cvt_pk_bf16_f32 v201, v201, v201
	ds_write_b16 v19, v180 offset:22592
	ds_write_b16 v19, v184 offset:22736
	ds_write_b16 v19, v188 offset:22880
	ds_write_b16 v19, v200 offset:23024
	ds_write_b16 v19, v181 offset:17984
	ds_write_b16 v19, v185 offset:18128
	ds_write_b16 v19, v189 offset:18272
	ds_write_b16 v19, v201 offset:18416
	v_mul_f32_e32 v180, v208, v182
	v_mul_f32_e32 v184, v209, v186
	v_mul_f32_e32 v188, v210, v190
	v_mul_f32_e32 v200, v211, v202
	v_mul_f32_e32 v181, v242, v182
	v_mul_f32_e32 v185, v243, v186
	v_mul_f32_e32 v189, v244, v190
	v_mul_f32_e32 v201, v245, v202
	v_mul_f32_e32 v208, v208, v183
	v_mul_f32_e32 v209, v209, v187
	v_mul_f32_e32 v210, v210, v191
	v_mul_f32_e32 v211, v211, v32
	v_mul_f32_e32 v242, v242, v183
	v_mul_f32_e32 v243, v243, v187
	v_mul_f32_e32 v244, v244, v191
	v_mul_f32_e32 v245, v245, v32
	v_cvt_pk_bf16_f32 v180, v180, v180
	v_cvt_pk_bf16_f32 v184, v184, v184
	v_cvt_pk_bf16_f32 v188, v188, v188
	v_cvt_pk_bf16_f32 v200, v200, v200
	v_cvt_pk_bf16_f32 v181, v181, v181
	v_cvt_pk_bf16_f32 v185, v185, v185
	v_cvt_pk_bf16_f32 v189, v189, v189
	v_cvt_pk_bf16_f32 v201, v201, v201
	ds_write_b16 v19, v180 offset:27200
	ds_write_b16 v19, v184 offset:27344
	ds_write_b16 v19, v188 offset:27488
	ds_write_b16 v19, v200 offset:27632
	ds_write_b16 v19, v181 offset:31808
	ds_write_b16 v19, v185 offset:31952
	ds_write_b16 v19, v189 offset:32096
	ds_write_b16 v19, v201 offset:32240
	v_cvt_f32_f16_e32 v212, v92
	v_cvt_f32_f16_e32 v213, v96
	v_cvt_f32_f16_e32 v214, v98
	v_cvt_f32_f16_e32 v215, v102
	v_cvt_f32_f16_e32 v216, v104
	v_cvt_f32_f16_e32 v217, v108
	v_cvt_f32_f16_e32 v218, v111
	v_cvt_f32_f16_e32 v219, v123
	v_mul_f32_e32 v212, v231, v212
	v_mul_f32_e32 v213, v231, v213
	v_mul_f32_e32 v214, v231, v214
	v_mul_f32_e32 v215, v231, v215
	v_mul_f32_e32 v216, v231, v216
	v_mul_f32_e32 v217, v231, v217
	v_mul_f32_e32 v218, v231, v218
	v_mul_f32_e32 v219, v231, v219
	v_fma_mix_f32 v212, v230, v90, v212 op_sel_hi:[0,1,0]
	v_fma_mix_f32 v213, v230, v92, v213 op_sel_hi:[0,1,0]
	v_fma_mix_f32 v214, v230, v96, v214 op_sel_hi:[0,1,0]
	v_fma_mix_f32 v215, v230, v98, v215 op_sel_hi:[0,1,0]
	v_fma_mix_f32 v216, v230, v102, v216 op_sel_hi:[0,1,0]
	v_fma_mix_f32 v217, v230, v104, v217 op_sel_hi:[0,1,0]
	v_fma_mix_f32 v218, v230, v108, v218 op_sel_hi:[0,1,0]
	v_fma_mix_f32 v219, v230, v111, v219 op_sel_hi:[0,1,0]
	v_fma_mix_f32 v212, v237, v96, v212 op_sel_hi:[0,1,0]
	v_fma_mix_f32 v213, v237, v98, v213 op_sel_hi:[0,1,0]
	v_fma_mix_f32 v214, v237, v102, v214 op_sel_hi:[0,1,0]
	v_fma_mix_f32 v215, v237, v104, v215 op_sel_hi:[0,1,0]
	v_fma_mix_f32 v216, v237, v108, v216 op_sel_hi:[0,1,0]
	v_fma_mix_f32 v217, v237, v111, v217 op_sel_hi:[0,1,0]
	v_fma_mix_f32 v218, v237, v123, v218 op_sel_hi:[0,1,0]
	v_fma_mix_f32 v219, v237, v147, v219 op_sel_hi:[0,1,0]
	v_cvt_pk_bf16_f32 v180, v204, v205
	v_cvt_pk_bf16_f32 v181, v206, v207
	v_cvt_pk_bf16_f32 v182, v208, v209
	v_cvt_pk_bf16_f32 v183, v210, v211
	v_cvt_pk_bf16_f32 v184, v238, v239
	v_cvt_pk_bf16_f32 v185, v240, v241
	v_cvt_pk_bf16_f32 v186, v242, v243
	v_cvt_pk_bf16_f32 v187, v244, v245
	v_cvt_pk_bf16_f32 v188, v212, v213
	v_cvt_pk_bf16_f32 v189, v214, v215
	v_cvt_pk_bf16_f32 v190, v216, v217
	v_cvt_pk_bf16_f32 v191, v218, v219
	ds_write_b128 v78, v[180:183] offset:35840
	ds_write_b128 v78, v[184:187] offset:40960
	ds_write_b128 v78, v[188:191] offset:46080
	v_mul_u32_u24_e32 v0, 0x48, v148
	v_lshlrev_b32_e32 v0, 1, v0
	v_lshlrev_b32_e32 v22, 4, v150
	v_add3_u32 v76, v114, v0, v22
	s_waitcnt lgkmcnt(0)
	s_barrier
; #define MFMAB(a, b, c) __builtin_amdgcn_mfma_f32_32x32x16_bf16((a), (b), (c), 0, 0, 0)
; DI void scan_chain_c(const P& p, int l, int chain, char* smem, const XcdBarrier* xb, const int* hint, int nhs) {
;     ...
;     {
;       const b16* X = (w < 2) ? Qt : Rt;
;       const b16* Y = (w & 1) ? Kt : Bt;
;       f32x16 acc;
; #pragma unroll
;       for (int i = 0; i < 16; ++i) acc[i] = 0.f;
; #pragma unroll
;       for (int ks = 0; ks < 4; ++ks) {
;         b16x8 a = *(const b16x8*)(X + r * 72 + ks * 16 + 8 * hh);
;         b16x8 bb = *(const b16x8*)(Y + r * 72 + ks * 16 + 8 * hh);
;         acc = MFMAB(a, bb, acc);
;       }
; #pragma unroll
;       for (int i = 0; i < 16; ++i) {
;         const int t = 4 * hh + (i & 3) + 8 * (i >> 2);
;         const bool keep = (w < 2) ? (r < t) : (r <= t);
;         const float v = keep ? acc[i] : 0.f;
;         if (w == 0) Am[t * 36 + r] = v;
;         else if (w == 1) Bm[t * 40 + r] = (b16)v;
;         else if (w == 2) A2[t * 40 + r] = (b16)v;
;         else B2[t * 40 + r] = (b16)v;
;       }
	v_add3_u32 v0, v115, v0, v22
	ds_read_b128 v[180:183], v76
	ds_read_b128 v[184:187], v0
	ds_read_b128 v[188:191], v76 offset:32
	ds_read_b128 v[192:195], v0 offset:32
	ds_read_b128 v[196:199], v76 offset:64
	ds_read_b128 v[204:207], v0 offset:64
	ds_read_b128 v[208:211], v76 offset:96
	ds_read_b128 v[212:215], v0 offset:96
	v_lshlrev_b32_e32 v151, 3, v150
	v_lshlrev_b32_e32 v76, 1, v148
	s_waitcnt lgkmcnt(6)
	v_mfma_f32_32x32x16_bf16 v[18:33], v[180:183], v[184:187], 0
	s_waitcnt lgkmcnt(4)
	v_mfma_f32_32x32x16_bf16 v[18:33], v[188:191], v[192:195], v[18:33]
	s_waitcnt lgkmcnt(2)
	v_mfma_f32_32x32x16_bf16 v[18:33], v[196:199], v[204:207], v[18:33]
	s_waitcnt lgkmcnt(0)
	v_mfma_f32_32x32x16_bf16 v[18:33], v[208:211], v[212:215], v[18:33]
	v_sub_u32_e32 v180, v148, v77
	v_cndmask_b32_e64 v181, 1, 0, s[50:51]
	v_readfirstlane_b32 s0, v67
	v_sub_u32_e32 v180, v180, v181
	v_mul_u32_u24_e32 v182, 0x140, v150
	v_mul_u32_u24_e32 v183, 0x90, v148
	s_mul_i32 s1, s0, 0xa00
	s_add_i32 s1, s1, 0xf400
	v_lshl_add_u32 v182, v148, 1, v182
	v_lshl_add_u32 v183, v150, 4, v183
	v_add_u32_e32 v182, s1, v182
	s_cmp_eq_u32 s0, 0
	s_cbranch_scc1 .Lscan_s3_w0
	v_cmp_gt_i32_e64 vcc, 0, v180
	v_cmp_gt_i32_e64 s[0:1], 1, v180
	v_cmp_gt_i32_e64 s[12:13], 2, v180
	v_cmp_gt_i32_e64 s[14:15], 3, v180
	v_cndmask_b32_e32 v184, 0, v18, vcc
	v_cndmask_b32_e64 v185, 0, v19, s[0:1]
	v_cndmask_b32_e64 v186, 0, v20, s[12:13]
	v_cndmask_b32_e64 v187, 0, v21, s[14:15]
	v_cvt_pk_bf16_f32 v184, v184, v184
	v_cvt_pk_bf16_f32 v185, v185, v185
	v_cvt_pk_bf16_f32 v186, v186, v186
	v_cvt_pk_bf16_f32 v187, v187, v187
	ds_write_b16 v182, v184 offset:0
	ds_write_b16 v182, v185 offset:80
	ds_write_b16 v182, v186 offset:160
	ds_write_b16 v182, v187 offset:240
	v_cmp_gt_i32_e64 vcc, 8, v180
	v_cmp_gt_i32_e64 s[0:1], 9, v180
	v_cmp_gt_i32_e64 s[12:13], 10, v180
	v_cmp_gt_i32_e64 s[14:15], 11, v180
	v_cndmask_b32_e32 v188, 0, v22, vcc
	v_cndmask_b32_e64 v189, 0, v23, s[0:1]
	v_cndmask_b32_e64 v190, 0, v24, s[12:13]
	v_cndmask_b32_e64 v191, 0, v25, s[14:15]
	v_cvt_pk_bf16_f32 v188, v188, v188
	v_cvt_pk_bf16_f32 v189, v189, v189
	v_cvt_pk_bf16_f32 v190, v190, v190
	v_cvt_pk_bf16_f32 v191, v191, v191
	ds_write_b16 v182, v188 offset:640
	ds_write_b16 v182, v189 offset:720
	ds_write_b16 v182, v190 offset:800
	ds_write_b16 v182, v191 offset:880
	v_cmp_gt_i32_e64 vcc, 16, v180
	v_cmp_gt_i32_e64 s[0:1], 17, v180
	v_cmp_gt_i32_e64 s[12:13], 18, v180
	v_cmp_gt_i32_e64 s[14:15], 19, v180
	v_cndmask_b32_e32 v184, 0, v26, vcc
	v_cndmask_b32_e64 v185, 0, v27, s[0:1]
	v_cndmask_b32_e64 v186, 0, v28, s[12:13]
	v_cndmask_b32_e64 v187, 0, v29, s[14:15]
	v_cvt_pk_bf16_f32 v184, v184, v184
	v_cvt_pk_bf16_f32 v185, v185, v185
	v_cvt_pk_bf16_f32 v186, v186, v186
	v_cvt_pk_bf16_f32 v187, v187, v187
	ds_write_b16 v182, v184 offset:1280
	ds_write_b16 v182, v185 offset:1360
	ds_write_b16 v182, v186 offset:1440
	ds_write_b16 v182, v187 offset:1520
	v_cmp_gt_i32_e64 vcc, 24, v180
	v_cmp_gt_i32_e64 s[0:1], 25, v180
	v_cmp_gt_i32_e64 s[12:13], 26, v180
	v_cmp_gt_i32_e64 s[14:15], 27, v180
	v_cndmask_b32_e32 v188, 0, v30, vcc
	v_cndmask_b32_e64 v189, 0, v31, s[0:1]
	v_cndmask_b32_e64 v190, 0, v32, s[12:13]
	v_cndmask_b32_e64 v191, 0, v33, s[14:15]
	v_cvt_pk_bf16_f32 v188, v188, v188
	v_cvt_pk_bf16_f32 v189, v189, v189
	v_cvt_pk_bf16_f32 v190, v190, v190
	v_cvt_pk_bf16_f32 v191, v191, v191
	ds_write_b16 v182, v188 offset:1920
	ds_write_b16 v182, v189 offset:2000
	ds_write_b16 v182, v190 offset:2080
	ds_write_b16 v182, v191 offset:2160
	s_branch .Lscan_s3_done
